# hyena st2 epilogue hand-written: loads of iteration i+1 issued ahead (was wait-after-every-load), pk-f32 inverse last pass
# speedup vs baseline: 1.1158x; 1.0234x over previous
; HD float2 cmul(float2 a, float2 b){ return make_float2(a.x*b.x - a.y*b.y, a.x*b.y + a.y*b.x); }
; HD float2 cmulc(float2 a, float2 b){ return make_float2(a.x*b.x + a.y*b.y, a.y*b.x - a.x*b.y); }
; template<bool INV, bool NOTW>
; HD void bf4c(float2* Z, int i0, int i1, int i2, int i3, float2 w1, float2 w2, float2 w3){
;   float2 a0=Z[i0], a1=Z[i1], a2=Z[i2], a3=Z[i3];
;   if (INV && !NOTW){ a1=cmulc(a1,w1); a2=cmulc(a2,w2); a3=cmulc(a3,w3); }
;   float2 s02=make_float2(a0.x+a2.x,a0.y+a2.y), d02=make_float2(a0.x-a2.x,a0.y-a2.y);
;   float2 s13=make_float2(a1.x+a3.x,a1.y+a3.y), d13=make_float2(a1.x-a3.x,a1.y-a3.y);
;   float2 y0=make_float2(s02.x+s13.x,s02.y+s13.y), y2=make_float2(s02.x-s13.x,s02.y-s13.y);
;   float2 ym=make_float2(d02.x+d13.y,d02.y-d13.x);
;   float2 yp=make_float2(d02.x-d13.y,d02.y+d13.x);
;   float2 y1, y3;
;   if (INV){ y1=yp; y3=ym; } else if (NOTW){ y1=ym; y3=yp; } else { y1=cmul(ym,w1); y2=cmul(y2,w2); y3=cmul(yp,w3); }
;   Z[i0]=y0; Z[i1]=y1; Z[i2]=y2; Z[i3]=y3;
; }
; template<bool INV, int LQ, bool BARRIER=true>
; HD void fft_pass(float2* Z, const float2* twA, const float2* twB, int tid){
;     ...
;   } else {
;     int j=tid&(q-1); int base0=((tid>>LQ)<<(LQ+2))+j;
;     float2 w1=make_float2(1.f,0.f), w2=w1, w3=w1;
;     if (LQ>0){ int k=j*tws; w1=cmul(twA[k>>6],twB[k&63]); w2=cmul(w1,w1); w3=cmul(w2,w1); }
;     _Pragma("unroll") for (int i=0;i<8;++i){ int base=base0+i*2048; bf4c<INV,(LQ==0)>(Z,base,base+q,base+2*q,base+3*q,w1,w2,w3); }
;   }
;   if (BARRIER) __syncthreads(); else asm volatile("s_waitcnt lgkmcnt(0)" ::: "memory");
.Lmy_pf_st1:
	global_load_dwordx4 v[228:231], v232, s[98:99]
	global_load_dwordx4 v[228:231], v233, s[98:99]
	global_load_dwordx4 v[228:231], v234, s[98:99]
	global_load_dwordx4 v[228:231], v235, s[98:99]
	s_add_u32 s98, s98, 0x1000000
	s_addc_u32 s99, s99, 0
	global_load_dwordx4 v[228:231], v232, s[98:99]
	global_load_dwordx4 v[228:231], v233, s[98:99]
	global_load_dwordx4 v[228:231], v234, s[98:99]
	global_load_dwordx4 v[228:231], v235, s[98:99]
	s_waitcnt lgkmcnt(0)
	v_and_b32_e32 v226, 3, v154
	v_lshlrev_b32_e32 v224, 7, v226
	v_add_u32_e32 v224, 0x20800, v224
	v_mov_b32_e32 v225, 0x20a00
	ds_read_b64 v[238:239], v224
	ds_read_b64 v[240:241], v225
	s_waitcnt lgkmcnt(0)
	v_pk_mul_f32 v[30:31], v[238:239], v[240:241] op_sel:[1,1] op_sel_hi:[1,0]
	v_pk_fma_f32 v[16:17], v[238:239], v[240:241], v[30:31] op_sel:[0,0,0] op_sel_hi:[0,1,1] neg_lo:[0,0,1]
	v_pk_mul_f32 v[30:31], v[16:17], v[16:17] op_sel:[1,1] op_sel_hi:[1,0]
	v_pk_fma_f32 v[18:19], v[16:17], v[16:17], v[30:31] op_sel:[0,0,0] op_sel_hi:[0,1,1] neg_lo:[0,0,1]
	v_pk_mul_f32 v[30:31], v[18:19], v[16:17] op_sel:[1,1] op_sel_hi:[1,0]
	v_pk_fma_f32 v[20:21], v[18:19], v[16:17], v[30:31] op_sel:[0,0,0] op_sel_hi:[0,1,1] neg_lo:[0,0,1]
	v_lshrrev_b32_e32 v222, 2, v154
	v_lshlrev_b32_e32 v222, 4, v222
	v_add_u32_e32 v222, v222, v226
	v_lshlrev_b32_e32 v222, 3, v222
	v_add_u32_e32 v223, 0x10000, v222
	ds_read_b64 v[0:1], v222 offset:0
	ds_read_b64 v[2:3], v222 offset:32
	ds_read_b64 v[4:5], v222 offset:64
	ds_read_b64 v[6:7], v222 offset:96
	ds_read_b64 v[8:9], v222 offset:16384
	ds_read_b64 v[10:11], v222 offset:16416
	ds_read_b64 v[12:13], v222 offset:16448
	ds_read_b64 v[14:15], v222 offset:16480
	s_waitcnt lgkmcnt(4)
	v_pk_mul_f32 v[30:31], v[4:5], v[18:19] op_sel:[1,1] op_sel_hi:[0,1]
	v_pk_fma_f32 v[244:245], v[4:5], v[18:19], v[30:31] op_sel:[0,0,0] op_sel_hi:[1,0,1] neg_hi:[0,0,1]
	v_pk_mul_f32 v[30:31], v[2:3], v[16:17] op_sel:[1,1] op_sel_hi:[0,1]
	v_pk_fma_f32 v[242:243], v[2:3], v[16:17], v[30:31] op_sel:[0,0,0] op_sel_hi:[1,0,1] neg_hi:[0,0,1]
	v_pk_mul_f32 v[30:31], v[6:7], v[20:21] op_sel:[1,1] op_sel_hi:[0,1]
	v_pk_fma_f32 v[246:247], v[6:7], v[20:21], v[30:31] op_sel:[0,0,0] op_sel_hi:[1,0,1] neg_hi:[0,0,1]
	v_pk_add_f32 v[22:23], v[0:1], v[244:245]
	v_pk_add_f32 v[24:25], v[0:1], v[244:245] neg_lo:[0,1] neg_hi:[0,1]
	v_pk_add_f32 v[26:27], v[242:243], v[246:247]
	v_pk_add_f32 v[28:29], v[242:243], v[246:247] neg_lo:[0,1] neg_hi:[0,1]
	v_pk_add_f32 v[80:81], v[22:23], v[26:27]
	ds_write_b64 v222, v[80:81] offset:0
	v_pk_add_f32 v[82:83], v[24:25], v[28:29] op_sel:[0,1] op_sel_hi:[1,0] neg_lo:[0,1]
	ds_write_b64 v222, v[82:83] offset:32
	v_pk_add_f32 v[84:85], v[22:23], v[26:27] neg_lo:[0,1] neg_hi:[0,1]
	ds_write_b64 v222, v[84:85] offset:64
	v_pk_add_f32 v[236:237], v[24:25], v[28:29] op_sel:[0,1] op_sel_hi:[1,0] neg_hi:[0,1]
	ds_write_b64 v222, v[236:237] offset:96
	ds_read_b64 v[0:1], v222 offset:32768
	ds_read_b64 v[2:3], v222 offset:32800
	ds_read_b64 v[4:5], v222 offset:32832
	ds_read_b64 v[6:7], v222 offset:32864
	s_waitcnt lgkmcnt(8)
	v_pk_mul_f32 v[30:31], v[12:13], v[18:19] op_sel:[1,1] op_sel_hi:[0,1]
	v_pk_fma_f32 v[244:245], v[12:13], v[18:19], v[30:31] op_sel:[0,0,0] op_sel_hi:[1,0,1] neg_hi:[0,0,1]
	v_pk_mul_f32 v[30:31], v[10:11], v[16:17] op_sel:[1,1] op_sel_hi:[0,1]
	v_pk_fma_f32 v[242:243], v[10:11], v[16:17], v[30:31] op_sel:[0,0,0] op_sel_hi:[1,0,1] neg_hi:[0,0,1]
	v_pk_mul_f32 v[30:31], v[14:15], v[20:21] op_sel:[1,1] op_sel_hi:[0,1]
	v_pk_fma_f32 v[246:247], v[14:15], v[20:21], v[30:31] op_sel:[0,0,0] op_sel_hi:[1,0,1] neg_hi:[0,0,1]
	v_pk_add_f32 v[22:23], v[8:9], v[244:245]
	v_pk_add_f32 v[24:25], v[8:9], v[244:245] neg_lo:[0,1] neg_hi:[0,1]
	v_pk_add_f32 v[26:27], v[242:243], v[246:247]
	v_pk_add_f32 v[28:29], v[242:243], v[246:247] neg_lo:[0,1] neg_hi:[0,1]
	v_pk_add_f32 v[80:81], v[22:23], v[26:27]
	ds_write_b64 v222, v[80:81] offset:16384
	v_pk_add_f32 v[82:83], v[24:25], v[28:29] op_sel:[0,1] op_sel_hi:[1,0] neg_lo:[0,1]
	ds_write_b64 v222, v[82:83] offset:16416
	v_pk_add_f32 v[84:85], v[22:23], v[26:27] neg_lo:[0,1] neg_hi:[0,1]
	ds_write_b64 v222, v[84:85] offset:16448
	v_pk_add_f32 v[236:237], v[24:25], v[28:29] op_sel:[0,1] op_sel_hi:[1,0] neg_hi:[0,1]
	ds_write_b64 v222, v[236:237] offset:16480
	ds_read_b64 v[8:9], v222 offset:49152
	ds_read_b64 v[10:11], v222 offset:49184
	ds_read_b64 v[12:13], v222 offset:49216
	ds_read_b64 v[14:15], v222 offset:49248
	s_waitcnt lgkmcnt(8)
	v_pk_mul_f32 v[30:31], v[4:5], v[18:19] op_sel:[1,1] op_sel_hi:[0,1]
	v_pk_fma_f32 v[244:245], v[4:5], v[18:19], v[30:31] op_sel:[0,0,0] op_sel_hi:[1,0,1] neg_hi:[0,0,1]
	v_pk_mul_f32 v[30:31], v[2:3], v[16:17] op_sel:[1,1] op_sel_hi:[0,1]
	v_pk_fma_f32 v[242:243], v[2:3], v[16:17], v[30:31] op_sel:[0,0,0] op_sel_hi:[1,0,1] neg_hi:[0,0,1]
	v_pk_mul_f32 v[30:31], v[6:7], v[20:21] op_sel:[1,1] op_sel_hi:[0,1]
	v_pk_fma_f32 v[246:247], v[6:7], v[20:21], v[30:31] op_sel:[0,0,0] op_sel_hi:[1,0,1] neg_hi:[0,0,1]
	v_pk_add_f32 v[22:23], v[0:1], v[244:245]
	v_pk_add_f32 v[24:25], v[0:1], v[244:245] neg_lo:[0,1] neg_hi:[0,1]
	v_pk_add_f32 v[26:27], v[242:243], v[246:247]
	v_pk_add_f32 v[28:29], v[242:243], v[246:247] neg_lo:[0,1] neg_hi:[0,1]
	v_pk_add_f32 v[80:81], v[22:23], v[26:27]
	ds_write_b64 v222, v[80:81] offset:32768
	v_pk_add_f32 v[82:83], v[24:25], v[28:29] op_sel:[0,1] op_sel_hi:[1,0] neg_lo:[0,1]
	ds_write_b64 v222, v[82:83] offset:32800
	v_pk_add_f32 v[84:85], v[22:23], v[26:27] neg_lo:[0,1] neg_hi:[0,1]
	ds_write_b64 v222, v[84:85] offset:32832
	v_pk_add_f32 v[236:237], v[24:25], v[28:29] op_sel:[0,1] op_sel_hi:[1,0] neg_hi:[0,1]
	ds_write_b64 v222, v[236:237] offset:32864
	ds_read_b64 v[0:1], v223 offset:0
	ds_read_b64 v[2:3], v223 offset:32
	ds_read_b64 v[4:5], v223 offset:64
	ds_read_b64 v[6:7], v223 offset:96
	s_waitcnt lgkmcnt(8)
; HD float2 cmul(float2 a, float2 b){ return make_float2(a.x*b.x - a.y*b.y, a.x*b.y + a.y*b.x); }
; HD float2 cmulc(float2 a, float2 b){ return make_float2(a.x*b.x + a.y*b.y, a.y*b.x - a.x*b.y); }
; template<bool INV, bool NOTW>
; HD void bf4c(float2* Z, int i0, int i1, int i2, int i3, float2 w1, float2 w2, float2 w3){
;   float2 a0=Z[i0], a1=Z[i1], a2=Z[i2], a3=Z[i3];
;   if (INV && !NOTW){ a1=cmulc(a1,w1); a2=cmulc(a2,w2); a3=cmulc(a3,w3); }
;   float2 s02=make_float2(a0.x+a2.x,a0.y+a2.y), d02=make_float2(a0.x-a2.x,a0.y-a2.y);
;   float2 s13=make_float2(a1.x+a3.x,a1.y+a3.y), d13=make_float2(a1.x-a3.x,a1.y-a3.y);
;   float2 y0=make_float2(s02.x+s13.x,s02.y+s13.y), y2=make_float2(s02.x-s13.x,s02.y-s13.y);
;   float2 ym=make_float2(d02.x+d13.y,d02.y-d13.x);
;   float2 yp=make_float2(d02.x-d13.y,d02.y+d13.x);
;   float2 y1, y3;
;   if (INV){ y1=yp; y3=ym; } else if (NOTW){ y1=ym; y3=yp; } else { y1=cmul(ym,w1); y2=cmul(y2,w2); y3=cmul(yp,w3); }
;   Z[i0]=y0; Z[i1]=y1; Z[i2]=y2; Z[i3]=y3;
; }
; template<bool INV, int LQ, bool BARRIER=true>
; HD void fft_pass(float2* Z, const float2* twA, const float2* twB, int tid){
;     ...
;   } else {
;     int j=tid&(q-1); int base0=((tid>>LQ)<<(LQ+2))+j;
;     float2 w1=make_float2(1.f,0.f), w2=w1, w3=w1;
;     if (LQ>0){ int k=j*tws; w1=cmul(twA[k>>6],twB[k&63]); w2=cmul(w1,w1); w3=cmul(w2,w1); }
;     _Pragma("unroll") for (int i=0;i<8;++i){ int base=base0+i*2048; bf4c<INV,(LQ==0)>(Z,base,base+q,base+2*q,base+3*q,w1,w2,w3); }
;   }
	v_pk_mul_f32 v[30:31], v[12:13], v[18:19] op_sel:[1,1] op_sel_hi:[0,1]
	v_pk_fma_f32 v[244:245], v[12:13], v[18:19], v[30:31] op_sel:[0,0,0] op_sel_hi:[1,0,1] neg_hi:[0,0,1]
	v_pk_mul_f32 v[30:31], v[10:11], v[16:17] op_sel:[1,1] op_sel_hi:[0,1]
	v_pk_fma_f32 v[242:243], v[10:11], v[16:17], v[30:31] op_sel:[0,0,0] op_sel_hi:[1,0,1] neg_hi:[0,0,1]
	v_pk_mul_f32 v[30:31], v[14:15], v[20:21] op_sel:[1,1] op_sel_hi:[0,1]
	v_pk_fma_f32 v[246:247], v[14:15], v[20:21], v[30:31] op_sel:[0,0,0] op_sel_hi:[1,0,1] neg_hi:[0,0,1]
	v_pk_add_f32 v[22:23], v[8:9], v[244:245]
	v_pk_add_f32 v[24:25], v[8:9], v[244:245] neg_lo:[0,1] neg_hi:[0,1]
	v_pk_add_f32 v[26:27], v[242:243], v[246:247]
	v_pk_add_f32 v[28:29], v[242:243], v[246:247] neg_lo:[0,1] neg_hi:[0,1]
	v_pk_add_f32 v[80:81], v[22:23], v[26:27]
	ds_write_b64 v222, v[80:81] offset:49152
	v_pk_add_f32 v[82:83], v[24:25], v[28:29] op_sel:[0,1] op_sel_hi:[1,0] neg_lo:[0,1]
	ds_write_b64 v222, v[82:83] offset:49184
	v_pk_add_f32 v[84:85], v[22:23], v[26:27] neg_lo:[0,1] neg_hi:[0,1]
	ds_write_b64 v222, v[84:85] offset:49216
	v_pk_add_f32 v[236:237], v[24:25], v[28:29] op_sel:[0,1] op_sel_hi:[1,0] neg_hi:[0,1]
	ds_write_b64 v222, v[236:237] offset:49248
	ds_read_b64 v[8:9], v223 offset:16384
	ds_read_b64 v[10:11], v223 offset:16416
	ds_read_b64 v[12:13], v223 offset:16448
	ds_read_b64 v[14:15], v223 offset:16480
	s_waitcnt lgkmcnt(8)
	v_pk_mul_f32 v[30:31], v[4:5], v[18:19] op_sel:[1,1] op_sel_hi:[0,1]
	v_pk_fma_f32 v[244:245], v[4:5], v[18:19], v[30:31] op_sel:[0,0,0] op_sel_hi:[1,0,1] neg_hi:[0,0,1]
	v_pk_mul_f32 v[30:31], v[2:3], v[16:17] op_sel:[1,1] op_sel_hi:[0,1]
	v_pk_fma_f32 v[242:243], v[2:3], v[16:17], v[30:31] op_sel:[0,0,0] op_sel_hi:[1,0,1] neg_hi:[0,0,1]
	v_pk_mul_f32 v[30:31], v[6:7], v[20:21] op_sel:[1,1] op_sel_hi:[0,1]
	v_pk_fma_f32 v[246:247], v[6:7], v[20:21], v[30:31] op_sel:[0,0,0] op_sel_hi:[1,0,1] neg_hi:[0,0,1]
	v_pk_add_f32 v[22:23], v[0:1], v[244:245]
	v_pk_add_f32 v[24:25], v[0:1], v[244:245] neg_lo:[0,1] neg_hi:[0,1]
	v_pk_add_f32 v[26:27], v[242:243], v[246:247]
	v_pk_add_f32 v[28:29], v[242:243], v[246:247] neg_lo:[0,1] neg_hi:[0,1]
	v_pk_add_f32 v[80:81], v[22:23], v[26:27]
	ds_write_b64 v223, v[80:81] offset:0
	v_pk_add_f32 v[82:83], v[24:25], v[28:29] op_sel:[0,1] op_sel_hi:[1,0] neg_lo:[0,1]
	ds_write_b64 v223, v[82:83] offset:32
	v_pk_add_f32 v[84:85], v[22:23], v[26:27] neg_lo:[0,1] neg_hi:[0,1]
	ds_write_b64 v223, v[84:85] offset:64
	v_pk_add_f32 v[236:237], v[24:25], v[28:29] op_sel:[0,1] op_sel_hi:[1,0] neg_hi:[0,1]
	ds_write_b64 v223, v[236:237] offset:96
	ds_read_b64 v[0:1], v223 offset:32768
	ds_read_b64 v[2:3], v223 offset:32800
	ds_read_b64 v[4:5], v223 offset:32832
	ds_read_b64 v[6:7], v223 offset:32864
	s_waitcnt lgkmcnt(8)
	v_pk_mul_f32 v[30:31], v[12:13], v[18:19] op_sel:[1,1] op_sel_hi:[0,1]
	v_pk_fma_f32 v[244:245], v[12:13], v[18:19], v[30:31] op_sel:[0,0,0] op_sel_hi:[1,0,1] neg_hi:[0,0,1]
	v_pk_mul_f32 v[30:31], v[10:11], v[16:17] op_sel:[1,1] op_sel_hi:[0,1]
	v_pk_fma_f32 v[242:243], v[10:11], v[16:17], v[30:31] op_sel:[0,0,0] op_sel_hi:[1,0,1] neg_hi:[0,0,1]
	v_pk_mul_f32 v[30:31], v[14:15], v[20:21] op_sel:[1,1] op_sel_hi:[0,1]
	v_pk_fma_f32 v[246:247], v[14:15], v[20:21], v[30:31] op_sel:[0,0,0] op_sel_hi:[1,0,1] neg_hi:[0,0,1]
	v_pk_add_f32 v[22:23], v[8:9], v[244:245]
	v_pk_add_f32 v[24:25], v[8:9], v[244:245] neg_lo:[0,1] neg_hi:[0,1]
	v_pk_add_f32 v[26:27], v[242:243], v[246:247]
	v_pk_add_f32 v[28:29], v[242:243], v[246:247] neg_lo:[0,1] neg_hi:[0,1]
	v_pk_add_f32 v[80:81], v[22:23], v[26:27]
	ds_write_b64 v223, v[80:81] offset:16384
	v_pk_add_f32 v[82:83], v[24:25], v[28:29] op_sel:[0,1] op_sel_hi:[1,0] neg_lo:[0,1]
	ds_write_b64 v223, v[82:83] offset:16416
	v_pk_add_f32 v[84:85], v[22:23], v[26:27] neg_lo:[0,1] neg_hi:[0,1]
	ds_write_b64 v223, v[84:85] offset:16448
	v_pk_add_f32 v[236:237], v[24:25], v[28:29] op_sel:[0,1] op_sel_hi:[1,0] neg_hi:[0,1]
	ds_write_b64 v223, v[236:237] offset:16480
	ds_read_b64 v[8:9], v223 offset:49152
	ds_read_b64 v[10:11], v223 offset:49184
	ds_read_b64 v[12:13], v223 offset:49216
	ds_read_b64 v[14:15], v223 offset:49248
	s_waitcnt lgkmcnt(8)
	v_pk_mul_f32 v[30:31], v[4:5], v[18:19] op_sel:[1,1] op_sel_hi:[0,1]
	v_pk_fma_f32 v[244:245], v[4:5], v[18:19], v[30:31] op_sel:[0,0,0] op_sel_hi:[1,0,1] neg_hi:[0,0,1]
	v_pk_mul_f32 v[30:31], v[2:3], v[16:17] op_sel:[1,1] op_sel_hi:[0,1]
	v_pk_fma_f32 v[242:243], v[2:3], v[16:17], v[30:31] op_sel:[0,0,0] op_sel_hi:[1,0,1] neg_hi:[0,0,1]
	v_pk_mul_f32 v[30:31], v[6:7], v[20:21] op_sel:[1,1] op_sel_hi:[0,1]
	v_pk_fma_f32 v[246:247], v[6:7], v[20:21], v[30:31] op_sel:[0,0,0] op_sel_hi:[1,0,1] neg_hi:[0,0,1]
	v_pk_add_f32 v[22:23], v[0:1], v[244:245]
	v_pk_add_f32 v[24:25], v[0:1], v[244:245] neg_lo:[0,1] neg_hi:[0,1]
	v_pk_add_f32 v[26:27], v[242:243], v[246:247]
	v_pk_add_f32 v[28:29], v[242:243], v[246:247] neg_lo:[0,1] neg_hi:[0,1]
	v_pk_add_f32 v[80:81], v[22:23], v[26:27]
	ds_write_b64 v223, v[80:81] offset:32768
	v_pk_add_f32 v[82:83], v[24:25], v[28:29] op_sel:[0,1] op_sel_hi:[1,0] neg_lo:[0,1]
	ds_write_b64 v223, v[82:83] offset:32800
	v_pk_add_f32 v[84:85], v[22:23], v[26:27] neg_lo:[0,1] neg_hi:[0,1]
	ds_write_b64 v223, v[84:85] offset:32832
	v_pk_add_f32 v[236:237], v[24:25], v[28:29] op_sel:[0,1] op_sel_hi:[1,0] neg_hi:[0,1]
	ds_write_b64 v223, v[236:237] offset:32864
	s_waitcnt lgkmcnt(4)
; HD float2 cmul(float2 a, float2 b){ return make_float2(a.x*b.x - a.y*b.y, a.x*b.y + a.y*b.x); }
; template<bool INV, int LQ, bool BARRIER=true>
; HD void fft_pass(float2* Z, const float2* twA, const float2* twB, int tid){
;     ...
;     int j=tid&(q-1); int base0=((tid>>LQ)<<(LQ+2))+j;
;     float2 w1=make_float2(1.f,0.f), w2=w1, w3=w1;
;     if (LQ>0){ int k=j*tws; w1=cmul(twA[k>>6],twB[k&63]); w2=cmul(w1,w1); w3=cmul(w2,w1); }
;     _Pragma("unroll") for (int i=0;i<8;++i){ int base=base0+i*2048; bf4c<INV,(LQ==0)>(Z,base,base+q,base+2*q,base+3*q,w1,w2,w3); }
;   }
;   if (BARRIER) __syncthreads(); else asm volatile("s_waitcnt lgkmcnt(0)" ::: "memory");
; __device__ __forceinline__ void fft_inv_tail(float2* Z, const float2* twA, const float2* twB, int tid){
;   fft_pass<true,2,false>(Z,twA,twB,tid); fft_pass<true,4,false>(Z,twA,twB,tid); fft_pass<true,6>(Z,twA,twB,tid);
;   fft_pass<true,8>(Z,twA,twB,tid); fft_pass<true,10>(Z,twA,twB,tid);
	v_pk_mul_f32 v[30:31], v[12:13], v[18:19] op_sel:[1,1] op_sel_hi:[0,1]
	v_pk_fma_f32 v[244:245], v[12:13], v[18:19], v[30:31] op_sel:[0,0,0] op_sel_hi:[1,0,1] neg_hi:[0,0,1]
	v_pk_mul_f32 v[30:31], v[10:11], v[16:17] op_sel:[1,1] op_sel_hi:[0,1]
	v_pk_fma_f32 v[242:243], v[10:11], v[16:17], v[30:31] op_sel:[0,0,0] op_sel_hi:[1,0,1] neg_hi:[0,0,1]
	v_pk_mul_f32 v[30:31], v[14:15], v[20:21] op_sel:[1,1] op_sel_hi:[0,1]
	v_pk_fma_f32 v[246:247], v[14:15], v[20:21], v[30:31] op_sel:[0,0,0] op_sel_hi:[1,0,1] neg_hi:[0,0,1]
	v_pk_add_f32 v[22:23], v[8:9], v[244:245]
	v_pk_add_f32 v[24:25], v[8:9], v[244:245] neg_lo:[0,1] neg_hi:[0,1]
	v_pk_add_f32 v[26:27], v[242:243], v[246:247]
	v_pk_add_f32 v[28:29], v[242:243], v[246:247] neg_lo:[0,1] neg_hi:[0,1]
	v_pk_add_f32 v[80:81], v[22:23], v[26:27]
	ds_write_b64 v223, v[80:81] offset:49152
	v_pk_add_f32 v[82:83], v[24:25], v[28:29] op_sel:[0,1] op_sel_hi:[1,0] neg_lo:[0,1]
	ds_write_b64 v223, v[82:83] offset:49184
	v_pk_add_f32 v[84:85], v[22:23], v[26:27] neg_lo:[0,1] neg_hi:[0,1]
	ds_write_b64 v223, v[84:85] offset:49216
	v_pk_add_f32 v[236:237], v[24:25], v[28:29] op_sel:[0,1] op_sel_hi:[1,0] neg_hi:[0,1]
	ds_write_b64 v223, v[236:237] offset:49248
	s_waitcnt lgkmcnt(0)
	v_mov_b32_e32 v222, 0x3f6c835e
	v_mov_b32_e32 v223, 0x3ec3ef15
	v_mov_b32_e32 v224, 0x3f3504f3
	v_mov_b32_e32 v225, 0x3f3504f3
	v_and_b32_e32 v8, 15, v154
	v_lshlrev_b32_e32 v9, 3, v8
	v_add_u32_e32 v9, 0x20800, v9
	v_mov_b32_e32 v10, 0x20a00
	ds_read_b64 v[0:1], v9
	ds_read_b64 v[2:3], v10
	s_waitcnt lgkmcnt(0)
	v_pk_mul_f32 v[250:251], v[0:1], v[2:3] op_sel:[1,1] op_sel_hi:[1,0]
	v_pk_fma_f32 v[80:81], v[0:1], v[2:3], v[250:251] op_sel:[0,0,0] op_sel_hi:[0,1,1] neg_lo:[0,0,1]
	v_pk_mul_f32 v[250:251], v[80:81], v[80:81] op_sel:[1,1] op_sel_hi:[1,0]
	v_pk_fma_f32 v[82:83], v[80:81], v[80:81], v[250:251] op_sel:[0,0,0] op_sel_hi:[0,1,1] neg_lo:[0,0,1]
	v_pk_mul_f32 v[250:251], v[82:83], v[80:81] op_sel:[1,1] op_sel_hi:[1,0]
	v_pk_fma_f32 v[84:85], v[82:83], v[80:81], v[250:251] op_sel:[0,0,0] op_sel_hi:[0,1,1] neg_lo:[0,0,1]
	v_lshlrev_b32_e32 v9, 5, v8
	v_add_u32_e32 v9, 0x20800, v9
	v_mov_b32_e32 v10, 0x20a00
	ds_read_b64 v[0:1], v9
	ds_read_b64 v[2:3], v10
	s_waitcnt lgkmcnt(0)
	v_pk_mul_f32 v[250:251], v[0:1], v[2:3] op_sel:[1,1] op_sel_hi:[1,0]
	v_pk_fma_f32 v[236:237], v[0:1], v[2:3], v[250:251] op_sel:[0,0,0] op_sel_hi:[0,1,1] neg_lo:[0,0,1]
	v_pk_mul_f32 v[250:251], v[236:237], v[236:237] op_sel:[1,1] op_sel_hi:[1,0]
	v_pk_fma_f32 v[238:239], v[236:237], v[236:237], v[250:251] op_sel:[0,0,0] op_sel_hi:[0,1,1] neg_lo:[0,0,1]
	v_pk_mul_f32 v[250:251], v[238:239], v[236:237] op_sel:[1,1] op_sel_hi:[1,0]
	v_pk_fma_f32 v[240:241], v[238:239], v[236:237], v[250:251] op_sel:[0,0,0] op_sel_hi:[0,1,1] neg_lo:[0,0,1]
	v_lshrrev_b32_e32 v226, 6, v154
	v_bfe_u32 v227, v154, 4, 2
	v_lshl_add_u32 v226, v227, 3, v226
	v_lshlrev_b32_e32 v226, 8, v226
	v_and_b32_e32 v227, 15, v154
	v_add_u32_e32 v226, v226, v227
	v_lshlrev_b32_e32 v226, 3, v226
	v_add_u32_e32 v227, 0x10000, v226
	ds_read_b64 v[0:1], v226 offset:0
	ds_read_b64 v[2:3], v226 offset:128
	ds_read_b64 v[4:5], v226 offset:256
	ds_read_b64 v[6:7], v226 offset:384
	ds_read_b64 v[8:9], v226 offset:512
	ds_read_b64 v[10:11], v226 offset:640
	ds_read_b64 v[12:13], v226 offset:768
	ds_read_b64 v[14:15], v226 offset:896
	ds_read_b64 v[16:17], v226 offset:1024
	ds_read_b64 v[18:19], v226 offset:1152
	ds_read_b64 v[20:21], v226 offset:1280
	ds_read_b64 v[22:23], v226 offset:1408
	ds_read_b64 v[24:25], v226 offset:1536
	ds_read_b64 v[26:27], v226 offset:1664
	ds_read_b64 v[28:29], v226 offset:1792
	ds_read_b64 v[30:31], v226 offset:1920
	s_waitcnt lgkmcnt(12)
	v_pk_mul_f32 v[250:251], v[4:5], v[238:239] op_sel:[1,1] op_sel_hi:[0,1]
	v_pk_fma_f32 v[4:5], v[4:5], v[238:239], v[250:251] op_sel:[0,0,0] op_sel_hi:[1,0,1] neg_hi:[0,0,1]
	v_pk_mul_f32 v[250:251], v[2:3], v[236:237] op_sel:[1,1] op_sel_hi:[0,1]
	v_pk_fma_f32 v[2:3], v[2:3], v[236:237], v[250:251] op_sel:[0,0,0] op_sel_hi:[1,0,1] neg_hi:[0,0,1]
	v_pk_mul_f32 v[250:251], v[6:7], v[240:241] op_sel:[1,1] op_sel_hi:[0,1]
	v_pk_fma_f32 v[6:7], v[6:7], v[240:241], v[250:251] op_sel:[0,0,0] op_sel_hi:[1,0,1] neg_hi:[0,0,1]
	v_pk_add_f32 v[242:243], v[0:1], v[4:5]
	v_pk_add_f32 v[244:245], v[0:1], v[4:5] neg_lo:[0,1] neg_hi:[0,1]
	v_pk_add_f32 v[246:247], v[2:3], v[6:7]
	v_pk_add_f32 v[248:249], v[2:3], v[6:7] neg_lo:[0,1] neg_hi:[0,1]
	v_pk_add_f32 v[0:1], v[242:243], v[246:247]
	v_pk_add_f32 v[2:3], v[244:245], v[248:249] op_sel:[0,1] op_sel_hi:[1,0] neg_lo:[0,1]
	v_pk_add_f32 v[4:5], v[242:243], v[246:247] neg_lo:[0,1] neg_hi:[0,1]
	v_pk_add_f32 v[6:7], v[244:245], v[248:249] op_sel:[0,1] op_sel_hi:[1,0] neg_hi:[0,1]
	s_waitcnt lgkmcnt(8)
	v_pk_mul_f32 v[250:251], v[12:13], v[238:239] op_sel:[1,1] op_sel_hi:[0,1]
	v_pk_fma_f32 v[12:13], v[12:13], v[238:239], v[250:251] op_sel:[0,0,0] op_sel_hi:[1,0,1] neg_hi:[0,0,1]
	v_pk_mul_f32 v[250:251], v[10:11], v[236:237] op_sel:[1,1] op_sel_hi:[0,1]
	v_pk_fma_f32 v[10:11], v[10:11], v[236:237], v[250:251] op_sel:[0,0,0] op_sel_hi:[1,0,1] neg_hi:[0,0,1]
	v_pk_mul_f32 v[250:251], v[14:15], v[240:241] op_sel:[1,1] op_sel_hi:[0,1]
	v_pk_fma_f32 v[14:15], v[14:15], v[240:241], v[250:251] op_sel:[0,0,0] op_sel_hi:[1,0,1] neg_hi:[0,0,1]
	v_pk_add_f32 v[242:243], v[8:9], v[12:13]
	v_pk_add_f32 v[244:245], v[8:9], v[12:13] neg_lo:[0,1] neg_hi:[0,1]
	v_pk_add_f32 v[246:247], v[10:11], v[14:15]
	v_pk_add_f32 v[248:249], v[10:11], v[14:15] neg_lo:[0,1] neg_hi:[0,1]
	v_pk_add_f32 v[8:9], v[242:243], v[246:247]
	v_pk_add_f32 v[10:11], v[244:245], v[248:249] op_sel:[0,1] op_sel_hi:[1,0] neg_lo:[0,1]
	v_pk_add_f32 v[12:13], v[242:243], v[246:247] neg_lo:[0,1] neg_hi:[0,1]
	v_pk_add_f32 v[14:15], v[244:245], v[248:249] op_sel:[0,1] op_sel_hi:[1,0] neg_hi:[0,1]
	s_waitcnt lgkmcnt(4)
; HD float2 cmul(float2 a, float2 b){ return make_float2(a.x*b.x - a.y*b.y, a.x*b.y + a.y*b.x); }
; HD float2 cmulc(float2 a, float2 b){ return make_float2(a.x*b.x + a.y*b.y, a.y*b.x - a.x*b.y); }
; template<bool INV, bool NOTW>
; HD void bf4c(float2* Z, int i0, int i1, int i2, int i3, float2 w1, float2 w2, float2 w3){
;   float2 a0=Z[i0], a1=Z[i1], a2=Z[i2], a3=Z[i3];
;   if (INV && !NOTW){ a1=cmulc(a1,w1); a2=cmulc(a2,w2); a3=cmulc(a3,w3); }
;   float2 s02=make_float2(a0.x+a2.x,a0.y+a2.y), d02=make_float2(a0.x-a2.x,a0.y-a2.y);
;   float2 s13=make_float2(a1.x+a3.x,a1.y+a3.y), d13=make_float2(a1.x-a3.x,a1.y-a3.y);
;   float2 y0=make_float2(s02.x+s13.x,s02.y+s13.y), y2=make_float2(s02.x-s13.x,s02.y-s13.y);
;   float2 ym=make_float2(d02.x+d13.y,d02.y-d13.x);
;   float2 yp=make_float2(d02.x-d13.y,d02.y+d13.x);
;   float2 y1, y3;
;   if (INV){ y1=yp; y3=ym; } else if (NOTW){ y1=ym; y3=yp; } else { y1=cmul(ym,w1); y2=cmul(y2,w2); y3=cmul(yp,w3); }
;   Z[i0]=y0; Z[i1]=y1; Z[i2]=y2; Z[i3]=y3;
; }
; __device__ __forceinline__ void fft_inv_tail(float2* Z, const float2* twA, const float2* twB, int tid){
;   fft_pass<true,2,false>(Z,twA,twB,tid); fft_pass<true,4,false>(Z,twA,twB,tid); fft_pass<true,6>(Z,twA,twB,tid);
;   fft_pass<true,8>(Z,twA,twB,tid); fft_pass<true,10>(Z,twA,twB,tid);
	v_pk_mul_f32 v[250:251], v[20:21], v[238:239] op_sel:[1,1] op_sel_hi:[0,1]
	v_pk_fma_f32 v[20:21], v[20:21], v[238:239], v[250:251] op_sel:[0,0,0] op_sel_hi:[1,0,1] neg_hi:[0,0,1]
	v_pk_mul_f32 v[250:251], v[18:19], v[236:237] op_sel:[1,1] op_sel_hi:[0,1]
	v_pk_fma_f32 v[18:19], v[18:19], v[236:237], v[250:251] op_sel:[0,0,0] op_sel_hi:[1,0,1] neg_hi:[0,0,1]
	v_pk_mul_f32 v[250:251], v[22:23], v[240:241] op_sel:[1,1] op_sel_hi:[0,1]
	v_pk_fma_f32 v[22:23], v[22:23], v[240:241], v[250:251] op_sel:[0,0,0] op_sel_hi:[1,0,1] neg_hi:[0,0,1]
	v_pk_add_f32 v[242:243], v[16:17], v[20:21]
	v_pk_add_f32 v[244:245], v[16:17], v[20:21] neg_lo:[0,1] neg_hi:[0,1]
	v_pk_add_f32 v[246:247], v[18:19], v[22:23]
	v_pk_add_f32 v[248:249], v[18:19], v[22:23] neg_lo:[0,1] neg_hi:[0,1]
	v_pk_add_f32 v[16:17], v[242:243], v[246:247]
	v_pk_add_f32 v[18:19], v[244:245], v[248:249] op_sel:[0,1] op_sel_hi:[1,0] neg_lo:[0,1]
	v_pk_add_f32 v[20:21], v[242:243], v[246:247] neg_lo:[0,1] neg_hi:[0,1]
	v_pk_add_f32 v[22:23], v[244:245], v[248:249] op_sel:[0,1] op_sel_hi:[1,0] neg_hi:[0,1]
	s_waitcnt lgkmcnt(0)
	v_pk_mul_f32 v[250:251], v[28:29], v[238:239] op_sel:[1,1] op_sel_hi:[0,1]
	v_pk_fma_f32 v[28:29], v[28:29], v[238:239], v[250:251] op_sel:[0,0,0] op_sel_hi:[1,0,1] neg_hi:[0,0,1]
	v_pk_mul_f32 v[250:251], v[26:27], v[236:237] op_sel:[1,1] op_sel_hi:[0,1]
	v_pk_fma_f32 v[26:27], v[26:27], v[236:237], v[250:251] op_sel:[0,0,0] op_sel_hi:[1,0,1] neg_hi:[0,0,1]
	v_pk_mul_f32 v[250:251], v[30:31], v[240:241] op_sel:[1,1] op_sel_hi:[0,1]
	v_pk_fma_f32 v[30:31], v[30:31], v[240:241], v[250:251] op_sel:[0,0,0] op_sel_hi:[1,0,1] neg_hi:[0,0,1]
	v_pk_add_f32 v[242:243], v[24:25], v[28:29]
	v_pk_add_f32 v[244:245], v[24:25], v[28:29] neg_lo:[0,1] neg_hi:[0,1]
	v_pk_add_f32 v[246:247], v[26:27], v[30:31]
	v_pk_add_f32 v[248:249], v[26:27], v[30:31] neg_lo:[0,1] neg_hi:[0,1]
	v_pk_add_f32 v[24:25], v[242:243], v[246:247]
	v_pk_add_f32 v[26:27], v[244:245], v[248:249] op_sel:[0,1] op_sel_hi:[1,0] neg_lo:[0,1]
	v_pk_add_f32 v[28:29], v[242:243], v[246:247] neg_lo:[0,1] neg_hi:[0,1]
	v_pk_add_f32 v[30:31], v[244:245], v[248:249] op_sel:[0,1] op_sel_hi:[1,0] neg_hi:[0,1]
	v_pk_mul_f32 v[250:251], v[16:17], v[82:83] op_sel:[1,1] op_sel_hi:[0,1]
	v_pk_fma_f32 v[16:17], v[16:17], v[82:83], v[250:251] op_sel:[0,0,0] op_sel_hi:[1,0,1] neg_hi:[0,0,1]
	v_pk_mul_f32 v[250:251], v[8:9], v[80:81] op_sel:[1,1] op_sel_hi:[0,1]
	v_pk_fma_f32 v[8:9], v[8:9], v[80:81], v[250:251] op_sel:[0,0,0] op_sel_hi:[1,0,1] neg_hi:[0,0,1]
	v_pk_mul_f32 v[250:251], v[24:25], v[84:85] op_sel:[1,1] op_sel_hi:[0,1]
	v_pk_fma_f32 v[24:25], v[24:25], v[84:85], v[250:251] op_sel:[0,0,0] op_sel_hi:[1,0,1] neg_hi:[0,0,1]
	v_pk_add_f32 v[242:243], v[0:1], v[16:17]
	v_pk_add_f32 v[244:245], v[0:1], v[16:17] neg_lo:[0,1] neg_hi:[0,1]
	v_pk_add_f32 v[246:247], v[8:9], v[24:25]
	v_pk_add_f32 v[248:249], v[8:9], v[24:25] neg_lo:[0,1] neg_hi:[0,1]
	v_pk_add_f32 v[0:1], v[242:243], v[246:247]
	ds_write_b64 v226, v[0:1] offset:0
	v_pk_add_f32 v[8:9], v[244:245], v[248:249] op_sel:[0,1] op_sel_hi:[1,0] neg_lo:[0,1]
	ds_write_b64 v226, v[8:9] offset:512
	v_pk_add_f32 v[16:17], v[242:243], v[246:247] neg_lo:[0,1] neg_hi:[0,1]
	ds_write_b64 v226, v[16:17] offset:1024
	v_pk_add_f32 v[24:25], v[244:245], v[248:249] op_sel:[0,1] op_sel_hi:[1,0] neg_hi:[0,1]
	ds_write_b64 v226, v[24:25] offset:1536
	v_pk_mul_f32 v[250:251], v[18:19], v[224:225] op_sel:[1,1] op_sel_hi:[1,0] neg_lo:[0,0] neg_hi:[0,0]
	v_pk_fma_f32 v[18:19], v[18:19], v[224:225], v[250:251] op_sel:[0,0,0] op_sel_hi:[0,1,1] neg_lo:[0,0,1] neg_hi:[0,0,0]
	v_pk_mul_f32 v[250:251], v[18:19], v[82:83] op_sel:[1,1] op_sel_hi:[0,1]
	v_pk_fma_f32 v[18:19], v[18:19], v[82:83], v[250:251] op_sel:[0,0,0] op_sel_hi:[1,0,1] neg_hi:[0,0,1]
	v_pk_mul_f32 v[250:251], v[10:11], v[222:223] op_sel:[1,1] op_sel_hi:[1,0] neg_lo:[0,0] neg_hi:[0,0]
	v_pk_fma_f32 v[10:11], v[10:11], v[222:223], v[250:251] op_sel:[0,0,0] op_sel_hi:[0,1,1] neg_lo:[0,0,1] neg_hi:[0,0,0]
	v_pk_mul_f32 v[250:251], v[10:11], v[80:81] op_sel:[1,1] op_sel_hi:[0,1]
	v_pk_fma_f32 v[10:11], v[10:11], v[80:81], v[250:251] op_sel:[0,0,0] op_sel_hi:[1,0,1] neg_hi:[0,0,1]
	v_pk_mul_f32 v[250:251], v[26:27], v[222:223] op_sel:[1,0] op_sel_hi:[1,1] neg_lo:[0,0] neg_hi:[0,0]
	v_pk_fma_f32 v[26:27], v[26:27], v[222:223], v[250:251] op_sel:[0,1,0] op_sel_hi:[0,0,1] neg_lo:[0,0,1] neg_hi:[0,0,0]
	v_pk_mul_f32 v[250:251], v[26:27], v[84:85] op_sel:[1,1] op_sel_hi:[0,1]
	v_pk_fma_f32 v[26:27], v[26:27], v[84:85], v[250:251] op_sel:[0,0,0] op_sel_hi:[1,0,1] neg_hi:[0,0,1]
	v_pk_add_f32 v[242:243], v[2:3], v[18:19]
	v_pk_add_f32 v[244:245], v[2:3], v[18:19] neg_lo:[0,1] neg_hi:[0,1]
	v_pk_add_f32 v[246:247], v[10:11], v[26:27]
	v_pk_add_f32 v[248:249], v[10:11], v[26:27] neg_lo:[0,1] neg_hi:[0,1]
	v_pk_add_f32 v[2:3], v[242:243], v[246:247]
	ds_write_b64 v226, v[2:3] offset:128
	v_pk_add_f32 v[10:11], v[244:245], v[248:249] op_sel:[0,1] op_sel_hi:[1,0] neg_lo:[0,1]
	ds_write_b64 v226, v[10:11] offset:640
	v_pk_add_f32 v[18:19], v[242:243], v[246:247] neg_lo:[0,1] neg_hi:[0,1]
	ds_write_b64 v226, v[18:19] offset:1152
	v_pk_add_f32 v[26:27], v[244:245], v[248:249] op_sel:[0,1] op_sel_hi:[1,0] neg_hi:[0,1]
	ds_write_b64 v226, v[26:27] offset:1664
	v_pk_add_f32 v[20:21], v[20:21], 0 op_sel:[1,0] op_sel_hi:[0,0] neg_lo:[1,0]
	v_pk_mul_f32 v[250:251], v[20:21], v[82:83] op_sel:[1,1] op_sel_hi:[0,1]
	v_pk_fma_f32 v[20:21], v[20:21], v[82:83], v[250:251] op_sel:[0,0,0] op_sel_hi:[1,0,1] neg_hi:[0,0,1]
	v_pk_mul_f32 v[250:251], v[12:13], v[224:225] op_sel:[1,1] op_sel_hi:[1,0] neg_lo:[0,0] neg_hi:[0,0]
; HD float2 cmul(float2 a, float2 b){ return make_float2(a.x*b.x - a.y*b.y, a.x*b.y + a.y*b.x); }
; HD float2 cmulc(float2 a, float2 b){ return make_float2(a.x*b.x + a.y*b.y, a.y*b.x - a.x*b.y); }
; template<bool INV, bool NOTW>
; HD void bf4c(float2* Z, int i0, int i1, int i2, int i3, float2 w1, float2 w2, float2 w3){
;   float2 a0=Z[i0], a1=Z[i1], a2=Z[i2], a3=Z[i3];
;   if (INV && !NOTW){ a1=cmulc(a1,w1); a2=cmulc(a2,w2); a3=cmulc(a3,w3); }
;   float2 s02=make_float2(a0.x+a2.x,a0.y+a2.y), d02=make_float2(a0.x-a2.x,a0.y-a2.y);
;   float2 s13=make_float2(a1.x+a3.x,a1.y+a3.y), d13=make_float2(a1.x-a3.x,a1.y-a3.y);
;   float2 y0=make_float2(s02.x+s13.x,s02.y+s13.y), y2=make_float2(s02.x-s13.x,s02.y-s13.y);
;   float2 ym=make_float2(d02.x+d13.y,d02.y-d13.x);
;   float2 yp=make_float2(d02.x-d13.y,d02.y+d13.x);
;   float2 y1, y3;
;   if (INV){ y1=yp; y3=ym; } else if (NOTW){ y1=ym; y3=yp; } else { y1=cmul(ym,w1); y2=cmul(y2,w2); y3=cmul(yp,w3); }
;   Z[i0]=y0; Z[i1]=y1; Z[i2]=y2; Z[i3]=y3;
; }
; __device__ __forceinline__ void fft_inv_tail(float2* Z, const float2* twA, const float2* twB, int tid){
;   fft_pass<true,2,false>(Z,twA,twB,tid); fft_pass<true,4,false>(Z,twA,twB,tid); fft_pass<true,6>(Z,twA,twB,tid);
;   fft_pass<true,8>(Z,twA,twB,tid); fft_pass<true,10>(Z,twA,twB,tid);
	v_pk_fma_f32 v[12:13], v[12:13], v[224:225], v[250:251] op_sel:[0,0,0] op_sel_hi:[0,1,1] neg_lo:[0,0,1] neg_hi:[0,0,0]
	v_pk_mul_f32 v[250:251], v[12:13], v[80:81] op_sel:[1,1] op_sel_hi:[0,1]
	v_pk_fma_f32 v[12:13], v[12:13], v[80:81], v[250:251] op_sel:[0,0,0] op_sel_hi:[1,0,1] neg_hi:[0,0,1]
	v_pk_mul_f32 v[250:251], v[28:29], v[224:225] op_sel:[1,1] op_sel_hi:[1,0] neg_lo:[0,0] neg_hi:[0,1]
	v_pk_fma_f32 v[28:29], v[28:29], v[224:225], v[250:251] op_sel:[0,0,0] op_sel_hi:[0,1,1] neg_lo:[0,1,1] neg_hi:[0,0,0]
	v_pk_mul_f32 v[250:251], v[28:29], v[84:85] op_sel:[1,1] op_sel_hi:[0,1]
	v_pk_fma_f32 v[28:29], v[28:29], v[84:85], v[250:251] op_sel:[0,0,0] op_sel_hi:[1,0,1] neg_hi:[0,0,1]
	v_pk_add_f32 v[242:243], v[4:5], v[20:21]
	v_pk_add_f32 v[244:245], v[4:5], v[20:21] neg_lo:[0,1] neg_hi:[0,1]
	v_pk_add_f32 v[246:247], v[12:13], v[28:29]
	v_pk_add_f32 v[248:249], v[12:13], v[28:29] neg_lo:[0,1] neg_hi:[0,1]
	v_pk_add_f32 v[4:5], v[242:243], v[246:247]
	ds_write_b64 v226, v[4:5] offset:256
	v_pk_add_f32 v[12:13], v[244:245], v[248:249] op_sel:[0,1] op_sel_hi:[1,0] neg_lo:[0,1]
	ds_write_b64 v226, v[12:13] offset:768
	v_pk_add_f32 v[20:21], v[242:243], v[246:247] neg_lo:[0,1] neg_hi:[0,1]
	ds_write_b64 v226, v[20:21] offset:1280
	v_pk_add_f32 v[28:29], v[244:245], v[248:249] op_sel:[0,1] op_sel_hi:[1,0] neg_hi:[0,1]
	ds_write_b64 v226, v[28:29] offset:1792
	v_pk_mul_f32 v[250:251], v[22:23], v[224:225] op_sel:[1,1] op_sel_hi:[1,0] neg_lo:[0,0] neg_hi:[0,1]
	v_pk_fma_f32 v[22:23], v[22:23], v[224:225], v[250:251] op_sel:[0,0,0] op_sel_hi:[0,1,1] neg_lo:[0,1,1] neg_hi:[0,0,0]
	v_pk_mul_f32 v[250:251], v[22:23], v[82:83] op_sel:[1,1] op_sel_hi:[0,1]
	v_pk_fma_f32 v[22:23], v[22:23], v[82:83], v[250:251] op_sel:[0,0,0] op_sel_hi:[1,0,1] neg_hi:[0,0,1]
	v_pk_mul_f32 v[250:251], v[14:15], v[222:223] op_sel:[1,0] op_sel_hi:[1,1] neg_lo:[0,0] neg_hi:[0,0]
	v_pk_fma_f32 v[14:15], v[14:15], v[222:223], v[250:251] op_sel:[0,1,0] op_sel_hi:[0,0,1] neg_lo:[0,0,1] neg_hi:[0,0,0]
	v_pk_mul_f32 v[250:251], v[14:15], v[80:81] op_sel:[1,1] op_sel_hi:[0,1]
	v_pk_fma_f32 v[14:15], v[14:15], v[80:81], v[250:251] op_sel:[0,0,0] op_sel_hi:[1,0,1] neg_hi:[0,0,1]
	v_pk_mul_f32 v[250:251], v[30:31], v[222:223] op_sel:[1,1] op_sel_hi:[1,0] neg_lo:[0,1] neg_hi:[0,1]
	v_pk_fma_f32 v[30:31], v[30:31], v[222:223], v[250:251] op_sel:[0,0,0] op_sel_hi:[0,1,1] neg_lo:[0,1,1] neg_hi:[0,1,0]
	v_pk_mul_f32 v[250:251], v[30:31], v[84:85] op_sel:[1,1] op_sel_hi:[0,1]
	v_pk_fma_f32 v[30:31], v[30:31], v[84:85], v[250:251] op_sel:[0,0,0] op_sel_hi:[1,0,1] neg_hi:[0,0,1]
	v_pk_add_f32 v[242:243], v[6:7], v[22:23]
	v_pk_add_f32 v[244:245], v[6:7], v[22:23] neg_lo:[0,1] neg_hi:[0,1]
	v_pk_add_f32 v[246:247], v[14:15], v[30:31]
	v_pk_add_f32 v[248:249], v[14:15], v[30:31] neg_lo:[0,1] neg_hi:[0,1]
	v_pk_add_f32 v[6:7], v[242:243], v[246:247]
	ds_write_b64 v226, v[6:7] offset:384
	v_pk_add_f32 v[14:15], v[244:245], v[248:249] op_sel:[0,1] op_sel_hi:[1,0] neg_lo:[0,1]
	ds_write_b64 v226, v[14:15] offset:896
	v_pk_add_f32 v[22:23], v[242:243], v[246:247] neg_lo:[0,1] neg_hi:[0,1]
	ds_write_b64 v226, v[22:23] offset:1408
	v_pk_add_f32 v[30:31], v[244:245], v[248:249] op_sel:[0,1] op_sel_hi:[1,0] neg_hi:[0,1]
	ds_write_b64 v226, v[30:31] offset:1920
	ds_read_b64 v[0:1], v227 offset:0
	ds_read_b64 v[2:3], v227 offset:128
	ds_read_b64 v[4:5], v227 offset:256
	ds_read_b64 v[6:7], v227 offset:384
	ds_read_b64 v[8:9], v227 offset:512
	ds_read_b64 v[10:11], v227 offset:640
	ds_read_b64 v[12:13], v227 offset:768
	ds_read_b64 v[14:15], v227 offset:896
	ds_read_b64 v[16:17], v227 offset:1024
	ds_read_b64 v[18:19], v227 offset:1152
	ds_read_b64 v[20:21], v227 offset:1280
	ds_read_b64 v[22:23], v227 offset:1408
	ds_read_b64 v[24:25], v227 offset:1536
	ds_read_b64 v[26:27], v227 offset:1664
	ds_read_b64 v[28:29], v227 offset:1792
	ds_read_b64 v[30:31], v227 offset:1920
	s_waitcnt lgkmcnt(12)
	v_pk_mul_f32 v[250:251], v[4:5], v[238:239] op_sel:[1,1] op_sel_hi:[0,1]
	v_pk_fma_f32 v[4:5], v[4:5], v[238:239], v[250:251] op_sel:[0,0,0] op_sel_hi:[1,0,1] neg_hi:[0,0,1]
	v_pk_mul_f32 v[250:251], v[2:3], v[236:237] op_sel:[1,1] op_sel_hi:[0,1]
	v_pk_fma_f32 v[2:3], v[2:3], v[236:237], v[250:251] op_sel:[0,0,0] op_sel_hi:[1,0,1] neg_hi:[0,0,1]
	v_pk_mul_f32 v[250:251], v[6:7], v[240:241] op_sel:[1,1] op_sel_hi:[0,1]
	v_pk_fma_f32 v[6:7], v[6:7], v[240:241], v[250:251] op_sel:[0,0,0] op_sel_hi:[1,0,1] neg_hi:[0,0,1]
	v_pk_add_f32 v[242:243], v[0:1], v[4:5]
	v_pk_add_f32 v[244:245], v[0:1], v[4:5] neg_lo:[0,1] neg_hi:[0,1]
	v_pk_add_f32 v[246:247], v[2:3], v[6:7]
	v_pk_add_f32 v[248:249], v[2:3], v[6:7] neg_lo:[0,1] neg_hi:[0,1]
	v_pk_add_f32 v[0:1], v[242:243], v[246:247]
	v_pk_add_f32 v[2:3], v[244:245], v[248:249] op_sel:[0,1] op_sel_hi:[1,0] neg_lo:[0,1]
	v_pk_add_f32 v[4:5], v[242:243], v[246:247] neg_lo:[0,1] neg_hi:[0,1]
	v_pk_add_f32 v[6:7], v[244:245], v[248:249] op_sel:[0,1] op_sel_hi:[1,0] neg_hi:[0,1]
	s_waitcnt lgkmcnt(8)
	v_pk_mul_f32 v[250:251], v[12:13], v[238:239] op_sel:[1,1] op_sel_hi:[0,1]
	v_pk_fma_f32 v[12:13], v[12:13], v[238:239], v[250:251] op_sel:[0,0,0] op_sel_hi:[1,0,1] neg_hi:[0,0,1]
	v_pk_mul_f32 v[250:251], v[10:11], v[236:237] op_sel:[1,1] op_sel_hi:[0,1]
	v_pk_fma_f32 v[10:11], v[10:11], v[236:237], v[250:251] op_sel:[0,0,0] op_sel_hi:[1,0,1] neg_hi:[0,0,1]
	v_pk_mul_f32 v[250:251], v[14:15], v[240:241] op_sel:[1,1] op_sel_hi:[0,1]
	v_pk_fma_f32 v[14:15], v[14:15], v[240:241], v[250:251] op_sel:[0,0,0] op_sel_hi:[1,0,1] neg_hi:[0,0,1]
	v_pk_add_f32 v[242:243], v[8:9], v[12:13]
	v_pk_add_f32 v[244:245], v[8:9], v[12:13] neg_lo:[0,1] neg_hi:[0,1]
	v_pk_add_f32 v[246:247], v[10:11], v[14:15]
	v_pk_add_f32 v[248:249], v[10:11], v[14:15] neg_lo:[0,1] neg_hi:[0,1]
	v_pk_add_f32 v[8:9], v[242:243], v[246:247]
	v_pk_add_f32 v[10:11], v[244:245], v[248:249] op_sel:[0,1] op_sel_hi:[1,0] neg_lo:[0,1]
	v_pk_add_f32 v[12:13], v[242:243], v[246:247] neg_lo:[0,1] neg_hi:[0,1]
	v_pk_add_f32 v[14:15], v[244:245], v[248:249] op_sel:[0,1] op_sel_hi:[1,0] neg_hi:[0,1]
	s_waitcnt lgkmcnt(4)
; HD float2 cmul(float2 a, float2 b){ return make_float2(a.x*b.x - a.y*b.y, a.x*b.y + a.y*b.x); }
; HD float2 cmulc(float2 a, float2 b){ return make_float2(a.x*b.x + a.y*b.y, a.y*b.x - a.x*b.y); }
; template<bool INV, bool NOTW>
; HD void bf4c(float2* Z, int i0, int i1, int i2, int i3, float2 w1, float2 w2, float2 w3){
;   float2 a0=Z[i0], a1=Z[i1], a2=Z[i2], a3=Z[i3];
;   if (INV && !NOTW){ a1=cmulc(a1,w1); a2=cmulc(a2,w2); a3=cmulc(a3,w3); }
;   float2 s02=make_float2(a0.x+a2.x,a0.y+a2.y), d02=make_float2(a0.x-a2.x,a0.y-a2.y);
;   float2 s13=make_float2(a1.x+a3.x,a1.y+a3.y), d13=make_float2(a1.x-a3.x,a1.y-a3.y);
;   float2 y0=make_float2(s02.x+s13.x,s02.y+s13.y), y2=make_float2(s02.x-s13.x,s02.y-s13.y);
;   float2 ym=make_float2(d02.x+d13.y,d02.y-d13.x);
;   float2 yp=make_float2(d02.x-d13.y,d02.y+d13.x);
;   float2 y1, y3;
;   if (INV){ y1=yp; y3=ym; } else if (NOTW){ y1=ym; y3=yp; } else { y1=cmul(ym,w1); y2=cmul(y2,w2); y3=cmul(yp,w3); }
;   Z[i0]=y0; Z[i1]=y1; Z[i2]=y2; Z[i3]=y3;
; }
; __device__ __forceinline__ void fft_inv_tail(float2* Z, const float2* twA, const float2* twB, int tid){
;   fft_pass<true,2,false>(Z,twA,twB,tid); fft_pass<true,4,false>(Z,twA,twB,tid); fft_pass<true,6>(Z,twA,twB,tid);
;   fft_pass<true,8>(Z,twA,twB,tid); fft_pass<true,10>(Z,twA,twB,tid);
; }
	v_pk_mul_f32 v[250:251], v[20:21], v[238:239] op_sel:[1,1] op_sel_hi:[0,1]
	v_pk_fma_f32 v[20:21], v[20:21], v[238:239], v[250:251] op_sel:[0,0,0] op_sel_hi:[1,0,1] neg_hi:[0,0,1]
	v_pk_mul_f32 v[250:251], v[18:19], v[236:237] op_sel:[1,1] op_sel_hi:[0,1]
	v_pk_fma_f32 v[18:19], v[18:19], v[236:237], v[250:251] op_sel:[0,0,0] op_sel_hi:[1,0,1] neg_hi:[0,0,1]
	v_pk_mul_f32 v[250:251], v[22:23], v[240:241] op_sel:[1,1] op_sel_hi:[0,1]
	v_pk_fma_f32 v[22:23], v[22:23], v[240:241], v[250:251] op_sel:[0,0,0] op_sel_hi:[1,0,1] neg_hi:[0,0,1]
	v_pk_add_f32 v[242:243], v[16:17], v[20:21]
	v_pk_add_f32 v[244:245], v[16:17], v[20:21] neg_lo:[0,1] neg_hi:[0,1]
	v_pk_add_f32 v[246:247], v[18:19], v[22:23]
	v_pk_add_f32 v[248:249], v[18:19], v[22:23] neg_lo:[0,1] neg_hi:[0,1]
	v_pk_add_f32 v[16:17], v[242:243], v[246:247]
	v_pk_add_f32 v[18:19], v[244:245], v[248:249] op_sel:[0,1] op_sel_hi:[1,0] neg_lo:[0,1]
	v_pk_add_f32 v[20:21], v[242:243], v[246:247] neg_lo:[0,1] neg_hi:[0,1]
	v_pk_add_f32 v[22:23], v[244:245], v[248:249] op_sel:[0,1] op_sel_hi:[1,0] neg_hi:[0,1]
	s_waitcnt lgkmcnt(0)
	v_pk_mul_f32 v[250:251], v[28:29], v[238:239] op_sel:[1,1] op_sel_hi:[0,1]
	v_pk_fma_f32 v[28:29], v[28:29], v[238:239], v[250:251] op_sel:[0,0,0] op_sel_hi:[1,0,1] neg_hi:[0,0,1]
	v_pk_mul_f32 v[250:251], v[26:27], v[236:237] op_sel:[1,1] op_sel_hi:[0,1]
	v_pk_fma_f32 v[26:27], v[26:27], v[236:237], v[250:251] op_sel:[0,0,0] op_sel_hi:[1,0,1] neg_hi:[0,0,1]
	v_pk_mul_f32 v[250:251], v[30:31], v[240:241] op_sel:[1,1] op_sel_hi:[0,1]
	v_pk_fma_f32 v[30:31], v[30:31], v[240:241], v[250:251] op_sel:[0,0,0] op_sel_hi:[1,0,1] neg_hi:[0,0,1]
	v_pk_add_f32 v[242:243], v[24:25], v[28:29]
	v_pk_add_f32 v[244:245], v[24:25], v[28:29] neg_lo:[0,1] neg_hi:[0,1]
	v_pk_add_f32 v[246:247], v[26:27], v[30:31]
	v_pk_add_f32 v[248:249], v[26:27], v[30:31] neg_lo:[0,1] neg_hi:[0,1]
	v_pk_add_f32 v[24:25], v[242:243], v[246:247]
	v_pk_add_f32 v[26:27], v[244:245], v[248:249] op_sel:[0,1] op_sel_hi:[1,0] neg_lo:[0,1]
	v_pk_add_f32 v[28:29], v[242:243], v[246:247] neg_lo:[0,1] neg_hi:[0,1]
	v_pk_add_f32 v[30:31], v[244:245], v[248:249] op_sel:[0,1] op_sel_hi:[1,0] neg_hi:[0,1]
	v_pk_mul_f32 v[250:251], v[16:17], v[82:83] op_sel:[1,1] op_sel_hi:[0,1]
	v_pk_fma_f32 v[16:17], v[16:17], v[82:83], v[250:251] op_sel:[0,0,0] op_sel_hi:[1,0,1] neg_hi:[0,0,1]
	v_pk_mul_f32 v[250:251], v[8:9], v[80:81] op_sel:[1,1] op_sel_hi:[0,1]
	v_pk_fma_f32 v[8:9], v[8:9], v[80:81], v[250:251] op_sel:[0,0,0] op_sel_hi:[1,0,1] neg_hi:[0,0,1]
	v_pk_mul_f32 v[250:251], v[24:25], v[84:85] op_sel:[1,1] op_sel_hi:[0,1]
	v_pk_fma_f32 v[24:25], v[24:25], v[84:85], v[250:251] op_sel:[0,0,0] op_sel_hi:[1,0,1] neg_hi:[0,0,1]
	v_pk_add_f32 v[242:243], v[0:1], v[16:17]
	v_pk_add_f32 v[244:245], v[0:1], v[16:17] neg_lo:[0,1] neg_hi:[0,1]
	v_pk_add_f32 v[246:247], v[8:9], v[24:25]
	v_pk_add_f32 v[248:249], v[8:9], v[24:25] neg_lo:[0,1] neg_hi:[0,1]
	v_pk_add_f32 v[0:1], v[242:243], v[246:247]
	ds_write_b64 v227, v[0:1] offset:0
	v_pk_add_f32 v[8:9], v[244:245], v[248:249] op_sel:[0,1] op_sel_hi:[1,0] neg_lo:[0,1]
	ds_write_b64 v227, v[8:9] offset:512
	v_pk_add_f32 v[16:17], v[242:243], v[246:247] neg_lo:[0,1] neg_hi:[0,1]
	ds_write_b64 v227, v[16:17] offset:1024
	v_pk_add_f32 v[24:25], v[244:245], v[248:249] op_sel:[0,1] op_sel_hi:[1,0] neg_hi:[0,1]
	ds_write_b64 v227, v[24:25] offset:1536
	v_pk_mul_f32 v[250:251], v[18:19], v[224:225] op_sel:[1,1] op_sel_hi:[1,0] neg_lo:[0,0] neg_hi:[0,0]
	v_pk_fma_f32 v[18:19], v[18:19], v[224:225], v[250:251] op_sel:[0,0,0] op_sel_hi:[0,1,1] neg_lo:[0,0,1] neg_hi:[0,0,0]
	v_pk_mul_f32 v[250:251], v[18:19], v[82:83] op_sel:[1,1] op_sel_hi:[0,1]
	v_pk_fma_f32 v[18:19], v[18:19], v[82:83], v[250:251] op_sel:[0,0,0] op_sel_hi:[1,0,1] neg_hi:[0,0,1]
	v_pk_mul_f32 v[250:251], v[10:11], v[222:223] op_sel:[1,1] op_sel_hi:[1,0] neg_lo:[0,0] neg_hi:[0,0]
	v_pk_fma_f32 v[10:11], v[10:11], v[222:223], v[250:251] op_sel:[0,0,0] op_sel_hi:[0,1,1] neg_lo:[0,0,1] neg_hi:[0,0,0]
	v_pk_mul_f32 v[250:251], v[10:11], v[80:81] op_sel:[1,1] op_sel_hi:[0,1]
	v_pk_fma_f32 v[10:11], v[10:11], v[80:81], v[250:251] op_sel:[0,0,0] op_sel_hi:[1,0,1] neg_hi:[0,0,1]
	v_pk_mul_f32 v[250:251], v[26:27], v[222:223] op_sel:[1,0] op_sel_hi:[1,1] neg_lo:[0,0] neg_hi:[0,0]
	v_pk_fma_f32 v[26:27], v[26:27], v[222:223], v[250:251] op_sel:[0,1,0] op_sel_hi:[0,0,1] neg_lo:[0,0,1] neg_hi:[0,0,0]
	v_pk_mul_f32 v[250:251], v[26:27], v[84:85] op_sel:[1,1] op_sel_hi:[0,1]
	v_pk_fma_f32 v[26:27], v[26:27], v[84:85], v[250:251] op_sel:[0,0,0] op_sel_hi:[1,0,1] neg_hi:[0,0,1]
	v_pk_add_f32 v[242:243], v[2:3], v[18:19]
	v_pk_add_f32 v[244:245], v[2:3], v[18:19] neg_lo:[0,1] neg_hi:[0,1]
	v_pk_add_f32 v[246:247], v[10:11], v[26:27]
	v_pk_add_f32 v[248:249], v[10:11], v[26:27] neg_lo:[0,1] neg_hi:[0,1]
	v_pk_add_f32 v[2:3], v[242:243], v[246:247]
	ds_write_b64 v227, v[2:3] offset:128
	v_pk_add_f32 v[10:11], v[244:245], v[248:249] op_sel:[0,1] op_sel_hi:[1,0] neg_lo:[0,1]
	ds_write_b64 v227, v[10:11] offset:640
	v_pk_add_f32 v[18:19], v[242:243], v[246:247] neg_lo:[0,1] neg_hi:[0,1]
	ds_write_b64 v227, v[18:19] offset:1152
	v_pk_add_f32 v[26:27], v[244:245], v[248:249] op_sel:[0,1] op_sel_hi:[1,0] neg_hi:[0,1]
	ds_write_b64 v227, v[26:27] offset:1664
	v_pk_add_f32 v[20:21], v[20:21], 0 op_sel:[1,0] op_sel_hi:[0,0] neg_lo:[1,0]
	v_pk_mul_f32 v[250:251], v[20:21], v[82:83] op_sel:[1,1] op_sel_hi:[0,1]
	v_pk_fma_f32 v[20:21], v[20:21], v[82:83], v[250:251] op_sel:[0,0,0] op_sel_hi:[1,0,1] neg_hi:[0,0,1]
	v_pk_mul_f32 v[250:251], v[12:13], v[224:225] op_sel:[1,1] op_sel_hi:[1,0] neg_lo:[0,0] neg_hi:[0,0]
; HD float2 cmul(float2 a, float2 b){ return make_float2(a.x*b.x - a.y*b.y, a.x*b.y + a.y*b.x); }
; HD float2 cmulc(float2 a, float2 b){ return make_float2(a.x*b.x + a.y*b.y, a.y*b.x - a.x*b.y); }
; template<bool INV, bool NOTW>
; HD void bf4c(float2* Z, int i0, int i1, int i2, int i3, float2 w1, float2 w2, float2 w3){
;   float2 a0=Z[i0], a1=Z[i1], a2=Z[i2], a3=Z[i3];
;   if (INV && !NOTW){ a1=cmulc(a1,w1); a2=cmulc(a2,w2); a3=cmulc(a3,w3); }
;   float2 s02=make_float2(a0.x+a2.x,a0.y+a2.y), d02=make_float2(a0.x-a2.x,a0.y-a2.y);
;   float2 s13=make_float2(a1.x+a3.x,a1.y+a3.y), d13=make_float2(a1.x-a3.x,a1.y-a3.y);
;   float2 y0=make_float2(s02.x+s13.x,s02.y+s13.y), y2=make_float2(s02.x-s13.x,s02.y-s13.y);
;   float2 ym=make_float2(d02.x+d13.y,d02.y-d13.x);
;   float2 yp=make_float2(d02.x-d13.y,d02.y+d13.x);
;   float2 y1, y3;
;   if (INV){ y1=yp; y3=ym; } else if (NOTW){ y1=ym; y3=yp; } else { y1=cmul(ym,w1); y2=cmul(y2,w2); y3=cmul(yp,w3); }
;   Z[i0]=y0; Z[i1]=y1; Z[i2]=y2; Z[i3]=y3;
; }
; template<bool INV, int LQ, bool BARRIER=true>
; HD void fft_pass(float2* Z, const float2* twA, const float2* twB, int tid){
;     ...
;   } else if (LQ==10){
;     _Pragma("unroll") for (int e=0;e<2;++e){ int j=tid+512*e; int k=j*tws;
;       float2 w1=cmul(twA[k>>6],twB[k&63]), w2=cmul(w1,w1), w3=cmul(w2,w1);
;       _Pragma("unroll") for (int ip=0;ip<4;++ip){ int base=ip*4096+j; bf4c<INV,false>(Z,base,base+q,base+2*q,base+3*q,w1,w2,w3); } }
;   } else {
;     int j=tid&(q-1); int base0=((tid>>LQ)<<(LQ+2))+j;
;     float2 w1=make_float2(1.f,0.f), w2=w1, w3=w1;
;     if (LQ>0){ int k=j*tws; w1=cmul(twA[k>>6],twB[k&63]); w2=cmul(w1,w1); w3=cmul(w2,w1); }
;     _Pragma("unroll") for (int i=0;i<8;++i){ int base=base0+i*2048; bf4c<INV,(LQ==0)>(Z,base,base+q,base+2*q,base+3*q,w1,w2,w3); }
;   }
;   if (BARRIER) __syncthreads(); else asm volatile("s_waitcnt lgkmcnt(0)" ::: "memory");
	v_pk_fma_f32 v[12:13], v[12:13], v[224:225], v[250:251] op_sel:[0,0,0] op_sel_hi:[0,1,1] neg_lo:[0,0,1] neg_hi:[0,0,0]
	v_pk_mul_f32 v[250:251], v[12:13], v[80:81] op_sel:[1,1] op_sel_hi:[0,1]
	v_pk_fma_f32 v[12:13], v[12:13], v[80:81], v[250:251] op_sel:[0,0,0] op_sel_hi:[1,0,1] neg_hi:[0,0,1]
	v_pk_mul_f32 v[250:251], v[28:29], v[224:225] op_sel:[1,1] op_sel_hi:[1,0] neg_lo:[0,0] neg_hi:[0,1]
	v_pk_fma_f32 v[28:29], v[28:29], v[224:225], v[250:251] op_sel:[0,0,0] op_sel_hi:[0,1,1] neg_lo:[0,1,1] neg_hi:[0,0,0]
	v_pk_mul_f32 v[250:251], v[28:29], v[84:85] op_sel:[1,1] op_sel_hi:[0,1]
	v_pk_fma_f32 v[28:29], v[28:29], v[84:85], v[250:251] op_sel:[0,0,0] op_sel_hi:[1,0,1] neg_hi:[0,0,1]
	v_pk_add_f32 v[242:243], v[4:5], v[20:21]
	v_pk_add_f32 v[244:245], v[4:5], v[20:21] neg_lo:[0,1] neg_hi:[0,1]
	v_pk_add_f32 v[246:247], v[12:13], v[28:29]
	v_pk_add_f32 v[248:249], v[12:13], v[28:29] neg_lo:[0,1] neg_hi:[0,1]
	v_pk_add_f32 v[4:5], v[242:243], v[246:247]
	ds_write_b64 v227, v[4:5] offset:256
	v_pk_add_f32 v[12:13], v[244:245], v[248:249] op_sel:[0,1] op_sel_hi:[1,0] neg_lo:[0,1]
	ds_write_b64 v227, v[12:13] offset:768
	v_pk_add_f32 v[20:21], v[242:243], v[246:247] neg_lo:[0,1] neg_hi:[0,1]
	ds_write_b64 v227, v[20:21] offset:1280
	v_pk_add_f32 v[28:29], v[244:245], v[248:249] op_sel:[0,1] op_sel_hi:[1,0] neg_hi:[0,1]
	ds_write_b64 v227, v[28:29] offset:1792
	v_pk_mul_f32 v[250:251], v[22:23], v[224:225] op_sel:[1,1] op_sel_hi:[1,0] neg_lo:[0,0] neg_hi:[0,1]
	v_pk_fma_f32 v[22:23], v[22:23], v[224:225], v[250:251] op_sel:[0,0,0] op_sel_hi:[0,1,1] neg_lo:[0,1,1] neg_hi:[0,0,0]
	v_pk_mul_f32 v[250:251], v[22:23], v[82:83] op_sel:[1,1] op_sel_hi:[0,1]
	v_pk_fma_f32 v[22:23], v[22:23], v[82:83], v[250:251] op_sel:[0,0,0] op_sel_hi:[1,0,1] neg_hi:[0,0,1]
	v_pk_mul_f32 v[250:251], v[14:15], v[222:223] op_sel:[1,0] op_sel_hi:[1,1] neg_lo:[0,0] neg_hi:[0,0]
	v_pk_fma_f32 v[14:15], v[14:15], v[222:223], v[250:251] op_sel:[0,1,0] op_sel_hi:[0,0,1] neg_lo:[0,0,1] neg_hi:[0,0,0]
	v_pk_mul_f32 v[250:251], v[14:15], v[80:81] op_sel:[1,1] op_sel_hi:[0,1]
	v_pk_fma_f32 v[14:15], v[14:15], v[80:81], v[250:251] op_sel:[0,0,0] op_sel_hi:[1,0,1] neg_hi:[0,0,1]
	v_pk_mul_f32 v[250:251], v[30:31], v[222:223] op_sel:[1,1] op_sel_hi:[1,0] neg_lo:[0,1] neg_hi:[0,1]
	v_pk_fma_f32 v[30:31], v[30:31], v[222:223], v[250:251] op_sel:[0,0,0] op_sel_hi:[0,1,1] neg_lo:[0,1,1] neg_hi:[0,1,0]
	v_pk_mul_f32 v[250:251], v[30:31], v[84:85] op_sel:[1,1] op_sel_hi:[0,1]
	v_pk_fma_f32 v[30:31], v[30:31], v[84:85], v[250:251] op_sel:[0,0,0] op_sel_hi:[1,0,1] neg_hi:[0,0,1]
	v_pk_add_f32 v[242:243], v[6:7], v[22:23]
	v_pk_add_f32 v[244:245], v[6:7], v[22:23] neg_lo:[0,1] neg_hi:[0,1]
	v_pk_add_f32 v[246:247], v[14:15], v[30:31]
	v_pk_add_f32 v[248:249], v[14:15], v[30:31] neg_lo:[0,1] neg_hi:[0,1]
	v_pk_add_f32 v[6:7], v[242:243], v[246:247]
	ds_write_b64 v227, v[6:7] offset:384
	v_pk_add_f32 v[14:15], v[244:245], v[248:249] op_sel:[0,1] op_sel_hi:[1,0] neg_lo:[0,1]
	ds_write_b64 v227, v[14:15] offset:896
	v_pk_add_f32 v[22:23], v[242:243], v[246:247] neg_lo:[0,1] neg_hi:[0,1]
	ds_write_b64 v227, v[22:23] offset:1408
	v_pk_add_f32 v[30:31], v[244:245], v[248:249] op_sel:[0,1] op_sel_hi:[1,0] neg_hi:[0,1]
	ds_write_b64 v227, v[30:31] offset:1920
	s_waitcnt lgkmcnt(0)
	s_barrier
	v_and_b32_e32 v8, 255, v154
	v_lshrrev_b32_e32 v9, 4, v8
	v_lshlrev_b32_e32 v9, 3, v9
	v_add_u32_e32 v9, 0x20800, v9
	v_and_b32_e32 v10, 15, v8
	v_lshlrev_b32_e32 v10, 5, v10
	v_add_u32_e32 v10, 0x20a00, v10
	ds_read_b64 v[0:1], v9
	ds_read_b64 v[2:3], v10
	s_waitcnt lgkmcnt(0)
	v_pk_mul_f32 v[250:251], v[0:1], v[2:3] op_sel:[1,1] op_sel_hi:[1,0]
	v_pk_fma_f32 v[80:81], v[0:1], v[2:3], v[250:251] op_sel:[0,0,0] op_sel_hi:[0,1,1] neg_lo:[0,0,1]
	v_pk_mul_f32 v[250:251], v[80:81], v[80:81] op_sel:[1,1] op_sel_hi:[1,0]
	v_pk_fma_f32 v[82:83], v[80:81], v[80:81], v[250:251] op_sel:[0,0,0] op_sel_hi:[0,1,1] neg_lo:[0,0,1]
	v_pk_mul_f32 v[250:251], v[82:83], v[80:81] op_sel:[1,1] op_sel_hi:[1,0]
	v_pk_fma_f32 v[84:85], v[82:83], v[80:81], v[250:251] op_sel:[0,0,0] op_sel_hi:[0,1,1] neg_lo:[0,0,1]
	v_lshrrev_b32_e32 v9, 2, v8
	v_lshlrev_b32_e32 v9, 3, v9
	v_add_u32_e32 v9, 0x20800, v9
	v_and_b32_e32 v10, 3, v8
	v_lshlrev_b32_e32 v10, 7, v10
	v_add_u32_e32 v10, 0x20a00, v10
	ds_read_b64 v[0:1], v9
	ds_read_b64 v[2:3], v10
	s_waitcnt lgkmcnt(0)
	v_pk_mul_f32 v[250:251], v[0:1], v[2:3] op_sel:[1,1] op_sel_hi:[1,0]
	v_pk_fma_f32 v[236:237], v[0:1], v[2:3], v[250:251] op_sel:[0,0,0] op_sel_hi:[0,1,1] neg_lo:[0,0,1]
	v_pk_mul_f32 v[250:251], v[236:237], v[236:237] op_sel:[1,1] op_sel_hi:[1,0]
	v_pk_fma_f32 v[238:239], v[236:237], v[236:237], v[250:251] op_sel:[0,0,0] op_sel_hi:[0,1,1] neg_lo:[0,0,1]
	v_pk_mul_f32 v[250:251], v[238:239], v[236:237] op_sel:[1,1] op_sel_hi:[1,0]
	v_pk_fma_f32 v[240:241], v[238:239], v[236:237], v[250:251] op_sel:[0,0,0] op_sel_hi:[0,1,1] neg_lo:[0,0,1]
	v_lshrrev_b32_e32 v226, 8, v154
	v_lshlrev_b32_e32 v226, 12, v226
	v_and_b32_e32 v227, 255, v154
	v_add_u32_e32 v226, v226, v227
	v_lshlrev_b32_e32 v226, 3, v226
	v_add_u32_e32 v227, 0x10000, v226
	ds_read_b64 v[0:1], v226 offset:0
	ds_read_b64 v[2:3], v226 offset:2048
	ds_read_b64 v[4:5], v226 offset:4096
	ds_read_b64 v[6:7], v226 offset:6144
	ds_read_b64 v[8:9], v226 offset:8192
	ds_read_b64 v[10:11], v226 offset:10240
	ds_read_b64 v[12:13], v226 offset:12288
	ds_read_b64 v[14:15], v226 offset:14336
	ds_read_b64 v[16:17], v226 offset:16384
	ds_read_b64 v[18:19], v226 offset:18432
	ds_read_b64 v[20:21], v226 offset:20480
	ds_read_b64 v[22:23], v226 offset:22528
	ds_read_b64 v[24:25], v226 offset:24576
	ds_read_b64 v[26:27], v226 offset:26624
	ds_read_b64 v[28:29], v226 offset:28672
	ds_read_b64 v[30:31], v226 offset:30720
	s_waitcnt lgkmcnt(12)
; HD float2 cmul(float2 a, float2 b){ return make_float2(a.x*b.x - a.y*b.y, a.x*b.y + a.y*b.x); }
; HD float2 cmulc(float2 a, float2 b){ return make_float2(a.x*b.x + a.y*b.y, a.y*b.x - a.x*b.y); }
; template<bool INV, bool NOTW>
; HD void bf4c(float2* Z, int i0, int i1, int i2, int i3, float2 w1, float2 w2, float2 w3){
;   float2 a0=Z[i0], a1=Z[i1], a2=Z[i2], a3=Z[i3];
;   if (INV && !NOTW){ a1=cmulc(a1,w1); a2=cmulc(a2,w2); a3=cmulc(a3,w3); }
;   float2 s02=make_float2(a0.x+a2.x,a0.y+a2.y), d02=make_float2(a0.x-a2.x,a0.y-a2.y);
;   float2 s13=make_float2(a1.x+a3.x,a1.y+a3.y), d13=make_float2(a1.x-a3.x,a1.y-a3.y);
;   float2 y0=make_float2(s02.x+s13.x,s02.y+s13.y), y2=make_float2(s02.x-s13.x,s02.y-s13.y);
;   float2 ym=make_float2(d02.x+d13.y,d02.y-d13.x);
;   float2 yp=make_float2(d02.x-d13.y,d02.y+d13.x);
;   float2 y1, y3;
;   if (INV){ y1=yp; y3=ym; } else if (NOTW){ y1=ym; y3=yp; } else { y1=cmul(ym,w1); y2=cmul(y2,w2); y3=cmul(yp,w3); }
;   Z[i0]=y0; Z[i1]=y1; Z[i2]=y2; Z[i3]=y3;
; }
; __device__ __forceinline__ void fft_inv_tail(float2* Z, const float2* twA, const float2* twB, int tid){
;   fft_pass<true,2,false>(Z,twA,twB,tid); fft_pass<true,4,false>(Z,twA,twB,tid); fft_pass<true,6>(Z,twA,twB,tid);
;   fft_pass<true,8>(Z,twA,twB,tid); fft_pass<true,10>(Z,twA,twB,tid);
; }
	v_pk_mul_f32 v[250:251], v[4:5], v[238:239] op_sel:[1,1] op_sel_hi:[0,1]
	v_pk_fma_f32 v[4:5], v[4:5], v[238:239], v[250:251] op_sel:[0,0,0] op_sel_hi:[1,0,1] neg_hi:[0,0,1]
	v_pk_mul_f32 v[250:251], v[2:3], v[236:237] op_sel:[1,1] op_sel_hi:[0,1]
	v_pk_fma_f32 v[2:3], v[2:3], v[236:237], v[250:251] op_sel:[0,0,0] op_sel_hi:[1,0,1] neg_hi:[0,0,1]
	v_pk_mul_f32 v[250:251], v[6:7], v[240:241] op_sel:[1,1] op_sel_hi:[0,1]
	v_pk_fma_f32 v[6:7], v[6:7], v[240:241], v[250:251] op_sel:[0,0,0] op_sel_hi:[1,0,1] neg_hi:[0,0,1]
	v_pk_add_f32 v[242:243], v[0:1], v[4:5]
	v_pk_add_f32 v[244:245], v[0:1], v[4:5] neg_lo:[0,1] neg_hi:[0,1]
	v_pk_add_f32 v[246:247], v[2:3], v[6:7]
	v_pk_add_f32 v[248:249], v[2:3], v[6:7] neg_lo:[0,1] neg_hi:[0,1]
	v_pk_add_f32 v[0:1], v[242:243], v[246:247]
	v_pk_add_f32 v[2:3], v[244:245], v[248:249] op_sel:[0,1] op_sel_hi:[1,0] neg_lo:[0,1]
	v_pk_add_f32 v[4:5], v[242:243], v[246:247] neg_lo:[0,1] neg_hi:[0,1]
	v_pk_add_f32 v[6:7], v[244:245], v[248:249] op_sel:[0,1] op_sel_hi:[1,0] neg_hi:[0,1]
	s_waitcnt lgkmcnt(8)
	v_pk_mul_f32 v[250:251], v[12:13], v[238:239] op_sel:[1,1] op_sel_hi:[0,1]
	v_pk_fma_f32 v[12:13], v[12:13], v[238:239], v[250:251] op_sel:[0,0,0] op_sel_hi:[1,0,1] neg_hi:[0,0,1]
	v_pk_mul_f32 v[250:251], v[10:11], v[236:237] op_sel:[1,1] op_sel_hi:[0,1]
	v_pk_fma_f32 v[10:11], v[10:11], v[236:237], v[250:251] op_sel:[0,0,0] op_sel_hi:[1,0,1] neg_hi:[0,0,1]
	v_pk_mul_f32 v[250:251], v[14:15], v[240:241] op_sel:[1,1] op_sel_hi:[0,1]
	v_pk_fma_f32 v[14:15], v[14:15], v[240:241], v[250:251] op_sel:[0,0,0] op_sel_hi:[1,0,1] neg_hi:[0,0,1]
	v_pk_add_f32 v[242:243], v[8:9], v[12:13]
	v_pk_add_f32 v[244:245], v[8:9], v[12:13] neg_lo:[0,1] neg_hi:[0,1]
	v_pk_add_f32 v[246:247], v[10:11], v[14:15]
	v_pk_add_f32 v[248:249], v[10:11], v[14:15] neg_lo:[0,1] neg_hi:[0,1]
	v_pk_add_f32 v[8:9], v[242:243], v[246:247]
	v_pk_add_f32 v[10:11], v[244:245], v[248:249] op_sel:[0,1] op_sel_hi:[1,0] neg_lo:[0,1]
	v_pk_add_f32 v[12:13], v[242:243], v[246:247] neg_lo:[0,1] neg_hi:[0,1]
	v_pk_add_f32 v[14:15], v[244:245], v[248:249] op_sel:[0,1] op_sel_hi:[1,0] neg_hi:[0,1]
	s_waitcnt lgkmcnt(4)
	v_pk_mul_f32 v[250:251], v[20:21], v[238:239] op_sel:[1,1] op_sel_hi:[0,1]
	v_pk_fma_f32 v[20:21], v[20:21], v[238:239], v[250:251] op_sel:[0,0,0] op_sel_hi:[1,0,1] neg_hi:[0,0,1]
	v_pk_mul_f32 v[250:251], v[18:19], v[236:237] op_sel:[1,1] op_sel_hi:[0,1]
	v_pk_fma_f32 v[18:19], v[18:19], v[236:237], v[250:251] op_sel:[0,0,0] op_sel_hi:[1,0,1] neg_hi:[0,0,1]
	v_pk_mul_f32 v[250:251], v[22:23], v[240:241] op_sel:[1,1] op_sel_hi:[0,1]
	v_pk_fma_f32 v[22:23], v[22:23], v[240:241], v[250:251] op_sel:[0,0,0] op_sel_hi:[1,0,1] neg_hi:[0,0,1]
	v_pk_add_f32 v[242:243], v[16:17], v[20:21]
	v_pk_add_f32 v[244:245], v[16:17], v[20:21] neg_lo:[0,1] neg_hi:[0,1]
	v_pk_add_f32 v[246:247], v[18:19], v[22:23]
	v_pk_add_f32 v[248:249], v[18:19], v[22:23] neg_lo:[0,1] neg_hi:[0,1]
	v_pk_add_f32 v[16:17], v[242:243], v[246:247]
	v_pk_add_f32 v[18:19], v[244:245], v[248:249] op_sel:[0,1] op_sel_hi:[1,0] neg_lo:[0,1]
	v_pk_add_f32 v[20:21], v[242:243], v[246:247] neg_lo:[0,1] neg_hi:[0,1]
	v_pk_add_f32 v[22:23], v[244:245], v[248:249] op_sel:[0,1] op_sel_hi:[1,0] neg_hi:[0,1]
	s_waitcnt lgkmcnt(0)
	v_pk_mul_f32 v[250:251], v[28:29], v[238:239] op_sel:[1,1] op_sel_hi:[0,1]
	v_pk_fma_f32 v[28:29], v[28:29], v[238:239], v[250:251] op_sel:[0,0,0] op_sel_hi:[1,0,1] neg_hi:[0,0,1]
	v_pk_mul_f32 v[250:251], v[26:27], v[236:237] op_sel:[1,1] op_sel_hi:[0,1]
	v_pk_fma_f32 v[26:27], v[26:27], v[236:237], v[250:251] op_sel:[0,0,0] op_sel_hi:[1,0,1] neg_hi:[0,0,1]
	v_pk_mul_f32 v[250:251], v[30:31], v[240:241] op_sel:[1,1] op_sel_hi:[0,1]
	v_pk_fma_f32 v[30:31], v[30:31], v[240:241], v[250:251] op_sel:[0,0,0] op_sel_hi:[1,0,1] neg_hi:[0,0,1]
	v_pk_add_f32 v[242:243], v[24:25], v[28:29]
	v_pk_add_f32 v[244:245], v[24:25], v[28:29] neg_lo:[0,1] neg_hi:[0,1]
	v_pk_add_f32 v[246:247], v[26:27], v[30:31]
	v_pk_add_f32 v[248:249], v[26:27], v[30:31] neg_lo:[0,1] neg_hi:[0,1]
	v_pk_add_f32 v[24:25], v[242:243], v[246:247]
	v_pk_add_f32 v[26:27], v[244:245], v[248:249] op_sel:[0,1] op_sel_hi:[1,0] neg_lo:[0,1]
	v_pk_add_f32 v[28:29], v[242:243], v[246:247] neg_lo:[0,1] neg_hi:[0,1]
	v_pk_add_f32 v[30:31], v[244:245], v[248:249] op_sel:[0,1] op_sel_hi:[1,0] neg_hi:[0,1]
	v_pk_mul_f32 v[250:251], v[16:17], v[82:83] op_sel:[1,1] op_sel_hi:[0,1]
	v_pk_fma_f32 v[16:17], v[16:17], v[82:83], v[250:251] op_sel:[0,0,0] op_sel_hi:[1,0,1] neg_hi:[0,0,1]
	v_pk_mul_f32 v[250:251], v[8:9], v[80:81] op_sel:[1,1] op_sel_hi:[0,1]
	v_pk_fma_f32 v[8:9], v[8:9], v[80:81], v[250:251] op_sel:[0,0,0] op_sel_hi:[1,0,1] neg_hi:[0,0,1]
	v_pk_mul_f32 v[250:251], v[24:25], v[84:85] op_sel:[1,1] op_sel_hi:[0,1]
	v_pk_fma_f32 v[24:25], v[24:25], v[84:85], v[250:251] op_sel:[0,0,0] op_sel_hi:[1,0,1] neg_hi:[0,0,1]
	v_pk_add_f32 v[242:243], v[0:1], v[16:17]
	v_pk_add_f32 v[244:245], v[0:1], v[16:17] neg_lo:[0,1] neg_hi:[0,1]
	v_pk_add_f32 v[246:247], v[8:9], v[24:25]
	v_pk_add_f32 v[248:249], v[8:9], v[24:25] neg_lo:[0,1] neg_hi:[0,1]
	v_pk_add_f32 v[0:1], v[242:243], v[246:247]
	ds_write_b64 v226, v[0:1] offset:0
	v_pk_add_f32 v[8:9], v[244:245], v[248:249] op_sel:[0,1] op_sel_hi:[1,0] neg_lo:[0,1]
	ds_write_b64 v226, v[8:9] offset:8192
	v_pk_add_f32 v[16:17], v[242:243], v[246:247] neg_lo:[0,1] neg_hi:[0,1]
	ds_write_b64 v226, v[16:17] offset:16384
	v_pk_add_f32 v[24:25], v[244:245], v[248:249] op_sel:[0,1] op_sel_hi:[1,0] neg_hi:[0,1]
	ds_write_b64 v226, v[24:25] offset:24576
	v_pk_mul_f32 v[250:251], v[18:19], v[224:225] op_sel:[1,1] op_sel_hi:[1,0] neg_lo:[0,0] neg_hi:[0,0]
; HD float2 cmul(float2 a, float2 b){ return make_float2(a.x*b.x - a.y*b.y, a.x*b.y + a.y*b.x); }
; HD float2 cmulc(float2 a, float2 b){ return make_float2(a.x*b.x + a.y*b.y, a.y*b.x - a.x*b.y); }
; template<bool INV, bool NOTW>
; HD void bf4c(float2* Z, int i0, int i1, int i2, int i3, float2 w1, float2 w2, float2 w3){
;   float2 a0=Z[i0], a1=Z[i1], a2=Z[i2], a3=Z[i3];
;   if (INV && !NOTW){ a1=cmulc(a1,w1); a2=cmulc(a2,w2); a3=cmulc(a3,w3); }
;   float2 s02=make_float2(a0.x+a2.x,a0.y+a2.y), d02=make_float2(a0.x-a2.x,a0.y-a2.y);
;   float2 s13=make_float2(a1.x+a3.x,a1.y+a3.y), d13=make_float2(a1.x-a3.x,a1.y-a3.y);
;   float2 y0=make_float2(s02.x+s13.x,s02.y+s13.y), y2=make_float2(s02.x-s13.x,s02.y-s13.y);
;   float2 ym=make_float2(d02.x+d13.y,d02.y-d13.x);
;   float2 yp=make_float2(d02.x-d13.y,d02.y+d13.x);
;   float2 y1, y3;
;   if (INV){ y1=yp; y3=ym; } else if (NOTW){ y1=ym; y3=yp; } else { y1=cmul(ym,w1); y2=cmul(y2,w2); y3=cmul(yp,w3); }
;   Z[i0]=y0; Z[i1]=y1; Z[i2]=y2; Z[i3]=y3;
; }
; __device__ __forceinline__ void fft_inv_tail(float2* Z, const float2* twA, const float2* twB, int tid){
;   fft_pass<true,2,false>(Z,twA,twB,tid); fft_pass<true,4,false>(Z,twA,twB,tid); fft_pass<true,6>(Z,twA,twB,tid);
;   fft_pass<true,8>(Z,twA,twB,tid); fft_pass<true,10>(Z,twA,twB,tid);
; }
	v_pk_fma_f32 v[18:19], v[18:19], v[224:225], v[250:251] op_sel:[0,0,0] op_sel_hi:[0,1,1] neg_lo:[0,0,1] neg_hi:[0,0,0]
	v_pk_mul_f32 v[250:251], v[18:19], v[82:83] op_sel:[1,1] op_sel_hi:[0,1]
	v_pk_fma_f32 v[18:19], v[18:19], v[82:83], v[250:251] op_sel:[0,0,0] op_sel_hi:[1,0,1] neg_hi:[0,0,1]
	v_pk_mul_f32 v[250:251], v[10:11], v[222:223] op_sel:[1,1] op_sel_hi:[1,0] neg_lo:[0,0] neg_hi:[0,0]
	v_pk_fma_f32 v[10:11], v[10:11], v[222:223], v[250:251] op_sel:[0,0,0] op_sel_hi:[0,1,1] neg_lo:[0,0,1] neg_hi:[0,0,0]
	v_pk_mul_f32 v[250:251], v[10:11], v[80:81] op_sel:[1,1] op_sel_hi:[0,1]
	v_pk_fma_f32 v[10:11], v[10:11], v[80:81], v[250:251] op_sel:[0,0,0] op_sel_hi:[1,0,1] neg_hi:[0,0,1]
	v_pk_mul_f32 v[250:251], v[26:27], v[222:223] op_sel:[1,0] op_sel_hi:[1,1] neg_lo:[0,0] neg_hi:[0,0]
	v_pk_fma_f32 v[26:27], v[26:27], v[222:223], v[250:251] op_sel:[0,1,0] op_sel_hi:[0,0,1] neg_lo:[0,0,1] neg_hi:[0,0,0]
	v_pk_mul_f32 v[250:251], v[26:27], v[84:85] op_sel:[1,1] op_sel_hi:[0,1]
	v_pk_fma_f32 v[26:27], v[26:27], v[84:85], v[250:251] op_sel:[0,0,0] op_sel_hi:[1,0,1] neg_hi:[0,0,1]
	v_pk_add_f32 v[242:243], v[2:3], v[18:19]
	v_pk_add_f32 v[244:245], v[2:3], v[18:19] neg_lo:[0,1] neg_hi:[0,1]
	v_pk_add_f32 v[246:247], v[10:11], v[26:27]
	v_pk_add_f32 v[248:249], v[10:11], v[26:27] neg_lo:[0,1] neg_hi:[0,1]
	v_pk_add_f32 v[2:3], v[242:243], v[246:247]
	ds_write_b64 v226, v[2:3] offset:2048
	v_pk_add_f32 v[10:11], v[244:245], v[248:249] op_sel:[0,1] op_sel_hi:[1,0] neg_lo:[0,1]
	ds_write_b64 v226, v[10:11] offset:10240
	v_pk_add_f32 v[18:19], v[242:243], v[246:247] neg_lo:[0,1] neg_hi:[0,1]
	ds_write_b64 v226, v[18:19] offset:18432
	v_pk_add_f32 v[26:27], v[244:245], v[248:249] op_sel:[0,1] op_sel_hi:[1,0] neg_hi:[0,1]
	ds_write_b64 v226, v[26:27] offset:26624
	v_pk_add_f32 v[20:21], v[20:21], 0 op_sel:[1,0] op_sel_hi:[0,0] neg_lo:[1,0]
	v_pk_mul_f32 v[250:251], v[20:21], v[82:83] op_sel:[1,1] op_sel_hi:[0,1]
	v_pk_fma_f32 v[20:21], v[20:21], v[82:83], v[250:251] op_sel:[0,0,0] op_sel_hi:[1,0,1] neg_hi:[0,0,1]
	v_pk_mul_f32 v[250:251], v[12:13], v[224:225] op_sel:[1,1] op_sel_hi:[1,0] neg_lo:[0,0] neg_hi:[0,0]
	v_pk_fma_f32 v[12:13], v[12:13], v[224:225], v[250:251] op_sel:[0,0,0] op_sel_hi:[0,1,1] neg_lo:[0,0,1] neg_hi:[0,0,0]
	v_pk_mul_f32 v[250:251], v[12:13], v[80:81] op_sel:[1,1] op_sel_hi:[0,1]
	v_pk_fma_f32 v[12:13], v[12:13], v[80:81], v[250:251] op_sel:[0,0,0] op_sel_hi:[1,0,1] neg_hi:[0,0,1]
	v_pk_mul_f32 v[250:251], v[28:29], v[224:225] op_sel:[1,1] op_sel_hi:[1,0] neg_lo:[0,0] neg_hi:[0,1]
	v_pk_fma_f32 v[28:29], v[28:29], v[224:225], v[250:251] op_sel:[0,0,0] op_sel_hi:[0,1,1] neg_lo:[0,1,1] neg_hi:[0,0,0]
	v_pk_mul_f32 v[250:251], v[28:29], v[84:85] op_sel:[1,1] op_sel_hi:[0,1]
	v_pk_fma_f32 v[28:29], v[28:29], v[84:85], v[250:251] op_sel:[0,0,0] op_sel_hi:[1,0,1] neg_hi:[0,0,1]
	v_pk_add_f32 v[242:243], v[4:5], v[20:21]
	v_pk_add_f32 v[244:245], v[4:5], v[20:21] neg_lo:[0,1] neg_hi:[0,1]
	v_pk_add_f32 v[246:247], v[12:13], v[28:29]
	v_pk_add_f32 v[248:249], v[12:13], v[28:29] neg_lo:[0,1] neg_hi:[0,1]
	v_pk_add_f32 v[4:5], v[242:243], v[246:247]
	ds_write_b64 v226, v[4:5] offset:4096
	v_pk_add_f32 v[12:13], v[244:245], v[248:249] op_sel:[0,1] op_sel_hi:[1,0] neg_lo:[0,1]
	ds_write_b64 v226, v[12:13] offset:12288
	v_pk_add_f32 v[20:21], v[242:243], v[246:247] neg_lo:[0,1] neg_hi:[0,1]
	ds_write_b64 v226, v[20:21] offset:20480
	v_pk_add_f32 v[28:29], v[244:245], v[248:249] op_sel:[0,1] op_sel_hi:[1,0] neg_hi:[0,1]
	ds_write_b64 v226, v[28:29] offset:28672
	v_pk_mul_f32 v[250:251], v[22:23], v[224:225] op_sel:[1,1] op_sel_hi:[1,0] neg_lo:[0,0] neg_hi:[0,1]
	v_pk_fma_f32 v[22:23], v[22:23], v[224:225], v[250:251] op_sel:[0,0,0] op_sel_hi:[0,1,1] neg_lo:[0,1,1] neg_hi:[0,0,0]
	v_pk_mul_f32 v[250:251], v[22:23], v[82:83] op_sel:[1,1] op_sel_hi:[0,1]
	v_pk_fma_f32 v[22:23], v[22:23], v[82:83], v[250:251] op_sel:[0,0,0] op_sel_hi:[1,0,1] neg_hi:[0,0,1]
	v_pk_mul_f32 v[250:251], v[14:15], v[222:223] op_sel:[1,0] op_sel_hi:[1,1] neg_lo:[0,0] neg_hi:[0,0]
	v_pk_fma_f32 v[14:15], v[14:15], v[222:223], v[250:251] op_sel:[0,1,0] op_sel_hi:[0,0,1] neg_lo:[0,0,1] neg_hi:[0,0,0]
	v_pk_mul_f32 v[250:251], v[14:15], v[80:81] op_sel:[1,1] op_sel_hi:[0,1]
	v_pk_fma_f32 v[14:15], v[14:15], v[80:81], v[250:251] op_sel:[0,0,0] op_sel_hi:[1,0,1] neg_hi:[0,0,1]
	v_pk_mul_f32 v[250:251], v[30:31], v[222:223] op_sel:[1,1] op_sel_hi:[1,0] neg_lo:[0,1] neg_hi:[0,1]
	v_pk_fma_f32 v[30:31], v[30:31], v[222:223], v[250:251] op_sel:[0,0,0] op_sel_hi:[0,1,1] neg_lo:[0,1,1] neg_hi:[0,1,0]
	v_pk_mul_f32 v[250:251], v[30:31], v[84:85] op_sel:[1,1] op_sel_hi:[0,1]
	v_pk_fma_f32 v[30:31], v[30:31], v[84:85], v[250:251] op_sel:[0,0,0] op_sel_hi:[1,0,1] neg_hi:[0,0,1]
	v_pk_add_f32 v[242:243], v[6:7], v[22:23]
	v_pk_add_f32 v[244:245], v[6:7], v[22:23] neg_lo:[0,1] neg_hi:[0,1]
	v_pk_add_f32 v[246:247], v[14:15], v[30:31]
	v_pk_add_f32 v[248:249], v[14:15], v[30:31] neg_lo:[0,1] neg_hi:[0,1]
	v_pk_add_f32 v[6:7], v[242:243], v[246:247]
	ds_write_b64 v226, v[6:7] offset:6144
	v_pk_add_f32 v[14:15], v[244:245], v[248:249] op_sel:[0,1] op_sel_hi:[1,0] neg_lo:[0,1]
	ds_write_b64 v226, v[14:15] offset:14336
	v_pk_add_f32 v[22:23], v[242:243], v[246:247] neg_lo:[0,1] neg_hi:[0,1]
	ds_write_b64 v226, v[22:23] offset:22528
	v_pk_add_f32 v[30:31], v[244:245], v[248:249] op_sel:[0,1] op_sel_hi:[1,0] neg_hi:[0,1]
	ds_write_b64 v226, v[30:31] offset:30720
	ds_read_b64 v[0:1], v227 offset:0
	ds_read_b64 v[2:3], v227 offset:2048
	ds_read_b64 v[4:5], v227 offset:4096
	ds_read_b64 v[6:7], v227 offset:6144
	ds_read_b64 v[8:9], v227 offset:8192
	ds_read_b64 v[10:11], v227 offset:10240
	ds_read_b64 v[12:13], v227 offset:12288
	ds_read_b64 v[14:15], v227 offset:14336
	ds_read_b64 v[16:17], v227 offset:16384
	ds_read_b64 v[18:19], v227 offset:18432
	ds_read_b64 v[20:21], v227 offset:20480
	ds_read_b64 v[22:23], v227 offset:22528
	ds_read_b64 v[24:25], v227 offset:24576
	ds_read_b64 v[26:27], v227 offset:26624
	ds_read_b64 v[28:29], v227 offset:28672
	ds_read_b64 v[30:31], v227 offset:30720
	s_waitcnt lgkmcnt(12)
; HD float2 cmul(float2 a, float2 b){ return make_float2(a.x*b.x - a.y*b.y, a.x*b.y + a.y*b.x); }
; HD float2 cmulc(float2 a, float2 b){ return make_float2(a.x*b.x + a.y*b.y, a.y*b.x - a.x*b.y); }
; template<bool INV, bool NOTW>
; HD void bf4c(float2* Z, int i0, int i1, int i2, int i3, float2 w1, float2 w2, float2 w3){
;   float2 a0=Z[i0], a1=Z[i1], a2=Z[i2], a3=Z[i3];
;   if (INV && !NOTW){ a1=cmulc(a1,w1); a2=cmulc(a2,w2); a3=cmulc(a3,w3); }
;   float2 s02=make_float2(a0.x+a2.x,a0.y+a2.y), d02=make_float2(a0.x-a2.x,a0.y-a2.y);
;   float2 s13=make_float2(a1.x+a3.x,a1.y+a3.y), d13=make_float2(a1.x-a3.x,a1.y-a3.y);
;   float2 y0=make_float2(s02.x+s13.x,s02.y+s13.y), y2=make_float2(s02.x-s13.x,s02.y-s13.y);
;   float2 ym=make_float2(d02.x+d13.y,d02.y-d13.x);
;   float2 yp=make_float2(d02.x-d13.y,d02.y+d13.x);
;   float2 y1, y3;
;   if (INV){ y1=yp; y3=ym; } else if (NOTW){ y1=ym; y3=yp; } else { y1=cmul(ym,w1); y2=cmul(y2,w2); y3=cmul(yp,w3); }
;   Z[i0]=y0; Z[i1]=y1; Z[i2]=y2; Z[i3]=y3;
; }
; __device__ __forceinline__ void fft_inv_tail(float2* Z, const float2* twA, const float2* twB, int tid){
;   fft_pass<true,2,false>(Z,twA,twB,tid); fft_pass<true,4,false>(Z,twA,twB,tid); fft_pass<true,6>(Z,twA,twB,tid);
;   fft_pass<true,8>(Z,twA,twB,tid); fft_pass<true,10>(Z,twA,twB,tid);
; }
	v_pk_mul_f32 v[250:251], v[4:5], v[238:239] op_sel:[1,1] op_sel_hi:[0,1]
	v_pk_fma_f32 v[4:5], v[4:5], v[238:239], v[250:251] op_sel:[0,0,0] op_sel_hi:[1,0,1] neg_hi:[0,0,1]
	v_pk_mul_f32 v[250:251], v[2:3], v[236:237] op_sel:[1,1] op_sel_hi:[0,1]
	v_pk_fma_f32 v[2:3], v[2:3], v[236:237], v[250:251] op_sel:[0,0,0] op_sel_hi:[1,0,1] neg_hi:[0,0,1]
	v_pk_mul_f32 v[250:251], v[6:7], v[240:241] op_sel:[1,1] op_sel_hi:[0,1]
	v_pk_fma_f32 v[6:7], v[6:7], v[240:241], v[250:251] op_sel:[0,0,0] op_sel_hi:[1,0,1] neg_hi:[0,0,1]
	v_pk_add_f32 v[242:243], v[0:1], v[4:5]
	v_pk_add_f32 v[244:245], v[0:1], v[4:5] neg_lo:[0,1] neg_hi:[0,1]
	v_pk_add_f32 v[246:247], v[2:3], v[6:7]
	v_pk_add_f32 v[248:249], v[2:3], v[6:7] neg_lo:[0,1] neg_hi:[0,1]
	v_pk_add_f32 v[0:1], v[242:243], v[246:247]
	v_pk_add_f32 v[2:3], v[244:245], v[248:249] op_sel:[0,1] op_sel_hi:[1,0] neg_lo:[0,1]
	v_pk_add_f32 v[4:5], v[242:243], v[246:247] neg_lo:[0,1] neg_hi:[0,1]
	v_pk_add_f32 v[6:7], v[244:245], v[248:249] op_sel:[0,1] op_sel_hi:[1,0] neg_hi:[0,1]
	s_waitcnt lgkmcnt(8)
	v_pk_mul_f32 v[250:251], v[12:13], v[238:239] op_sel:[1,1] op_sel_hi:[0,1]
	v_pk_fma_f32 v[12:13], v[12:13], v[238:239], v[250:251] op_sel:[0,0,0] op_sel_hi:[1,0,1] neg_hi:[0,0,1]
	v_pk_mul_f32 v[250:251], v[10:11], v[236:237] op_sel:[1,1] op_sel_hi:[0,1]
	v_pk_fma_f32 v[10:11], v[10:11], v[236:237], v[250:251] op_sel:[0,0,0] op_sel_hi:[1,0,1] neg_hi:[0,0,1]
	v_pk_mul_f32 v[250:251], v[14:15], v[240:241] op_sel:[1,1] op_sel_hi:[0,1]
	v_pk_fma_f32 v[14:15], v[14:15], v[240:241], v[250:251] op_sel:[0,0,0] op_sel_hi:[1,0,1] neg_hi:[0,0,1]
	v_pk_add_f32 v[242:243], v[8:9], v[12:13]
	v_pk_add_f32 v[244:245], v[8:9], v[12:13] neg_lo:[0,1] neg_hi:[0,1]
	v_pk_add_f32 v[246:247], v[10:11], v[14:15]
	v_pk_add_f32 v[248:249], v[10:11], v[14:15] neg_lo:[0,1] neg_hi:[0,1]
	v_pk_add_f32 v[8:9], v[242:243], v[246:247]
	v_pk_add_f32 v[10:11], v[244:245], v[248:249] op_sel:[0,1] op_sel_hi:[1,0] neg_lo:[0,1]
	v_pk_add_f32 v[12:13], v[242:243], v[246:247] neg_lo:[0,1] neg_hi:[0,1]
	v_pk_add_f32 v[14:15], v[244:245], v[248:249] op_sel:[0,1] op_sel_hi:[1,0] neg_hi:[0,1]
	s_waitcnt lgkmcnt(4)
	v_pk_mul_f32 v[250:251], v[20:21], v[238:239] op_sel:[1,1] op_sel_hi:[0,1]
	v_pk_fma_f32 v[20:21], v[20:21], v[238:239], v[250:251] op_sel:[0,0,0] op_sel_hi:[1,0,1] neg_hi:[0,0,1]
	v_pk_mul_f32 v[250:251], v[18:19], v[236:237] op_sel:[1,1] op_sel_hi:[0,1]
	v_pk_fma_f32 v[18:19], v[18:19], v[236:237], v[250:251] op_sel:[0,0,0] op_sel_hi:[1,0,1] neg_hi:[0,0,1]
	v_pk_mul_f32 v[250:251], v[22:23], v[240:241] op_sel:[1,1] op_sel_hi:[0,1]
	v_pk_fma_f32 v[22:23], v[22:23], v[240:241], v[250:251] op_sel:[0,0,0] op_sel_hi:[1,0,1] neg_hi:[0,0,1]
	v_pk_add_f32 v[242:243], v[16:17], v[20:21]
	v_pk_add_f32 v[244:245], v[16:17], v[20:21] neg_lo:[0,1] neg_hi:[0,1]
	v_pk_add_f32 v[246:247], v[18:19], v[22:23]
	v_pk_add_f32 v[248:249], v[18:19], v[22:23] neg_lo:[0,1] neg_hi:[0,1]
	v_pk_add_f32 v[16:17], v[242:243], v[246:247]
	v_pk_add_f32 v[18:19], v[244:245], v[248:249] op_sel:[0,1] op_sel_hi:[1,0] neg_lo:[0,1]
	v_pk_add_f32 v[20:21], v[242:243], v[246:247] neg_lo:[0,1] neg_hi:[0,1]
	v_pk_add_f32 v[22:23], v[244:245], v[248:249] op_sel:[0,1] op_sel_hi:[1,0] neg_hi:[0,1]
	s_waitcnt lgkmcnt(0)
	v_pk_mul_f32 v[250:251], v[28:29], v[238:239] op_sel:[1,1] op_sel_hi:[0,1]
	v_pk_fma_f32 v[28:29], v[28:29], v[238:239], v[250:251] op_sel:[0,0,0] op_sel_hi:[1,0,1] neg_hi:[0,0,1]
	v_pk_mul_f32 v[250:251], v[26:27], v[236:237] op_sel:[1,1] op_sel_hi:[0,1]
	v_pk_fma_f32 v[26:27], v[26:27], v[236:237], v[250:251] op_sel:[0,0,0] op_sel_hi:[1,0,1] neg_hi:[0,0,1]
	v_pk_mul_f32 v[250:251], v[30:31], v[240:241] op_sel:[1,1] op_sel_hi:[0,1]
	v_pk_fma_f32 v[30:31], v[30:31], v[240:241], v[250:251] op_sel:[0,0,0] op_sel_hi:[1,0,1] neg_hi:[0,0,1]
	v_pk_add_f32 v[242:243], v[24:25], v[28:29]
	v_pk_add_f32 v[244:245], v[24:25], v[28:29] neg_lo:[0,1] neg_hi:[0,1]
	v_pk_add_f32 v[246:247], v[26:27], v[30:31]
	v_pk_add_f32 v[248:249], v[26:27], v[30:31] neg_lo:[0,1] neg_hi:[0,1]
	v_pk_add_f32 v[24:25], v[242:243], v[246:247]
	v_pk_add_f32 v[26:27], v[244:245], v[248:249] op_sel:[0,1] op_sel_hi:[1,0] neg_lo:[0,1]
	v_pk_add_f32 v[28:29], v[242:243], v[246:247] neg_lo:[0,1] neg_hi:[0,1]
	v_pk_add_f32 v[30:31], v[244:245], v[248:249] op_sel:[0,1] op_sel_hi:[1,0] neg_hi:[0,1]
	v_pk_mul_f32 v[250:251], v[16:17], v[82:83] op_sel:[1,1] op_sel_hi:[0,1]
	v_pk_fma_f32 v[16:17], v[16:17], v[82:83], v[250:251] op_sel:[0,0,0] op_sel_hi:[1,0,1] neg_hi:[0,0,1]
	v_pk_mul_f32 v[250:251], v[8:9], v[80:81] op_sel:[1,1] op_sel_hi:[0,1]
	v_pk_fma_f32 v[8:9], v[8:9], v[80:81], v[250:251] op_sel:[0,0,0] op_sel_hi:[1,0,1] neg_hi:[0,0,1]
	v_pk_mul_f32 v[250:251], v[24:25], v[84:85] op_sel:[1,1] op_sel_hi:[0,1]
	v_pk_fma_f32 v[24:25], v[24:25], v[84:85], v[250:251] op_sel:[0,0,0] op_sel_hi:[1,0,1] neg_hi:[0,0,1]
	v_pk_add_f32 v[242:243], v[0:1], v[16:17]
	v_pk_add_f32 v[244:245], v[0:1], v[16:17] neg_lo:[0,1] neg_hi:[0,1]
	v_pk_add_f32 v[246:247], v[8:9], v[24:25]
	v_pk_add_f32 v[248:249], v[8:9], v[24:25] neg_lo:[0,1] neg_hi:[0,1]
	v_pk_add_f32 v[0:1], v[242:243], v[246:247]
	ds_write_b64 v227, v[0:1] offset:0
	v_pk_add_f32 v[8:9], v[244:245], v[248:249] op_sel:[0,1] op_sel_hi:[1,0] neg_lo:[0,1]
	ds_write_b64 v227, v[8:9] offset:8192
	v_pk_add_f32 v[16:17], v[242:243], v[246:247] neg_lo:[0,1] neg_hi:[0,1]
	ds_write_b64 v227, v[16:17] offset:16384
	v_pk_add_f32 v[24:25], v[244:245], v[248:249] op_sel:[0,1] op_sel_hi:[1,0] neg_hi:[0,1]
	ds_write_b64 v227, v[24:25] offset:24576
	v_pk_mul_f32 v[250:251], v[18:19], v[224:225] op_sel:[1,1] op_sel_hi:[1,0] neg_lo:[0,0] neg_hi:[0,0]
; HD float2 cmul(float2 a, float2 b){ return make_float2(a.x*b.x - a.y*b.y, a.x*b.y + a.y*b.x); }
; HD float2 cmulc(float2 a, float2 b){ return make_float2(a.x*b.x + a.y*b.y, a.y*b.x - a.x*b.y); }
; template<bool INV, bool NOTW>
; HD void bf4c(float2* Z, int i0, int i1, int i2, int i3, float2 w1, float2 w2, float2 w3){
;   float2 a0=Z[i0], a1=Z[i1], a2=Z[i2], a3=Z[i3];
;   if (INV && !NOTW){ a1=cmulc(a1,w1); a2=cmulc(a2,w2); a3=cmulc(a3,w3); }
;   float2 s02=make_float2(a0.x+a2.x,a0.y+a2.y), d02=make_float2(a0.x-a2.x,a0.y-a2.y);
;   float2 s13=make_float2(a1.x+a3.x,a1.y+a3.y), d13=make_float2(a1.x-a3.x,a1.y-a3.y);
;   float2 y0=make_float2(s02.x+s13.x,s02.y+s13.y), y2=make_float2(s02.x-s13.x,s02.y-s13.y);
;   float2 ym=make_float2(d02.x+d13.y,d02.y-d13.x);
;   float2 yp=make_float2(d02.x-d13.y,d02.y+d13.x);
;   float2 y1, y3;
;   if (INV){ y1=yp; y3=ym; } else if (NOTW){ y1=ym; y3=yp; } else { y1=cmul(ym,w1); y2=cmul(y2,w2); y3=cmul(yp,w3); }
;   Z[i0]=y0; Z[i1]=y1; Z[i2]=y2; Z[i3]=y3;
; }
; template<bool INV, int LQ, bool BARRIER=true>
; HD void fft_pass(float2* Z, const float2* twA, const float2* twB, int tid){
;     ...
;   if (BARRIER) __syncthreads(); else asm volatile("s_waitcnt lgkmcnt(0)" ::: "memory");
; }
; __device__ __forceinline__ void fft_fwd_head(float2* Z, const float2* twA, const float2* twB, int tid){
;   fft_pass<false,10>(Z,twA,twB,tid); fft_pass<false,8>(Z,twA,twB,tid); fft_pass<false,6,false>(Z,twA,twB,tid);
;   fft_pass<false,4,false>(Z,twA,twB,tid); fft_pass<false,2,false>(Z,twA,twB,tid);
; }
; __device__ __forceinline__ void fft_inv_tail(float2* Z, const float2* twA, const float2* twB, int tid){
;   fft_pass<true,2,false>(Z,twA,twB,tid); fft_pass<true,4,false>(Z,twA,twB,tid); fft_pass<true,6>(Z,twA,twB,tid);
;   fft_pass<true,8>(Z,twA,twB,tid); fft_pass<true,10>(Z,twA,twB,tid);
	v_pk_fma_f32 v[18:19], v[18:19], v[224:225], v[250:251] op_sel:[0,0,0] op_sel_hi:[0,1,1] neg_lo:[0,0,1] neg_hi:[0,0,0]
	v_pk_mul_f32 v[250:251], v[18:19], v[82:83] op_sel:[1,1] op_sel_hi:[0,1]
	v_pk_fma_f32 v[18:19], v[18:19], v[82:83], v[250:251] op_sel:[0,0,0] op_sel_hi:[1,0,1] neg_hi:[0,0,1]
	v_pk_mul_f32 v[250:251], v[10:11], v[222:223] op_sel:[1,1] op_sel_hi:[1,0] neg_lo:[0,0] neg_hi:[0,0]
	v_pk_fma_f32 v[10:11], v[10:11], v[222:223], v[250:251] op_sel:[0,0,0] op_sel_hi:[0,1,1] neg_lo:[0,0,1] neg_hi:[0,0,0]
	v_pk_mul_f32 v[250:251], v[10:11], v[80:81] op_sel:[1,1] op_sel_hi:[0,1]
	v_pk_fma_f32 v[10:11], v[10:11], v[80:81], v[250:251] op_sel:[0,0,0] op_sel_hi:[1,0,1] neg_hi:[0,0,1]
	v_pk_mul_f32 v[250:251], v[26:27], v[222:223] op_sel:[1,0] op_sel_hi:[1,1] neg_lo:[0,0] neg_hi:[0,0]
	v_pk_fma_f32 v[26:27], v[26:27], v[222:223], v[250:251] op_sel:[0,1,0] op_sel_hi:[0,0,1] neg_lo:[0,0,1] neg_hi:[0,0,0]
	v_pk_mul_f32 v[250:251], v[26:27], v[84:85] op_sel:[1,1] op_sel_hi:[0,1]
	v_pk_fma_f32 v[26:27], v[26:27], v[84:85], v[250:251] op_sel:[0,0,0] op_sel_hi:[1,0,1] neg_hi:[0,0,1]
	v_pk_add_f32 v[242:243], v[2:3], v[18:19]
	v_pk_add_f32 v[244:245], v[2:3], v[18:19] neg_lo:[0,1] neg_hi:[0,1]
	v_pk_add_f32 v[246:247], v[10:11], v[26:27]
	v_pk_add_f32 v[248:249], v[10:11], v[26:27] neg_lo:[0,1] neg_hi:[0,1]
	v_pk_add_f32 v[2:3], v[242:243], v[246:247]
	ds_write_b64 v227, v[2:3] offset:2048
	v_pk_add_f32 v[10:11], v[244:245], v[248:249] op_sel:[0,1] op_sel_hi:[1,0] neg_lo:[0,1]
	ds_write_b64 v227, v[10:11] offset:10240
	v_pk_add_f32 v[18:19], v[242:243], v[246:247] neg_lo:[0,1] neg_hi:[0,1]
	ds_write_b64 v227, v[18:19] offset:18432
	v_pk_add_f32 v[26:27], v[244:245], v[248:249] op_sel:[0,1] op_sel_hi:[1,0] neg_hi:[0,1]
	ds_write_b64 v227, v[26:27] offset:26624
	v_pk_add_f32 v[20:21], v[20:21], 0 op_sel:[1,0] op_sel_hi:[0,0] neg_lo:[1,0]
	v_pk_mul_f32 v[250:251], v[20:21], v[82:83] op_sel:[1,1] op_sel_hi:[0,1]
	v_pk_fma_f32 v[20:21], v[20:21], v[82:83], v[250:251] op_sel:[0,0,0] op_sel_hi:[1,0,1] neg_hi:[0,0,1]
	v_pk_mul_f32 v[250:251], v[12:13], v[224:225] op_sel:[1,1] op_sel_hi:[1,0] neg_lo:[0,0] neg_hi:[0,0]
	v_pk_fma_f32 v[12:13], v[12:13], v[224:225], v[250:251] op_sel:[0,0,0] op_sel_hi:[0,1,1] neg_lo:[0,0,1] neg_hi:[0,0,0]
	v_pk_mul_f32 v[250:251], v[12:13], v[80:81] op_sel:[1,1] op_sel_hi:[0,1]
	v_pk_fma_f32 v[12:13], v[12:13], v[80:81], v[250:251] op_sel:[0,0,0] op_sel_hi:[1,0,1] neg_hi:[0,0,1]
	v_pk_mul_f32 v[250:251], v[28:29], v[224:225] op_sel:[1,1] op_sel_hi:[1,0] neg_lo:[0,0] neg_hi:[0,1]
	v_pk_fma_f32 v[28:29], v[28:29], v[224:225], v[250:251] op_sel:[0,0,0] op_sel_hi:[0,1,1] neg_lo:[0,1,1] neg_hi:[0,0,0]
	v_pk_mul_f32 v[250:251], v[28:29], v[84:85] op_sel:[1,1] op_sel_hi:[0,1]
	v_pk_fma_f32 v[28:29], v[28:29], v[84:85], v[250:251] op_sel:[0,0,0] op_sel_hi:[1,0,1] neg_hi:[0,0,1]
	v_pk_add_f32 v[242:243], v[4:5], v[20:21]
	v_pk_add_f32 v[244:245], v[4:5], v[20:21] neg_lo:[0,1] neg_hi:[0,1]
	v_pk_add_f32 v[246:247], v[12:13], v[28:29]
	v_pk_add_f32 v[248:249], v[12:13], v[28:29] neg_lo:[0,1] neg_hi:[0,1]
	v_pk_add_f32 v[4:5], v[242:243], v[246:247]
	ds_write_b64 v227, v[4:5] offset:4096
	v_pk_add_f32 v[12:13], v[244:245], v[248:249] op_sel:[0,1] op_sel_hi:[1,0] neg_lo:[0,1]
	ds_write_b64 v227, v[12:13] offset:12288
	v_pk_add_f32 v[20:21], v[242:243], v[246:247] neg_lo:[0,1] neg_hi:[0,1]
	ds_write_b64 v227, v[20:21] offset:20480
	v_pk_add_f32 v[28:29], v[244:245], v[248:249] op_sel:[0,1] op_sel_hi:[1,0] neg_hi:[0,1]
	ds_write_b64 v227, v[28:29] offset:28672
	v_pk_mul_f32 v[250:251], v[22:23], v[224:225] op_sel:[1,1] op_sel_hi:[1,0] neg_lo:[0,0] neg_hi:[0,1]
	v_pk_fma_f32 v[22:23], v[22:23], v[224:225], v[250:251] op_sel:[0,0,0] op_sel_hi:[0,1,1] neg_lo:[0,1,1] neg_hi:[0,0,0]
	v_pk_mul_f32 v[250:251], v[22:23], v[82:83] op_sel:[1,1] op_sel_hi:[0,1]
	v_pk_fma_f32 v[22:23], v[22:23], v[82:83], v[250:251] op_sel:[0,0,0] op_sel_hi:[1,0,1] neg_hi:[0,0,1]
	v_pk_mul_f32 v[250:251], v[14:15], v[222:223] op_sel:[1,0] op_sel_hi:[1,1] neg_lo:[0,0] neg_hi:[0,0]
	v_pk_fma_f32 v[14:15], v[14:15], v[222:223], v[250:251] op_sel:[0,1,0] op_sel_hi:[0,0,1] neg_lo:[0,0,1] neg_hi:[0,0,0]
	v_pk_mul_f32 v[250:251], v[14:15], v[80:81] op_sel:[1,1] op_sel_hi:[0,1]
	v_pk_fma_f32 v[14:15], v[14:15], v[80:81], v[250:251] op_sel:[0,0,0] op_sel_hi:[1,0,1] neg_hi:[0,0,1]
	v_pk_mul_f32 v[250:251], v[30:31], v[222:223] op_sel:[1,1] op_sel_hi:[1,0] neg_lo:[0,1] neg_hi:[0,1]
	v_pk_fma_f32 v[30:31], v[30:31], v[222:223], v[250:251] op_sel:[0,0,0] op_sel_hi:[0,1,1] neg_lo:[0,1,1] neg_hi:[0,1,0]
	v_pk_mul_f32 v[250:251], v[30:31], v[84:85] op_sel:[1,1] op_sel_hi:[0,1]
	v_pk_fma_f32 v[30:31], v[30:31], v[84:85], v[250:251] op_sel:[0,0,0] op_sel_hi:[1,0,1] neg_hi:[0,0,1]
	v_pk_add_f32 v[242:243], v[6:7], v[22:23]
	v_pk_add_f32 v[244:245], v[6:7], v[22:23] neg_lo:[0,1] neg_hi:[0,1]
	v_pk_add_f32 v[246:247], v[14:15], v[30:31]
	v_pk_add_f32 v[248:249], v[14:15], v[30:31] neg_lo:[0,1] neg_hi:[0,1]
	v_pk_add_f32 v[6:7], v[242:243], v[246:247]
	ds_write_b64 v227, v[6:7] offset:6144
	v_pk_add_f32 v[14:15], v[244:245], v[248:249] op_sel:[0,1] op_sel_hi:[1,0] neg_lo:[0,1]
	ds_write_b64 v227, v[14:15] offset:14336
	v_pk_add_f32 v[22:23], v[242:243], v[246:247] neg_lo:[0,1] neg_hi:[0,1]
	ds_write_b64 v227, v[22:23] offset:22528
	v_pk_add_f32 v[30:31], v[244:245], v[248:249] op_sel:[0,1] op_sel_hi:[1,0] neg_hi:[0,1]
	ds_write_b64 v227, v[30:31] offset:30720
	s_waitcnt lgkmcnt(0)
	s_barrier
	s_mov_b64 s[12:13], -1
	s_and_b64 vcc, exec, s[50:51]
	s_cbranch_vccz .LBB0_1340
; __device__ __forceinline__ float bf2f(u16 h){ return __uint_as_float(((unsigned)h)<<16); }
; HD float2 cmul(float2 a, float2 b){ return make_float2(a.x*b.x - a.y*b.y, a.x*b.y + a.y*b.x); }
; HD float2 cmulc(float2 a, float2 b){ return make_float2(a.x*b.x + a.y*b.y, a.y*b.x - a.x*b.y); }
; HD void inv12_half(const float2* Z, const float2* twA, const float2* twB, int t, float2& x0, float2& x1){
;   float2 w1=cmul(twA[t>>6],twB[t&63]), w2=cmul(w1,w1), w3=cmul(w2,w1);
;   float2 b0=Z[t], b1=cmulc(Z[t+4096],w1), b2=cmulc(Z[t+8192],w2), b3=cmulc(Z[t+12288],w3);
;   float2 s02=make_float2(b0.x+b2.x,b0.y+b2.y), d02=make_float2(b0.x-b2.x,b0.y-b2.y);
;   float2 s13=make_float2(b1.x+b3.x,b1.y+b3.y), d13=make_float2(b1.x-b3.x,b1.y-b3.y);
;   x0=make_float2(s02.x+s13.x,s02.y+s13.y);
;   x1=make_float2(d02.x-d13.y,d02.y+d13.x);
; }
; __device__ __forceinline__ void phase_hyena(KP kp_, int hf){ asm volatile("" : "+s"(kp_)); const Params p=load_params(kp_);
;     ...
;         } else { int tq=tid; asm volatile("" : "+v"(tq));
;           _Pragma("unroll 4") for (int i=0;i<8;++i){ int tb=tq+512*i; float2 xr[2]; inv12_half(Z,twA,twB,tb,xr[0],xr[1]);
;             _Pragma("unroll") for (int hh=0;hh<2;++hh){ int t=tb+hh*4096;
;               float x0=hconv3(r2,t,wb0,wb1,wb2,bb_), x1=hconv3(r2+8192,t,wb0,wb1,wb2,bb_);
;               float2 y=xr[hh]; y.x*=(1.f/16384.f); y.y*=(1.f/16384.f); float2 z1=Zs[t];
;               float o0=x0*(y.x+z1.x*bias1)*bf2f(rz[t]); float o1=x1*(y.y+z1.y*bias1)*bf2f(rz[8192+t]);
;               ybT[(size_t)c*16384+t]=f2bf(o0); ybT[(size_t)c*16384+8192+t]=f2bf(o1); } }
	v_lshlrev_b32_e32 v0, 1, v86
	v_add_u32_e32 v1, 0x1000, v0
	v_add_u32_e32 v2, 0x2000, v0
	v_add_u32_e32 v4, 0x3000, v0
	v_lshlrev_b32_e32 v5, 3, v86
	v_mov_b32_e32 v8, v5
	v_add_u32_e32 v9, 0x10000, v5
	v_lshrrev_b32_e32 v7, 6, v86
	v_lshl_add_u32 v7, v7, 3, s88
	v_and_b32_e32 v108, 63, v86
	v_lshl_add_u32 v108, v108, 3, s91
	ds_read_b64 v[10:11], v108
	s_add_u32 s12, s72, 0x4000
	s_addc_u32 s13, s73, 0
	s_add_u32 s50, s80, 0x8000
	s_addc_u32 s51, s81, 0
	v_mov_b32_e32 v107, 0
	global_load_ushort v228, v0, s[96:97] offset:0
	global_load_ushort v230, v0, s[74:75] offset:0
	global_load_ushort v232, v0, s[72:73] offset:0
	global_load_ushort v234, v0, s[12:13] offset:0
	global_load_ushort v229, v2, s[96:97] offset:0
	global_load_ushort v231, v2, s[74:75] offset:0
	global_load_ushort v233, v2, s[72:73] offset:0
	global_load_ushort v235, v2, s[12:13] offset:0
	v_mov_b32_e32 v6, v5
	global_load_dwordx2 v[236:237], v6, s[80:81]
	global_load_dwordx2 v[238:239], v6, s[50:51]
	ds_read_b64 v[12:13], v7 offset:0
	ds_read_b64 v[14:15], v8 offset:0
	ds_read_b64 v[16:17], v8 offset:32768
	ds_read_b64 v[18:19], v9 offset:0
	ds_read_b64 v[20:21], v9 offset:32768
	global_load_ushort v240, v0, s[96:97] offset:1024
	global_load_ushort v242, v0, s[74:75] offset:1024
	global_load_ushort v244, v0, s[72:73] offset:1024
	global_load_ushort v246, v0, s[12:13] offset:1024
	global_load_ushort v241, v2, s[96:97] offset:1024
	global_load_ushort v243, v2, s[74:75] offset:1024
	global_load_ushort v245, v2, s[72:73] offset:1024
	global_load_ushort v247, v2, s[12:13] offset:1024
	v_add_u32_e32 v6, 0x1000, v5
	global_load_dwordx2 v[248:249], v6, s[80:81]
	global_load_dwordx2 v[250:251], v6, s[50:51]
	ds_read_b64 v[58:59], v7 offset:64
	ds_read_b64 v[60:61], v8 offset:4096
	ds_read_b64 v[62:63], v8 offset:36864
	ds_read_b64 v[64:65], v9 offset:4096
	ds_read_b64 v[66:67], v9 offset:36864
	s_waitcnt lgkmcnt(5)
	v_pk_mul_f32 v[222:223], v[12:13], v[10:11] op_sel:[1,1] op_sel_hi:[1,0]
	v_pk_fma_f32 v[22:23], v[12:13], v[10:11], v[222:223] op_sel:[0,0,0] op_sel_hi:[0,1,1] neg_lo:[0,0,1]
	v_pk_mul_f32 v[222:223], v[22:23], v[22:23] op_sel:[1,1] op_sel_hi:[1,0]
	v_pk_fma_f32 v[24:25], v[22:23], v[22:23], v[222:223] op_sel:[0,0,0] op_sel_hi:[0,1,1] neg_lo:[0,0,1]
	v_pk_mul_f32 v[222:223], v[24:25], v[22:23] op_sel:[1,1] op_sel_hi:[1,0]
	v_pk_fma_f32 v[26:27], v[24:25], v[22:23], v[222:223] op_sel:[0,0,0] op_sel_hi:[0,1,1] neg_lo:[0,0,1]
	v_pk_mul_f32 v[222:223], v[16:17], v[22:23] op_sel:[1,1] op_sel_hi:[0,1]
	v_pk_fma_f32 v[28:29], v[16:17], v[22:23], v[222:223] op_sel:[0,0,0] op_sel_hi:[1,0,1] neg_hi:[0,0,1]
	v_pk_mul_f32 v[222:223], v[18:19], v[24:25] op_sel:[1,1] op_sel_hi:[0,1]
	v_pk_fma_f32 v[30:31], v[18:19], v[24:25], v[222:223] op_sel:[0,0,0] op_sel_hi:[1,0,1] neg_hi:[0,0,1]
	v_pk_mul_f32 v[222:223], v[20:21], v[26:27] op_sel:[1,1] op_sel_hi:[0,1]
	v_pk_fma_f32 v[68:69], v[20:21], v[26:27], v[222:223] op_sel:[0,0,0] op_sel_hi:[1,0,1] neg_hi:[0,0,1]
	v_pk_add_f32 v[70:71], v[14:15], v[30:31]
	v_pk_add_f32 v[72:73], v[14:15], v[30:31] neg_lo:[0,1] neg_hi:[0,1]
	v_pk_add_f32 v[74:75], v[28:29], v[68:69]
	v_pk_add_f32 v[80:81], v[28:29], v[68:69] neg_lo:[0,1] neg_hi:[0,1]
	v_pk_add_f32 v[82:83], v[70:71], v[74:75]
	v_pk_add_f32 v[84:85], v[72:73], v[80:81] op_sel:[0,1] op_sel_hi:[1,0] neg_lo:[0,1]
	s_waitcnt vmcnt(10)
	v_lshlrev_b32_e32 v224, 16, v228
	v_mov_b32_e32 v225, 0
	v_mov_b32_e32 v226, 0
	v_mov_b32_dpp v225, v224 wave_shr:1 row_mask:0xf bank_mask:0xf
	v_mov_b32_dpp v226, v224 wave_shl:1 row_mask:0xf bank_mask:0xf
	v_mul_f32_e32 v227, v88, v224
	v_fmac_f32_e32 v227, v87, v225
	v_fmac_f32_e32 v227, v89, v226
	v_add_f32_e32 v94, v90, v227
	v_lshlrev_b32_e32 v224, 16, v230
	v_mov_b32_e32 v225, 0
	v_mov_b32_e32 v226, 0
	v_mov_b32_dpp v225, v224 wave_shr:1 row_mask:0xf bank_mask:0xf
	v_mov_b32_dpp v226, v224 wave_shl:1 row_mask:0xf bank_mask:0xf
	v_mul_f32_e32 v227, v88, v224
	v_fmac_f32_e32 v227, v87, v225
	v_fmac_f32_e32 v227, v89, v226
	v_add_f32_e32 v97, v90, v227
	v_lshlrev_b32_e32 v224, 16, v229
	v_mov_b32_e32 v225, 0
	v_mov_b32_e32 v226, 0
	v_mov_b32_dpp v225, v224 wave_shr:1 row_mask:0xf bank_mask:0xf
	v_mov_b32_dpp v226, v224 wave_shl:1 row_mask:0xf bank_mask:0xf
	v_mul_f32_e32 v227, v88, v224
	v_fmac_f32_e32 v227, v87, v225
	v_fmac_f32_e32 v227, v89, v226
	v_add_f32_e32 v98, v90, v227
	v_lshlrev_b32_e32 v224, 16, v231
	v_mov_b32_e32 v225, 0
	v_mov_b32_e32 v226, 0
	v_mov_b32_dpp v225, v224 wave_shr:1 row_mask:0xf bank_mask:0xf
	v_mov_b32_dpp v226, v224 wave_shl:1 row_mask:0xf bank_mask:0xf
	v_mul_f32_e32 v227, v88, v224
	v_fmac_f32_e32 v227, v87, v225
	v_fmac_f32_e32 v227, v89, v226
	v_add_f32_e32 v100, v90, v227
	v_mul_f32_e32 v108, v91, v236
	v_fmac_f32_e32 v108, 0x38800000, v82
	v_mul_f32_e32 v108, v94, v108
	v_lshlrev_b32_e32 v109, 16, v232
	v_mul_f32_e32 v108, v108, v109
	v_cvt_pk_bf16_f32 v224, v108, v108
	v_mul_f32_e32 v108, v91, v237
	v_fmac_f32_e32 v108, 0x38800000, v83
	v_mul_f32_e32 v108, v108, v97
	v_lshlrev_b32_e32 v109, 16, v234
	v_mul_f32_e32 v108, v108, v109
	v_cvt_pk_bf16_f32 v225, v108, v108
	v_add_u32_e32 v106, 0x0, v0
	v_lshl_add_u64 v[104:105], v[54:55], 0, v[106:107]
	global_store_short v[104:105], v224, off
	v_lshl_add_u64 v[104:105], v[56:57], 0, v[106:107]
	global_store_short v[104:105], v225, off
	v_mul_f32_e32 v108, v91, v238
	v_fmac_f32_e32 v108, 0x38800000, v84
	v_mul_f32_e32 v108, v98, v108
	v_lshlrev_b32_e32 v109, 16, v233
	v_mul_f32_e32 v108, v108, v109
	v_cvt_pk_bf16_f32 v224, v108, v108
	v_mul_f32_e32 v108, v91, v239
	v_fmac_f32_e32 v108, 0x38800000, v85
	v_mul_f32_e32 v108, v108, v100
	v_lshlrev_b32_e32 v109, 16, v235
	v_mul_f32_e32 v108, v108, v109
	v_cvt_pk_bf16_f32 v225, v108, v108
	v_add_u32_e32 v106, 0x0, v2
	v_lshl_add_u64 v[104:105], v[54:55], 0, v[106:107]
	global_store_short v[104:105], v224, off
	v_lshl_add_u64 v[104:105], v[56:57], 0, v[106:107]
	global_store_short v[104:105], v225, off
	global_load_ushort v228, v0, s[96:97] offset:2048
	global_load_ushort v230, v0, s[74:75] offset:2048
	global_load_ushort v232, v0, s[72:73] offset:2048
	global_load_ushort v234, v0, s[12:13] offset:2048
	global_load_ushort v229, v2, s[96:97] offset:2048
	global_load_ushort v231, v2, s[74:75] offset:2048
	global_load_ushort v233, v2, s[72:73] offset:2048
	global_load_ushort v235, v2, s[12:13] offset:2048
	v_add_u32_e32 v6, 0x2000, v5
	global_load_dwordx2 v[236:237], v6, s[80:81]
	global_load_dwordx2 v[238:239], v6, s[50:51]
	ds_read_b64 v[12:13], v7 offset:128
	ds_read_b64 v[14:15], v8 offset:8192
	ds_read_b64 v[16:17], v8 offset:40960
	ds_read_b64 v[18:19], v9 offset:8192
	ds_read_b64 v[20:21], v9 offset:40960
	s_waitcnt lgkmcnt(5)
; __device__ __forceinline__ float bf2f(u16 h){ return __uint_as_float(((unsigned)h)<<16); }
; HD float2 cmul(float2 a, float2 b){ return make_float2(a.x*b.x - a.y*b.y, a.x*b.y + a.y*b.x); }
; HD float2 cmulc(float2 a, float2 b){ return make_float2(a.x*b.x + a.y*b.y, a.y*b.x - a.x*b.y); }
; HD void inv12_half(const float2* Z, const float2* twA, const float2* twB, int t, float2& x0, float2& x1){
;   float2 w1=cmul(twA[t>>6],twB[t&63]), w2=cmul(w1,w1), w3=cmul(w2,w1);
;   float2 b0=Z[t], b1=cmulc(Z[t+4096],w1), b2=cmulc(Z[t+8192],w2), b3=cmulc(Z[t+12288],w3);
;   float2 s02=make_float2(b0.x+b2.x,b0.y+b2.y), d02=make_float2(b0.x-b2.x,b0.y-b2.y);
;   float2 s13=make_float2(b1.x+b3.x,b1.y+b3.y), d13=make_float2(b1.x-b3.x,b1.y-b3.y);
;   x0=make_float2(s02.x+s13.x,s02.y+s13.y);
;   x1=make_float2(d02.x-d13.y,d02.y+d13.x);
; }
; __device__ __forceinline__ void phase_hyena(KP kp_, int hf){ asm volatile("" : "+s"(kp_)); const Params p=load_params(kp_);
;     ...
;         } else { int tq=tid; asm volatile("" : "+v"(tq));
;           _Pragma("unroll 4") for (int i=0;i<8;++i){ int tb=tq+512*i; float2 xr[2]; inv12_half(Z,twA,twB,tb,xr[0],xr[1]);
;             _Pragma("unroll") for (int hh=0;hh<2;++hh){ int t=tb+hh*4096;
;               float x0=hconv3(r2,t,wb0,wb1,wb2,bb_), x1=hconv3(r2+8192,t,wb0,wb1,wb2,bb_);
;               float2 y=xr[hh]; y.x*=(1.f/16384.f); y.y*=(1.f/16384.f); float2 z1=Zs[t];
;               float o0=x0*(y.x+z1.x*bias1)*bf2f(rz[t]); float o1=x1*(y.y+z1.y*bias1)*bf2f(rz[8192+t]);
;               ybT[(size_t)c*16384+t]=f2bf(o0); ybT[(size_t)c*16384+8192+t]=f2bf(o1); } }
	v_pk_mul_f32 v[222:223], v[58:59], v[10:11] op_sel:[1,1] op_sel_hi:[1,0]
	v_pk_fma_f32 v[22:23], v[58:59], v[10:11], v[222:223] op_sel:[0,0,0] op_sel_hi:[0,1,1] neg_lo:[0,0,1]
	v_pk_mul_f32 v[222:223], v[22:23], v[22:23] op_sel:[1,1] op_sel_hi:[1,0]
	v_pk_fma_f32 v[24:25], v[22:23], v[22:23], v[222:223] op_sel:[0,0,0] op_sel_hi:[0,1,1] neg_lo:[0,0,1]
	v_pk_mul_f32 v[222:223], v[24:25], v[22:23] op_sel:[1,1] op_sel_hi:[1,0]
	v_pk_fma_f32 v[26:27], v[24:25], v[22:23], v[222:223] op_sel:[0,0,0] op_sel_hi:[0,1,1] neg_lo:[0,0,1]
	v_pk_mul_f32 v[222:223], v[62:63], v[22:23] op_sel:[1,1] op_sel_hi:[0,1]
	v_pk_fma_f32 v[28:29], v[62:63], v[22:23], v[222:223] op_sel:[0,0,0] op_sel_hi:[1,0,1] neg_hi:[0,0,1]
	v_pk_mul_f32 v[222:223], v[64:65], v[24:25] op_sel:[1,1] op_sel_hi:[0,1]
	v_pk_fma_f32 v[30:31], v[64:65], v[24:25], v[222:223] op_sel:[0,0,0] op_sel_hi:[1,0,1] neg_hi:[0,0,1]
	v_pk_mul_f32 v[222:223], v[66:67], v[26:27] op_sel:[1,1] op_sel_hi:[0,1]
	v_pk_fma_f32 v[68:69], v[66:67], v[26:27], v[222:223] op_sel:[0,0,0] op_sel_hi:[1,0,1] neg_hi:[0,0,1]
	v_pk_add_f32 v[70:71], v[60:61], v[30:31]
	v_pk_add_f32 v[72:73], v[60:61], v[30:31] neg_lo:[0,1] neg_hi:[0,1]
	v_pk_add_f32 v[74:75], v[28:29], v[68:69]
	v_pk_add_f32 v[80:81], v[28:29], v[68:69] neg_lo:[0,1] neg_hi:[0,1]
	v_pk_add_f32 v[82:83], v[70:71], v[74:75]
	v_pk_add_f32 v[84:85], v[72:73], v[80:81] op_sel:[0,1] op_sel_hi:[1,0] neg_lo:[0,1]
	s_waitcnt vmcnt(14)
	v_lshlrev_b32_e32 v224, 16, v240
	v_mov_b32_e32 v225, 0
	v_mov_b32_e32 v226, 0
	v_mov_b32_dpp v225, v224 wave_shr:1 row_mask:0xf bank_mask:0xf
	v_mov_b32_dpp v226, v224 wave_shl:1 row_mask:0xf bank_mask:0xf
	v_mul_f32_e32 v227, v88, v224
	v_fmac_f32_e32 v227, v87, v225
	v_fmac_f32_e32 v227, v89, v226
	v_add_f32_e32 v94, v90, v227
	v_lshlrev_b32_e32 v224, 16, v242
	v_mov_b32_e32 v225, 0
	v_mov_b32_e32 v226, 0
	v_mov_b32_dpp v225, v224 wave_shr:1 row_mask:0xf bank_mask:0xf
	v_mov_b32_dpp v226, v224 wave_shl:1 row_mask:0xf bank_mask:0xf
	v_mul_f32_e32 v227, v88, v224
	v_fmac_f32_e32 v227, v87, v225
	v_fmac_f32_e32 v227, v89, v226
	v_add_f32_e32 v97, v90, v227
	v_lshlrev_b32_e32 v224, 16, v241
	v_mov_b32_e32 v225, 0
	v_mov_b32_e32 v226, 0
	v_mov_b32_dpp v225, v224 wave_shr:1 row_mask:0xf bank_mask:0xf
	v_mov_b32_dpp v226, v224 wave_shl:1 row_mask:0xf bank_mask:0xf
	v_mul_f32_e32 v227, v88, v224
	v_fmac_f32_e32 v227, v87, v225
	v_fmac_f32_e32 v227, v89, v226
	v_add_f32_e32 v98, v90, v227
	v_lshlrev_b32_e32 v224, 16, v243
	v_mov_b32_e32 v225, 0
	v_mov_b32_e32 v226, 0
	v_mov_b32_dpp v225, v224 wave_shr:1 row_mask:0xf bank_mask:0xf
	v_mov_b32_dpp v226, v224 wave_shl:1 row_mask:0xf bank_mask:0xf
	v_mul_f32_e32 v227, v88, v224
	v_fmac_f32_e32 v227, v87, v225
	v_fmac_f32_e32 v227, v89, v226
	v_add_f32_e32 v100, v90, v227
	v_mul_f32_e32 v108, v91, v248
	v_fmac_f32_e32 v108, 0x38800000, v82
	v_mul_f32_e32 v108, v94, v108
	v_lshlrev_b32_e32 v109, 16, v244
	v_mul_f32_e32 v108, v108, v109
	v_cvt_pk_bf16_f32 v224, v108, v108
	v_mul_f32_e32 v108, v91, v249
	v_fmac_f32_e32 v108, 0x38800000, v83
	v_mul_f32_e32 v108, v108, v97
	v_lshlrev_b32_e32 v109, 16, v246
	v_mul_f32_e32 v108, v108, v109
	v_cvt_pk_bf16_f32 v225, v108, v108
	v_add_u32_e32 v106, 0x400, v0
	v_lshl_add_u64 v[104:105], v[54:55], 0, v[106:107]
	global_store_short v[104:105], v224, off
	v_lshl_add_u64 v[104:105], v[56:57], 0, v[106:107]
	global_store_short v[104:105], v225, off
	v_mul_f32_e32 v108, v91, v250
	v_fmac_f32_e32 v108, 0x38800000, v84
	v_mul_f32_e32 v108, v98, v108
	v_lshlrev_b32_e32 v109, 16, v245
	v_mul_f32_e32 v108, v108, v109
	v_cvt_pk_bf16_f32 v224, v108, v108
	v_mul_f32_e32 v108, v91, v251
	v_fmac_f32_e32 v108, 0x38800000, v85
	v_mul_f32_e32 v108, v108, v100
	v_lshlrev_b32_e32 v109, 16, v247
	v_mul_f32_e32 v108, v108, v109
	v_cvt_pk_bf16_f32 v225, v108, v108
	v_add_u32_e32 v106, 0x400, v2
	v_lshl_add_u64 v[104:105], v[54:55], 0, v[106:107]
	global_store_short v[104:105], v224, off
	v_lshl_add_u64 v[104:105], v[56:57], 0, v[106:107]
	global_store_short v[104:105], v225, off
	global_load_ushort v240, v0, s[96:97] offset:3072
	global_load_ushort v242, v0, s[74:75] offset:3072
	global_load_ushort v244, v0, s[72:73] offset:3072
	global_load_ushort v246, v0, s[12:13] offset:3072
	global_load_ushort v241, v2, s[96:97] offset:3072
	global_load_ushort v243, v2, s[74:75] offset:3072
	global_load_ushort v245, v2, s[72:73] offset:3072
	global_load_ushort v247, v2, s[12:13] offset:3072
	v_add_u32_e32 v6, 0x3000, v5
	global_load_dwordx2 v[248:249], v6, s[80:81]
	global_load_dwordx2 v[250:251], v6, s[50:51]
	ds_read_b64 v[58:59], v7 offset:192
	ds_read_b64 v[60:61], v8 offset:12288
	ds_read_b64 v[62:63], v8 offset:45056
	ds_read_b64 v[64:65], v9 offset:12288
	ds_read_b64 v[66:67], v9 offset:45056
	s_waitcnt lgkmcnt(5)
	v_pk_mul_f32 v[222:223], v[12:13], v[10:11] op_sel:[1,1] op_sel_hi:[1,0]
	v_pk_fma_f32 v[22:23], v[12:13], v[10:11], v[222:223] op_sel:[0,0,0] op_sel_hi:[0,1,1] neg_lo:[0,0,1]
	v_pk_mul_f32 v[222:223], v[22:23], v[22:23] op_sel:[1,1] op_sel_hi:[1,0]
	v_pk_fma_f32 v[24:25], v[22:23], v[22:23], v[222:223] op_sel:[0,0,0] op_sel_hi:[0,1,1] neg_lo:[0,0,1]
	v_pk_mul_f32 v[222:223], v[24:25], v[22:23] op_sel:[1,1] op_sel_hi:[1,0]
	v_pk_fma_f32 v[26:27], v[24:25], v[22:23], v[222:223] op_sel:[0,0,0] op_sel_hi:[0,1,1] neg_lo:[0,0,1]
	v_pk_mul_f32 v[222:223], v[16:17], v[22:23] op_sel:[1,1] op_sel_hi:[0,1]
	v_pk_fma_f32 v[28:29], v[16:17], v[22:23], v[222:223] op_sel:[0,0,0] op_sel_hi:[1,0,1] neg_hi:[0,0,1]
	v_pk_mul_f32 v[222:223], v[18:19], v[24:25] op_sel:[1,1] op_sel_hi:[0,1]
	v_pk_fma_f32 v[30:31], v[18:19], v[24:25], v[222:223] op_sel:[0,0,0] op_sel_hi:[1,0,1] neg_hi:[0,0,1]
	v_pk_mul_f32 v[222:223], v[20:21], v[26:27] op_sel:[1,1] op_sel_hi:[0,1]
	v_pk_fma_f32 v[68:69], v[20:21], v[26:27], v[222:223] op_sel:[0,0,0] op_sel_hi:[1,0,1] neg_hi:[0,0,1]
	v_pk_add_f32 v[70:71], v[14:15], v[30:31]
	v_pk_add_f32 v[72:73], v[14:15], v[30:31] neg_lo:[0,1] neg_hi:[0,1]
	v_pk_add_f32 v[74:75], v[28:29], v[68:69]
	v_pk_add_f32 v[80:81], v[28:29], v[68:69] neg_lo:[0,1] neg_hi:[0,1]
	v_pk_add_f32 v[82:83], v[70:71], v[74:75]
	v_pk_add_f32 v[84:85], v[72:73], v[80:81] op_sel:[0,1] op_sel_hi:[1,0] neg_lo:[0,1]
	s_waitcnt vmcnt(14)
; __device__ __forceinline__ float bf2f(u16 h){ return __uint_as_float(((unsigned)h)<<16); }
; HD float2 cmul(float2 a, float2 b){ return make_float2(a.x*b.x - a.y*b.y, a.x*b.y + a.y*b.x); }
; HD float2 cmulc(float2 a, float2 b){ return make_float2(a.x*b.x + a.y*b.y, a.y*b.x - a.x*b.y); }
; HD void inv12_half(const float2* Z, const float2* twA, const float2* twB, int t, float2& x0, float2& x1){
;   float2 w1=cmul(twA[t>>6],twB[t&63]), w2=cmul(w1,w1), w3=cmul(w2,w1);
;   float2 b0=Z[t], b1=cmulc(Z[t+4096],w1), b2=cmulc(Z[t+8192],w2), b3=cmulc(Z[t+12288],w3);
;   float2 s02=make_float2(b0.x+b2.x,b0.y+b2.y), d02=make_float2(b0.x-b2.x,b0.y-b2.y);
;   float2 s13=make_float2(b1.x+b3.x,b1.y+b3.y), d13=make_float2(b1.x-b3.x,b1.y-b3.y);
;   x0=make_float2(s02.x+s13.x,s02.y+s13.y);
;   x1=make_float2(d02.x-d13.y,d02.y+d13.x);
; }
; __device__ __forceinline__ void phase_hyena(KP kp_, int hf){ asm volatile("" : "+s"(kp_)); const Params p=load_params(kp_);
;     ...
;         } else { int tq=tid; asm volatile("" : "+v"(tq));
;           _Pragma("unroll 4") for (int i=0;i<8;++i){ int tb=tq+512*i; float2 xr[2]; inv12_half(Z,twA,twB,tb,xr[0],xr[1]);
;             _Pragma("unroll") for (int hh=0;hh<2;++hh){ int t=tb+hh*4096;
;               float x0=hconv3(r2,t,wb0,wb1,wb2,bb_), x1=hconv3(r2+8192,t,wb0,wb1,wb2,bb_);
;               float2 y=xr[hh]; y.x*=(1.f/16384.f); y.y*=(1.f/16384.f); float2 z1=Zs[t];
;               float o0=x0*(y.x+z1.x*bias1)*bf2f(rz[t]); float o1=x1*(y.y+z1.y*bias1)*bf2f(rz[8192+t]);
;               ybT[(size_t)c*16384+t]=f2bf(o0); ybT[(size_t)c*16384+8192+t]=f2bf(o1); } }
	v_lshlrev_b32_e32 v224, 16, v228
	v_mov_b32_e32 v225, 0
	v_mov_b32_e32 v226, 0
	v_mov_b32_dpp v225, v224 wave_shr:1 row_mask:0xf bank_mask:0xf
	v_mov_b32_dpp v226, v224 wave_shl:1 row_mask:0xf bank_mask:0xf
	v_mul_f32_e32 v227, v88, v224
	v_fmac_f32_e32 v227, v87, v225
	v_fmac_f32_e32 v227, v89, v226
	v_add_f32_e32 v94, v90, v227
	v_lshlrev_b32_e32 v224, 16, v230
	v_mov_b32_e32 v225, 0
	v_mov_b32_e32 v226, 0
	v_mov_b32_dpp v225, v224 wave_shr:1 row_mask:0xf bank_mask:0xf
	v_mov_b32_dpp v226, v224 wave_shl:1 row_mask:0xf bank_mask:0xf
	v_mul_f32_e32 v227, v88, v224
	v_fmac_f32_e32 v227, v87, v225
	v_fmac_f32_e32 v227, v89, v226
	v_add_f32_e32 v97, v90, v227
	v_lshlrev_b32_e32 v224, 16, v229
	v_mov_b32_e32 v225, 0
	v_mov_b32_e32 v226, 0
	v_mov_b32_dpp v225, v224 wave_shr:1 row_mask:0xf bank_mask:0xf
	v_mov_b32_dpp v226, v224 wave_shl:1 row_mask:0xf bank_mask:0xf
	v_mul_f32_e32 v227, v88, v224
	v_fmac_f32_e32 v227, v87, v225
	v_fmac_f32_e32 v227, v89, v226
	v_add_f32_e32 v98, v90, v227
	v_lshlrev_b32_e32 v224, 16, v231
	v_mov_b32_e32 v225, 0
	v_mov_b32_e32 v226, 0
	v_mov_b32_dpp v225, v224 wave_shr:1 row_mask:0xf bank_mask:0xf
	v_mov_b32_dpp v226, v224 wave_shl:1 row_mask:0xf bank_mask:0xf
	v_mul_f32_e32 v227, v88, v224
	v_fmac_f32_e32 v227, v87, v225
	v_fmac_f32_e32 v227, v89, v226
	v_add_f32_e32 v100, v90, v227
	v_mul_f32_e32 v108, v91, v236
	v_fmac_f32_e32 v108, 0x38800000, v82
	v_mul_f32_e32 v108, v94, v108
	v_lshlrev_b32_e32 v109, 16, v232
	v_mul_f32_e32 v108, v108, v109
	v_cvt_pk_bf16_f32 v224, v108, v108
	v_mul_f32_e32 v108, v91, v237
	v_fmac_f32_e32 v108, 0x38800000, v83
	v_mul_f32_e32 v108, v108, v97
	v_lshlrev_b32_e32 v109, 16, v234
	v_mul_f32_e32 v108, v108, v109
	v_cvt_pk_bf16_f32 v225, v108, v108
	v_add_u32_e32 v106, 0x800, v0
	v_lshl_add_u64 v[104:105], v[54:55], 0, v[106:107]
	global_store_short v[104:105], v224, off
	v_lshl_add_u64 v[104:105], v[56:57], 0, v[106:107]
	global_store_short v[104:105], v225, off
	v_mul_f32_e32 v108, v91, v238
	v_fmac_f32_e32 v108, 0x38800000, v84
	v_mul_f32_e32 v108, v98, v108
	v_lshlrev_b32_e32 v109, 16, v233
	v_mul_f32_e32 v108, v108, v109
	v_cvt_pk_bf16_f32 v224, v108, v108
	v_mul_f32_e32 v108, v91, v239
	v_fmac_f32_e32 v108, 0x38800000, v85
	v_mul_f32_e32 v108, v108, v100
	v_lshlrev_b32_e32 v109, 16, v235
	v_mul_f32_e32 v108, v108, v109
	v_cvt_pk_bf16_f32 v225, v108, v108
	v_add_u32_e32 v106, 0x800, v2
	v_lshl_add_u64 v[104:105], v[54:55], 0, v[106:107]
	global_store_short v[104:105], v224, off
	v_lshl_add_u64 v[104:105], v[56:57], 0, v[106:107]
	global_store_short v[104:105], v225, off
	global_load_ushort v228, v1, s[96:97] offset:0
	global_load_ushort v230, v1, s[74:75] offset:0
	global_load_ushort v232, v1, s[72:73] offset:0
	global_load_ushort v234, v1, s[12:13] offset:0
	global_load_ushort v229, v4, s[96:97] offset:0
	global_load_ushort v231, v4, s[74:75] offset:0
	global_load_ushort v233, v4, s[72:73] offset:0
	global_load_ushort v235, v4, s[12:13] offset:0
	v_add_u32_e32 v6, 0x4000, v5
	global_load_dwordx2 v[236:237], v6, s[80:81]
	global_load_dwordx2 v[238:239], v6, s[50:51]
	ds_read_b64 v[12:13], v7 offset:256
	ds_read_b64 v[14:15], v8 offset:16384
	ds_read_b64 v[16:17], v8 offset:49152
	ds_read_b64 v[18:19], v9 offset:16384
	ds_read_b64 v[20:21], v9 offset:49152
	s_waitcnt lgkmcnt(5)
	v_pk_mul_f32 v[222:223], v[58:59], v[10:11] op_sel:[1,1] op_sel_hi:[1,0]
	v_pk_fma_f32 v[22:23], v[58:59], v[10:11], v[222:223] op_sel:[0,0,0] op_sel_hi:[0,1,1] neg_lo:[0,0,1]
	v_pk_mul_f32 v[222:223], v[22:23], v[22:23] op_sel:[1,1] op_sel_hi:[1,0]
	v_pk_fma_f32 v[24:25], v[22:23], v[22:23], v[222:223] op_sel:[0,0,0] op_sel_hi:[0,1,1] neg_lo:[0,0,1]
	v_pk_mul_f32 v[222:223], v[24:25], v[22:23] op_sel:[1,1] op_sel_hi:[1,0]
	v_pk_fma_f32 v[26:27], v[24:25], v[22:23], v[222:223] op_sel:[0,0,0] op_sel_hi:[0,1,1] neg_lo:[0,0,1]
	v_pk_mul_f32 v[222:223], v[62:63], v[22:23] op_sel:[1,1] op_sel_hi:[0,1]
	v_pk_fma_f32 v[28:29], v[62:63], v[22:23], v[222:223] op_sel:[0,0,0] op_sel_hi:[1,0,1] neg_hi:[0,0,1]
	v_pk_mul_f32 v[222:223], v[64:65], v[24:25] op_sel:[1,1] op_sel_hi:[0,1]
	v_pk_fma_f32 v[30:31], v[64:65], v[24:25], v[222:223] op_sel:[0,0,0] op_sel_hi:[1,0,1] neg_hi:[0,0,1]
	v_pk_mul_f32 v[222:223], v[66:67], v[26:27] op_sel:[1,1] op_sel_hi:[0,1]
	v_pk_fma_f32 v[68:69], v[66:67], v[26:27], v[222:223] op_sel:[0,0,0] op_sel_hi:[1,0,1] neg_hi:[0,0,1]
	v_pk_add_f32 v[70:71], v[60:61], v[30:31]
	v_pk_add_f32 v[72:73], v[60:61], v[30:31] neg_lo:[0,1] neg_hi:[0,1]
	v_pk_add_f32 v[74:75], v[28:29], v[68:69]
	v_pk_add_f32 v[80:81], v[28:29], v[68:69] neg_lo:[0,1] neg_hi:[0,1]
	v_pk_add_f32 v[82:83], v[70:71], v[74:75]
	v_pk_add_f32 v[84:85], v[72:73], v[80:81] op_sel:[0,1] op_sel_hi:[1,0] neg_lo:[0,1]
	s_waitcnt vmcnt(14)
; __device__ __forceinline__ float bf2f(u16 h){ return __uint_as_float(((unsigned)h)<<16); }
; HD float2 cmul(float2 a, float2 b){ return make_float2(a.x*b.x - a.y*b.y, a.x*b.y + a.y*b.x); }
; HD float2 cmulc(float2 a, float2 b){ return make_float2(a.x*b.x + a.y*b.y, a.y*b.x - a.x*b.y); }
; HD void inv12_half(const float2* Z, const float2* twA, const float2* twB, int t, float2& x0, float2& x1){
;   float2 w1=cmul(twA[t>>6],twB[t&63]), w2=cmul(w1,w1), w3=cmul(w2,w1);
;   float2 b0=Z[t], b1=cmulc(Z[t+4096],w1), b2=cmulc(Z[t+8192],w2), b3=cmulc(Z[t+12288],w3);
;   float2 s02=make_float2(b0.x+b2.x,b0.y+b2.y), d02=make_float2(b0.x-b2.x,b0.y-b2.y);
;   float2 s13=make_float2(b1.x+b3.x,b1.y+b3.y), d13=make_float2(b1.x-b3.x,b1.y-b3.y);
;   x0=make_float2(s02.x+s13.x,s02.y+s13.y);
;   x1=make_float2(d02.x-d13.y,d02.y+d13.x);
; }
; __device__ __forceinline__ void phase_hyena(KP kp_, int hf){ asm volatile("" : "+s"(kp_)); const Params p=load_params(kp_);
;     ...
;         } else { int tq=tid; asm volatile("" : "+v"(tq));
;           _Pragma("unroll 4") for (int i=0;i<8;++i){ int tb=tq+512*i; float2 xr[2]; inv12_half(Z,twA,twB,tb,xr[0],xr[1]);
;             _Pragma("unroll") for (int hh=0;hh<2;++hh){ int t=tb+hh*4096;
;               float x0=hconv3(r2,t,wb0,wb1,wb2,bb_), x1=hconv3(r2+8192,t,wb0,wb1,wb2,bb_);
;               float2 y=xr[hh]; y.x*=(1.f/16384.f); y.y*=(1.f/16384.f); float2 z1=Zs[t];
;               float o0=x0*(y.x+z1.x*bias1)*bf2f(rz[t]); float o1=x1*(y.y+z1.y*bias1)*bf2f(rz[8192+t]);
;               ybT[(size_t)c*16384+t]=f2bf(o0); ybT[(size_t)c*16384+8192+t]=f2bf(o1); } }
	v_lshlrev_b32_e32 v224, 16, v240
	v_mov_b32_e32 v225, 0
	v_mov_b32_e32 v226, 0
	v_mov_b32_dpp v225, v224 wave_shr:1 row_mask:0xf bank_mask:0xf
	v_mov_b32_dpp v226, v224 wave_shl:1 row_mask:0xf bank_mask:0xf
	v_mul_f32_e32 v227, v88, v224
	v_fmac_f32_e32 v227, v87, v225
	v_fmac_f32_e32 v227, v89, v226
	v_add_f32_e32 v94, v90, v227
	v_lshlrev_b32_e32 v224, 16, v242
	v_mov_b32_e32 v225, 0
	v_mov_b32_e32 v226, 0
	v_mov_b32_dpp v225, v224 wave_shr:1 row_mask:0xf bank_mask:0xf
	v_mov_b32_dpp v226, v224 wave_shl:1 row_mask:0xf bank_mask:0xf
	v_mul_f32_e32 v227, v88, v224
	v_fmac_f32_e32 v227, v87, v225
	v_fmac_f32_e32 v227, v89, v226
	v_add_f32_e32 v97, v90, v227
	v_lshlrev_b32_e32 v224, 16, v241
	v_mov_b32_e32 v225, 0
	v_mov_b32_e32 v226, 0
	v_mov_b32_dpp v225, v224 wave_shr:1 row_mask:0xf bank_mask:0xf
	v_mov_b32_dpp v226, v224 wave_shl:1 row_mask:0xf bank_mask:0xf
	v_mul_f32_e32 v227, v88, v224
	v_fmac_f32_e32 v227, v87, v225
	v_fmac_f32_e32 v227, v89, v226
	v_add_f32_e32 v98, v90, v227
	v_lshlrev_b32_e32 v224, 16, v243
	v_mov_b32_e32 v225, 0
	v_mov_b32_e32 v226, 0
	v_mov_b32_dpp v225, v224 wave_shr:1 row_mask:0xf bank_mask:0xf
	v_mov_b32_dpp v226, v224 wave_shl:1 row_mask:0xf bank_mask:0xf
	v_mul_f32_e32 v227, v88, v224
	v_fmac_f32_e32 v227, v87, v225
	v_fmac_f32_e32 v227, v89, v226
	v_add_f32_e32 v100, v90, v227
	v_mul_f32_e32 v108, v91, v248
	v_fmac_f32_e32 v108, 0x38800000, v82
	v_mul_f32_e32 v108, v94, v108
	v_lshlrev_b32_e32 v109, 16, v244
	v_mul_f32_e32 v108, v108, v109
	v_cvt_pk_bf16_f32 v224, v108, v108
	v_mul_f32_e32 v108, v91, v249
	v_fmac_f32_e32 v108, 0x38800000, v83
	v_mul_f32_e32 v108, v108, v97
	v_lshlrev_b32_e32 v109, 16, v246
	v_mul_f32_e32 v108, v108, v109
	v_cvt_pk_bf16_f32 v225, v108, v108
	v_add_u32_e32 v106, 0xc00, v0
	v_lshl_add_u64 v[104:105], v[54:55], 0, v[106:107]
	global_store_short v[104:105], v224, off
	v_lshl_add_u64 v[104:105], v[56:57], 0, v[106:107]
	global_store_short v[104:105], v225, off
	v_mul_f32_e32 v108, v91, v250
	v_fmac_f32_e32 v108, 0x38800000, v84
	v_mul_f32_e32 v108, v98, v108
	v_lshlrev_b32_e32 v109, 16, v245
	v_mul_f32_e32 v108, v108, v109
	v_cvt_pk_bf16_f32 v224, v108, v108
	v_mul_f32_e32 v108, v91, v251
	v_fmac_f32_e32 v108, 0x38800000, v85
	v_mul_f32_e32 v108, v108, v100
	v_lshlrev_b32_e32 v109, 16, v247
	v_mul_f32_e32 v108, v108, v109
	v_cvt_pk_bf16_f32 v225, v108, v108
	v_add_u32_e32 v106, 0xc00, v2
	v_lshl_add_u64 v[104:105], v[54:55], 0, v[106:107]
	global_store_short v[104:105], v224, off
	v_lshl_add_u64 v[104:105], v[56:57], 0, v[106:107]
	global_store_short v[104:105], v225, off
	global_load_ushort v240, v1, s[96:97] offset:1024
	global_load_ushort v242, v1, s[74:75] offset:1024
	global_load_ushort v244, v1, s[72:73] offset:1024
	global_load_ushort v246, v1, s[12:13] offset:1024
	global_load_ushort v241, v4, s[96:97] offset:1024
	global_load_ushort v243, v4, s[74:75] offset:1024
	global_load_ushort v245, v4, s[72:73] offset:1024
	global_load_ushort v247, v4, s[12:13] offset:1024
	v_add_u32_e32 v6, 0x5000, v5
	global_load_dwordx2 v[248:249], v6, s[80:81]
	global_load_dwordx2 v[250:251], v6, s[50:51]
	ds_read_b64 v[58:59], v7 offset:320
	ds_read_b64 v[60:61], v8 offset:20480
	ds_read_b64 v[62:63], v8 offset:53248
	ds_read_b64 v[64:65], v9 offset:20480
	ds_read_b64 v[66:67], v9 offset:53248
	s_waitcnt lgkmcnt(5)
	v_pk_mul_f32 v[222:223], v[12:13], v[10:11] op_sel:[1,1] op_sel_hi:[1,0]
	v_pk_fma_f32 v[22:23], v[12:13], v[10:11], v[222:223] op_sel:[0,0,0] op_sel_hi:[0,1,1] neg_lo:[0,0,1]
	v_pk_mul_f32 v[222:223], v[22:23], v[22:23] op_sel:[1,1] op_sel_hi:[1,0]
	v_pk_fma_f32 v[24:25], v[22:23], v[22:23], v[222:223] op_sel:[0,0,0] op_sel_hi:[0,1,1] neg_lo:[0,0,1]
	v_pk_mul_f32 v[222:223], v[24:25], v[22:23] op_sel:[1,1] op_sel_hi:[1,0]
	v_pk_fma_f32 v[26:27], v[24:25], v[22:23], v[222:223] op_sel:[0,0,0] op_sel_hi:[0,1,1] neg_lo:[0,0,1]
	v_pk_mul_f32 v[222:223], v[16:17], v[22:23] op_sel:[1,1] op_sel_hi:[0,1]
	v_pk_fma_f32 v[28:29], v[16:17], v[22:23], v[222:223] op_sel:[0,0,0] op_sel_hi:[1,0,1] neg_hi:[0,0,1]
	v_pk_mul_f32 v[222:223], v[18:19], v[24:25] op_sel:[1,1] op_sel_hi:[0,1]
	v_pk_fma_f32 v[30:31], v[18:19], v[24:25], v[222:223] op_sel:[0,0,0] op_sel_hi:[1,0,1] neg_hi:[0,0,1]
	v_pk_mul_f32 v[222:223], v[20:21], v[26:27] op_sel:[1,1] op_sel_hi:[0,1]
	v_pk_fma_f32 v[68:69], v[20:21], v[26:27], v[222:223] op_sel:[0,0,0] op_sel_hi:[1,0,1] neg_hi:[0,0,1]
	v_pk_add_f32 v[70:71], v[14:15], v[30:31]
	v_pk_add_f32 v[72:73], v[14:15], v[30:31] neg_lo:[0,1] neg_hi:[0,1]
	v_pk_add_f32 v[74:75], v[28:29], v[68:69]
	v_pk_add_f32 v[80:81], v[28:29], v[68:69] neg_lo:[0,1] neg_hi:[0,1]
	v_pk_add_f32 v[82:83], v[70:71], v[74:75]
	v_pk_add_f32 v[84:85], v[72:73], v[80:81] op_sel:[0,1] op_sel_hi:[1,0] neg_lo:[0,1]
	s_waitcnt vmcnt(14)
; __device__ __forceinline__ float bf2f(u16 h){ return __uint_as_float(((unsigned)h)<<16); }
; HD float2 cmul(float2 a, float2 b){ return make_float2(a.x*b.x - a.y*b.y, a.x*b.y + a.y*b.x); }
; HD float2 cmulc(float2 a, float2 b){ return make_float2(a.x*b.x + a.y*b.y, a.y*b.x - a.x*b.y); }
; HD void inv12_half(const float2* Z, const float2* twA, const float2* twB, int t, float2& x0, float2& x1){
;   float2 w1=cmul(twA[t>>6],twB[t&63]), w2=cmul(w1,w1), w3=cmul(w2,w1);
;   float2 b0=Z[t], b1=cmulc(Z[t+4096],w1), b2=cmulc(Z[t+8192],w2), b3=cmulc(Z[t+12288],w3);
;   float2 s02=make_float2(b0.x+b2.x,b0.y+b2.y), d02=make_float2(b0.x-b2.x,b0.y-b2.y);
;   float2 s13=make_float2(b1.x+b3.x,b1.y+b3.y), d13=make_float2(b1.x-b3.x,b1.y-b3.y);
;   x0=make_float2(s02.x+s13.x,s02.y+s13.y);
;   x1=make_float2(d02.x-d13.y,d02.y+d13.x);
; }
; __device__ __forceinline__ void phase_hyena(KP kp_, int hf){ asm volatile("" : "+s"(kp_)); const Params p=load_params(kp_);
;     ...
;         } else { int tq=tid; asm volatile("" : "+v"(tq));
;           _Pragma("unroll 4") for (int i=0;i<8;++i){ int tb=tq+512*i; float2 xr[2]; inv12_half(Z,twA,twB,tb,xr[0],xr[1]);
;             _Pragma("unroll") for (int hh=0;hh<2;++hh){ int t=tb+hh*4096;
;               float x0=hconv3(r2,t,wb0,wb1,wb2,bb_), x1=hconv3(r2+8192,t,wb0,wb1,wb2,bb_);
;               float2 y=xr[hh]; y.x*=(1.f/16384.f); y.y*=(1.f/16384.f); float2 z1=Zs[t];
;               float o0=x0*(y.x+z1.x*bias1)*bf2f(rz[t]); float o1=x1*(y.y+z1.y*bias1)*bf2f(rz[8192+t]);
;               ybT[(size_t)c*16384+t]=f2bf(o0); ybT[(size_t)c*16384+8192+t]=f2bf(o1); } }
	v_lshlrev_b32_e32 v224, 16, v228
	v_mov_b32_e32 v225, 0
	v_mov_b32_e32 v226, 0
	v_mov_b32_dpp v225, v224 wave_shr:1 row_mask:0xf bank_mask:0xf
	v_mov_b32_dpp v226, v224 wave_shl:1 row_mask:0xf bank_mask:0xf
	v_mul_f32_e32 v227, v88, v224
	v_fmac_f32_e32 v227, v87, v225
	v_fmac_f32_e32 v227, v89, v226
	v_add_f32_e32 v94, v90, v227
	v_lshlrev_b32_e32 v224, 16, v230
	v_mov_b32_e32 v225, 0
	v_mov_b32_e32 v226, 0
	v_mov_b32_dpp v225, v224 wave_shr:1 row_mask:0xf bank_mask:0xf
	v_mov_b32_dpp v226, v224 wave_shl:1 row_mask:0xf bank_mask:0xf
	v_mul_f32_e32 v227, v88, v224
	v_fmac_f32_e32 v227, v87, v225
	v_fmac_f32_e32 v227, v89, v226
	v_add_f32_e32 v97, v90, v227
	v_lshlrev_b32_e32 v224, 16, v229
	v_mov_b32_e32 v225, 0
	v_mov_b32_e32 v226, 0
	v_mov_b32_dpp v225, v224 wave_shr:1 row_mask:0xf bank_mask:0xf
	v_mov_b32_dpp v226, v224 wave_shl:1 row_mask:0xf bank_mask:0xf
	v_mul_f32_e32 v227, v88, v224
	v_fmac_f32_e32 v227, v87, v225
	v_fmac_f32_e32 v227, v89, v226
	v_add_f32_e32 v98, v90, v227
	v_lshlrev_b32_e32 v224, 16, v231
	v_mov_b32_e32 v225, 0
	v_mov_b32_e32 v226, 0
	v_mov_b32_dpp v225, v224 wave_shr:1 row_mask:0xf bank_mask:0xf
	v_mov_b32_dpp v226, v224 wave_shl:1 row_mask:0xf bank_mask:0xf
	v_mul_f32_e32 v227, v88, v224
	v_fmac_f32_e32 v227, v87, v225
	v_fmac_f32_e32 v227, v89, v226
	v_add_f32_e32 v100, v90, v227
	v_mul_f32_e32 v108, v91, v236
	v_fmac_f32_e32 v108, 0x38800000, v82
	v_mul_f32_e32 v108, v94, v108
	v_lshlrev_b32_e32 v109, 16, v232
	v_mul_f32_e32 v108, v108, v109
	v_cvt_pk_bf16_f32 v224, v108, v108
	v_mul_f32_e32 v108, v91, v237
	v_fmac_f32_e32 v108, 0x38800000, v83
	v_mul_f32_e32 v108, v108, v97
	v_lshlrev_b32_e32 v109, 16, v234
	v_mul_f32_e32 v108, v108, v109
	v_cvt_pk_bf16_f32 v225, v108, v108
	v_add_u32_e32 v106, 0x0, v1
	v_lshl_add_u64 v[104:105], v[54:55], 0, v[106:107]
	global_store_short v[104:105], v224, off
	v_lshl_add_u64 v[104:105], v[56:57], 0, v[106:107]
	global_store_short v[104:105], v225, off
	v_mul_f32_e32 v108, v91, v238
	v_fmac_f32_e32 v108, 0x38800000, v84
	v_mul_f32_e32 v108, v98, v108
	v_lshlrev_b32_e32 v109, 16, v233
	v_mul_f32_e32 v108, v108, v109
	v_cvt_pk_bf16_f32 v224, v108, v108
	v_mul_f32_e32 v108, v91, v239
	v_fmac_f32_e32 v108, 0x38800000, v85
	v_mul_f32_e32 v108, v108, v100
	v_lshlrev_b32_e32 v109, 16, v235
	v_mul_f32_e32 v108, v108, v109
	v_cvt_pk_bf16_f32 v225, v108, v108
	v_add_u32_e32 v106, 0x0, v4
	v_lshl_add_u64 v[104:105], v[54:55], 0, v[106:107]
	global_store_short v[104:105], v224, off
	v_lshl_add_u64 v[104:105], v[56:57], 0, v[106:107]
	global_store_short v[104:105], v225, off
	global_load_ushort v228, v1, s[96:97] offset:2048
	global_load_ushort v230, v1, s[74:75] offset:2048
	global_load_ushort v232, v1, s[72:73] offset:2048
	global_load_ushort v234, v1, s[12:13] offset:2048
	global_load_ushort v229, v4, s[96:97] offset:2048
	global_load_ushort v231, v4, s[74:75] offset:2048
	global_load_ushort v233, v4, s[72:73] offset:2048
	global_load_ushort v235, v4, s[12:13] offset:2048
	v_add_u32_e32 v6, 0x6000, v5
	global_load_dwordx2 v[236:237], v6, s[80:81]
	global_load_dwordx2 v[238:239], v6, s[50:51]
	ds_read_b64 v[12:13], v7 offset:384
	ds_read_b64 v[14:15], v8 offset:24576
	ds_read_b64 v[16:17], v8 offset:57344
	ds_read_b64 v[18:19], v9 offset:24576
	ds_read_b64 v[20:21], v9 offset:57344
	s_waitcnt lgkmcnt(5)
	v_pk_mul_f32 v[222:223], v[58:59], v[10:11] op_sel:[1,1] op_sel_hi:[1,0]
	v_pk_fma_f32 v[22:23], v[58:59], v[10:11], v[222:223] op_sel:[0,0,0] op_sel_hi:[0,1,1] neg_lo:[0,0,1]
	v_pk_mul_f32 v[222:223], v[22:23], v[22:23] op_sel:[1,1] op_sel_hi:[1,0]
	v_pk_fma_f32 v[24:25], v[22:23], v[22:23], v[222:223] op_sel:[0,0,0] op_sel_hi:[0,1,1] neg_lo:[0,0,1]
	v_pk_mul_f32 v[222:223], v[24:25], v[22:23] op_sel:[1,1] op_sel_hi:[1,0]
	v_pk_fma_f32 v[26:27], v[24:25], v[22:23], v[222:223] op_sel:[0,0,0] op_sel_hi:[0,1,1] neg_lo:[0,0,1]
	v_pk_mul_f32 v[222:223], v[62:63], v[22:23] op_sel:[1,1] op_sel_hi:[0,1]
	v_pk_fma_f32 v[28:29], v[62:63], v[22:23], v[222:223] op_sel:[0,0,0] op_sel_hi:[1,0,1] neg_hi:[0,0,1]
	v_pk_mul_f32 v[222:223], v[64:65], v[24:25] op_sel:[1,1] op_sel_hi:[0,1]
	v_pk_fma_f32 v[30:31], v[64:65], v[24:25], v[222:223] op_sel:[0,0,0] op_sel_hi:[1,0,1] neg_hi:[0,0,1]
	v_pk_mul_f32 v[222:223], v[66:67], v[26:27] op_sel:[1,1] op_sel_hi:[0,1]
	v_pk_fma_f32 v[68:69], v[66:67], v[26:27], v[222:223] op_sel:[0,0,0] op_sel_hi:[1,0,1] neg_hi:[0,0,1]
	v_pk_add_f32 v[70:71], v[60:61], v[30:31]
	v_pk_add_f32 v[72:73], v[60:61], v[30:31] neg_lo:[0,1] neg_hi:[0,1]
	v_pk_add_f32 v[74:75], v[28:29], v[68:69]
	v_pk_add_f32 v[80:81], v[28:29], v[68:69] neg_lo:[0,1] neg_hi:[0,1]
	v_pk_add_f32 v[82:83], v[70:71], v[74:75]
	v_pk_add_f32 v[84:85], v[72:73], v[80:81] op_sel:[0,1] op_sel_hi:[1,0] neg_lo:[0,1]
	s_waitcnt vmcnt(14)
; __device__ __forceinline__ float bf2f(u16 h){ return __uint_as_float(((unsigned)h)<<16); }
; HD float2 cmul(float2 a, float2 b){ return make_float2(a.x*b.x - a.y*b.y, a.x*b.y + a.y*b.x); }
; HD float2 cmulc(float2 a, float2 b){ return make_float2(a.x*b.x + a.y*b.y, a.y*b.x - a.x*b.y); }
; HD void inv12_half(const float2* Z, const float2* twA, const float2* twB, int t, float2& x0, float2& x1){
;   float2 w1=cmul(twA[t>>6],twB[t&63]), w2=cmul(w1,w1), w3=cmul(w2,w1);
;   float2 b0=Z[t], b1=cmulc(Z[t+4096],w1), b2=cmulc(Z[t+8192],w2), b3=cmulc(Z[t+12288],w3);
;   float2 s02=make_float2(b0.x+b2.x,b0.y+b2.y), d02=make_float2(b0.x-b2.x,b0.y-b2.y);
;   float2 s13=make_float2(b1.x+b3.x,b1.y+b3.y), d13=make_float2(b1.x-b3.x,b1.y-b3.y);
;   x0=make_float2(s02.x+s13.x,s02.y+s13.y);
;   x1=make_float2(d02.x-d13.y,d02.y+d13.x);
; }
; __device__ __forceinline__ void phase_hyena(KP kp_, int hf){ asm volatile("" : "+s"(kp_)); const Params p=load_params(kp_);
;     ...
;         } else { int tq=tid; asm volatile("" : "+v"(tq));
;           _Pragma("unroll 4") for (int i=0;i<8;++i){ int tb=tq+512*i; float2 xr[2]; inv12_half(Z,twA,twB,tb,xr[0],xr[1]);
;             _Pragma("unroll") for (int hh=0;hh<2;++hh){ int t=tb+hh*4096;
;               float x0=hconv3(r2,t,wb0,wb1,wb2,bb_), x1=hconv3(r2+8192,t,wb0,wb1,wb2,bb_);
;               float2 y=xr[hh]; y.x*=(1.f/16384.f); y.y*=(1.f/16384.f); float2 z1=Zs[t];
;               float o0=x0*(y.x+z1.x*bias1)*bf2f(rz[t]); float o1=x1*(y.y+z1.y*bias1)*bf2f(rz[8192+t]);
;               ybT[(size_t)c*16384+t]=f2bf(o0); ybT[(size_t)c*16384+8192+t]=f2bf(o1); } }
	v_lshlrev_b32_e32 v224, 16, v240
	v_mov_b32_e32 v225, 0
	v_mov_b32_e32 v226, 0
	v_mov_b32_dpp v225, v224 wave_shr:1 row_mask:0xf bank_mask:0xf
	v_mov_b32_dpp v226, v224 wave_shl:1 row_mask:0xf bank_mask:0xf
	v_mul_f32_e32 v227, v88, v224
	v_fmac_f32_e32 v227, v87, v225
	v_fmac_f32_e32 v227, v89, v226
	v_add_f32_e32 v94, v90, v227
	v_lshlrev_b32_e32 v224, 16, v242
	v_mov_b32_e32 v225, 0
	v_mov_b32_e32 v226, 0
	v_mov_b32_dpp v225, v224 wave_shr:1 row_mask:0xf bank_mask:0xf
	v_mov_b32_dpp v226, v224 wave_shl:1 row_mask:0xf bank_mask:0xf
	v_mul_f32_e32 v227, v88, v224
	v_fmac_f32_e32 v227, v87, v225
	v_fmac_f32_e32 v227, v89, v226
	v_add_f32_e32 v97, v90, v227
	v_lshlrev_b32_e32 v224, 16, v241
	v_mov_b32_e32 v225, 0
	v_mov_b32_e32 v226, 0
	v_mov_b32_dpp v225, v224 wave_shr:1 row_mask:0xf bank_mask:0xf
	v_mov_b32_dpp v226, v224 wave_shl:1 row_mask:0xf bank_mask:0xf
	v_mul_f32_e32 v227, v88, v224
	v_fmac_f32_e32 v227, v87, v225
	v_fmac_f32_e32 v227, v89, v226
	v_add_f32_e32 v98, v90, v227
	v_lshlrev_b32_e32 v224, 16, v243
	v_mov_b32_e32 v225, 0
	v_mov_b32_e32 v226, 0
	v_mov_b32_dpp v225, v224 wave_shr:1 row_mask:0xf bank_mask:0xf
	v_mov_b32_dpp v226, v224 wave_shl:1 row_mask:0xf bank_mask:0xf
	v_mul_f32_e32 v227, v88, v224
	v_fmac_f32_e32 v227, v87, v225
	v_fmac_f32_e32 v227, v89, v226
	v_add_f32_e32 v100, v90, v227
	v_mul_f32_e32 v108, v91, v248
	v_fmac_f32_e32 v108, 0x38800000, v82
	v_mul_f32_e32 v108, v94, v108
	v_lshlrev_b32_e32 v109, 16, v244
	v_mul_f32_e32 v108, v108, v109
	v_cvt_pk_bf16_f32 v224, v108, v108
	v_mul_f32_e32 v108, v91, v249
	v_fmac_f32_e32 v108, 0x38800000, v83
	v_mul_f32_e32 v108, v108, v97
	v_lshlrev_b32_e32 v109, 16, v246
	v_mul_f32_e32 v108, v108, v109
	v_cvt_pk_bf16_f32 v225, v108, v108
	v_add_u32_e32 v106, 0x400, v1
	v_lshl_add_u64 v[104:105], v[54:55], 0, v[106:107]
	global_store_short v[104:105], v224, off
	v_lshl_add_u64 v[104:105], v[56:57], 0, v[106:107]
	global_store_short v[104:105], v225, off
	v_mul_f32_e32 v108, v91, v250
	v_fmac_f32_e32 v108, 0x38800000, v84
	v_mul_f32_e32 v108, v98, v108
	v_lshlrev_b32_e32 v109, 16, v245
	v_mul_f32_e32 v108, v108, v109
	v_cvt_pk_bf16_f32 v224, v108, v108
	v_mul_f32_e32 v108, v91, v251
	v_fmac_f32_e32 v108, 0x38800000, v85
	v_mul_f32_e32 v108, v108, v100
	v_lshlrev_b32_e32 v109, 16, v247
	v_mul_f32_e32 v108, v108, v109
	v_cvt_pk_bf16_f32 v225, v108, v108
	v_add_u32_e32 v106, 0x400, v4
	v_lshl_add_u64 v[104:105], v[54:55], 0, v[106:107]
	global_store_short v[104:105], v224, off
	v_lshl_add_u64 v[104:105], v[56:57], 0, v[106:107]
	global_store_short v[104:105], v225, off
	global_load_ushort v240, v1, s[96:97] offset:3072
	global_load_ushort v242, v1, s[74:75] offset:3072
	global_load_ushort v244, v1, s[72:73] offset:3072
	global_load_ushort v246, v1, s[12:13] offset:3072
	global_load_ushort v241, v4, s[96:97] offset:3072
	global_load_ushort v243, v4, s[74:75] offset:3072
	global_load_ushort v245, v4, s[72:73] offset:3072
	global_load_ushort v247, v4, s[12:13] offset:3072
	v_add_u32_e32 v6, 0x7000, v5
	global_load_dwordx2 v[248:249], v6, s[80:81]
	global_load_dwordx2 v[250:251], v6, s[50:51]
	ds_read_b64 v[58:59], v7 offset:448
	ds_read_b64 v[60:61], v8 offset:28672
	ds_read_b64 v[62:63], v8 offset:61440
	ds_read_b64 v[64:65], v9 offset:28672
	ds_read_b64 v[66:67], v9 offset:61440
	s_waitcnt lgkmcnt(5)
	v_pk_mul_f32 v[222:223], v[12:13], v[10:11] op_sel:[1,1] op_sel_hi:[1,0]
	v_pk_fma_f32 v[22:23], v[12:13], v[10:11], v[222:223] op_sel:[0,0,0] op_sel_hi:[0,1,1] neg_lo:[0,0,1]
	v_pk_mul_f32 v[222:223], v[22:23], v[22:23] op_sel:[1,1] op_sel_hi:[1,0]
	v_pk_fma_f32 v[24:25], v[22:23], v[22:23], v[222:223] op_sel:[0,0,0] op_sel_hi:[0,1,1] neg_lo:[0,0,1]
	v_pk_mul_f32 v[222:223], v[24:25], v[22:23] op_sel:[1,1] op_sel_hi:[1,0]
	v_pk_fma_f32 v[26:27], v[24:25], v[22:23], v[222:223] op_sel:[0,0,0] op_sel_hi:[0,1,1] neg_lo:[0,0,1]
	v_pk_mul_f32 v[222:223], v[16:17], v[22:23] op_sel:[1,1] op_sel_hi:[0,1]
	v_pk_fma_f32 v[28:29], v[16:17], v[22:23], v[222:223] op_sel:[0,0,0] op_sel_hi:[1,0,1] neg_hi:[0,0,1]
	v_pk_mul_f32 v[222:223], v[18:19], v[24:25] op_sel:[1,1] op_sel_hi:[0,1]
	v_pk_fma_f32 v[30:31], v[18:19], v[24:25], v[222:223] op_sel:[0,0,0] op_sel_hi:[1,0,1] neg_hi:[0,0,1]
	v_pk_mul_f32 v[222:223], v[20:21], v[26:27] op_sel:[1,1] op_sel_hi:[0,1]
	v_pk_fma_f32 v[68:69], v[20:21], v[26:27], v[222:223] op_sel:[0,0,0] op_sel_hi:[1,0,1] neg_hi:[0,0,1]
	v_pk_add_f32 v[70:71], v[14:15], v[30:31]
	v_pk_add_f32 v[72:73], v[14:15], v[30:31] neg_lo:[0,1] neg_hi:[0,1]
	v_pk_add_f32 v[74:75], v[28:29], v[68:69]
	v_pk_add_f32 v[80:81], v[28:29], v[68:69] neg_lo:[0,1] neg_hi:[0,1]
	v_pk_add_f32 v[82:83], v[70:71], v[74:75]
	v_pk_add_f32 v[84:85], v[72:73], v[80:81] op_sel:[0,1] op_sel_hi:[1,0] neg_lo:[0,1]
	s_waitcnt vmcnt(14)
; __device__ __forceinline__ float bf2f(u16 h){ return __uint_as_float(((unsigned)h)<<16); }
; HD float2 cmul(float2 a, float2 b){ return make_float2(a.x*b.x - a.y*b.y, a.x*b.y + a.y*b.x); }
; HD float2 cmulc(float2 a, float2 b){ return make_float2(a.x*b.x + a.y*b.y, a.y*b.x - a.x*b.y); }
; HD void inv12_half(const float2* Z, const float2* twA, const float2* twB, int t, float2& x0, float2& x1){
;   float2 w1=cmul(twA[t>>6],twB[t&63]), w2=cmul(w1,w1), w3=cmul(w2,w1);
;   float2 b0=Z[t], b1=cmulc(Z[t+4096],w1), b2=cmulc(Z[t+8192],w2), b3=cmulc(Z[t+12288],w3);
;   float2 s02=make_float2(b0.x+b2.x,b0.y+b2.y), d02=make_float2(b0.x-b2.x,b0.y-b2.y);
;   float2 s13=make_float2(b1.x+b3.x,b1.y+b3.y), d13=make_float2(b1.x-b3.x,b1.y-b3.y);
;   x0=make_float2(s02.x+s13.x,s02.y+s13.y);
;   x1=make_float2(d02.x-d13.y,d02.y+d13.x);
; }
; __device__ __forceinline__ void phase_hyena(KP kp_, int hf){ asm volatile("" : "+s"(kp_)); const Params p=load_params(kp_);
;     ...
;         } else { int tq=tid; asm volatile("" : "+v"(tq));
;           _Pragma("unroll 4") for (int i=0;i<8;++i){ int tb=tq+512*i; float2 xr[2]; inv12_half(Z,twA,twB,tb,xr[0],xr[1]);
;             _Pragma("unroll") for (int hh=0;hh<2;++hh){ int t=tb+hh*4096;
;               float x0=hconv3(r2,t,wb0,wb1,wb2,bb_), x1=hconv3(r2+8192,t,wb0,wb1,wb2,bb_);
;               float2 y=xr[hh]; y.x*=(1.f/16384.f); y.y*=(1.f/16384.f); float2 z1=Zs[t];
;               float o0=x0*(y.x+z1.x*bias1)*bf2f(rz[t]); float o1=x1*(y.y+z1.y*bias1)*bf2f(rz[8192+t]);
;               ybT[(size_t)c*16384+t]=f2bf(o0); ybT[(size_t)c*16384+8192+t]=f2bf(o1); } }
	v_lshlrev_b32_e32 v224, 16, v228
	v_mov_b32_e32 v225, 0
	v_mov_b32_e32 v226, 0
	v_mov_b32_dpp v225, v224 wave_shr:1 row_mask:0xf bank_mask:0xf
	v_mov_b32_dpp v226, v224 wave_shl:1 row_mask:0xf bank_mask:0xf
	v_mul_f32_e32 v227, v88, v224
	v_fmac_f32_e32 v227, v87, v225
	v_fmac_f32_e32 v227, v89, v226
	v_add_f32_e32 v94, v90, v227
	v_lshlrev_b32_e32 v224, 16, v230
	v_mov_b32_e32 v225, 0
	v_mov_b32_e32 v226, 0
	v_mov_b32_dpp v225, v224 wave_shr:1 row_mask:0xf bank_mask:0xf
	v_mov_b32_dpp v226, v224 wave_shl:1 row_mask:0xf bank_mask:0xf
	v_mul_f32_e32 v227, v88, v224
	v_fmac_f32_e32 v227, v87, v225
	v_fmac_f32_e32 v227, v89, v226
	v_add_f32_e32 v97, v90, v227
	v_lshlrev_b32_e32 v224, 16, v229
	v_mov_b32_e32 v225, 0
	v_mov_b32_e32 v226, 0
	v_mov_b32_dpp v225, v224 wave_shr:1 row_mask:0xf bank_mask:0xf
	v_mov_b32_dpp v226, v224 wave_shl:1 row_mask:0xf bank_mask:0xf
	v_mul_f32_e32 v227, v88, v224
	v_fmac_f32_e32 v227, v87, v225
	v_fmac_f32_e32 v227, v89, v226
	v_add_f32_e32 v98, v90, v227
	v_lshlrev_b32_e32 v224, 16, v231
	v_mov_b32_e32 v225, 0
	v_mov_b32_e32 v226, 0
	v_mov_b32_dpp v225, v224 wave_shr:1 row_mask:0xf bank_mask:0xf
	v_mov_b32_dpp v226, v224 wave_shl:1 row_mask:0xf bank_mask:0xf
	v_mul_f32_e32 v227, v88, v224
	v_fmac_f32_e32 v227, v87, v225
	v_fmac_f32_e32 v227, v89, v226
	v_add_f32_e32 v100, v90, v227
	v_mul_f32_e32 v108, v91, v236
	v_fmac_f32_e32 v108, 0x38800000, v82
	v_mul_f32_e32 v108, v94, v108
	v_lshlrev_b32_e32 v109, 16, v232
	v_mul_f32_e32 v108, v108, v109
	v_cvt_pk_bf16_f32 v224, v108, v108
	v_mul_f32_e32 v108, v91, v237
	v_fmac_f32_e32 v108, 0x38800000, v83
	v_mul_f32_e32 v108, v108, v97
	v_lshlrev_b32_e32 v109, 16, v234
	v_mul_f32_e32 v108, v108, v109
	v_cvt_pk_bf16_f32 v225, v108, v108
	v_add_u32_e32 v106, 0x800, v1
	v_lshl_add_u64 v[104:105], v[54:55], 0, v[106:107]
	global_store_short v[104:105], v224, off
	v_lshl_add_u64 v[104:105], v[56:57], 0, v[106:107]
	global_store_short v[104:105], v225, off
	v_mul_f32_e32 v108, v91, v238
	v_fmac_f32_e32 v108, 0x38800000, v84
	v_mul_f32_e32 v108, v98, v108
	v_lshlrev_b32_e32 v109, 16, v233
	v_mul_f32_e32 v108, v108, v109
	v_cvt_pk_bf16_f32 v224, v108, v108
	v_mul_f32_e32 v108, v91, v239
	v_fmac_f32_e32 v108, 0x38800000, v85
	v_mul_f32_e32 v108, v108, v100
	v_lshlrev_b32_e32 v109, 16, v235
	v_mul_f32_e32 v108, v108, v109
	v_cvt_pk_bf16_f32 v225, v108, v108
	v_add_u32_e32 v106, 0x800, v4
	v_lshl_add_u64 v[104:105], v[54:55], 0, v[106:107]
	global_store_short v[104:105], v224, off
	v_lshl_add_u64 v[104:105], v[56:57], 0, v[106:107]
	global_store_short v[104:105], v225, off
	s_waitcnt lgkmcnt(0)
	v_pk_mul_f32 v[222:223], v[58:59], v[10:11] op_sel:[1,1] op_sel_hi:[1,0]
	v_pk_fma_f32 v[22:23], v[58:59], v[10:11], v[222:223] op_sel:[0,0,0] op_sel_hi:[0,1,1] neg_lo:[0,0,1]
	v_pk_mul_f32 v[222:223], v[22:23], v[22:23] op_sel:[1,1] op_sel_hi:[1,0]
	v_pk_fma_f32 v[24:25], v[22:23], v[22:23], v[222:223] op_sel:[0,0,0] op_sel_hi:[0,1,1] neg_lo:[0,0,1]
	v_pk_mul_f32 v[222:223], v[24:25], v[22:23] op_sel:[1,1] op_sel_hi:[1,0]
	v_pk_fma_f32 v[26:27], v[24:25], v[22:23], v[222:223] op_sel:[0,0,0] op_sel_hi:[0,1,1] neg_lo:[0,0,1]
	v_pk_mul_f32 v[222:223], v[62:63], v[22:23] op_sel:[1,1] op_sel_hi:[0,1]
	v_pk_fma_f32 v[28:29], v[62:63], v[22:23], v[222:223] op_sel:[0,0,0] op_sel_hi:[1,0,1] neg_hi:[0,0,1]
	v_pk_mul_f32 v[222:223], v[64:65], v[24:25] op_sel:[1,1] op_sel_hi:[0,1]
	v_pk_fma_f32 v[30:31], v[64:65], v[24:25], v[222:223] op_sel:[0,0,0] op_sel_hi:[1,0,1] neg_hi:[0,0,1]
	v_pk_mul_f32 v[222:223], v[66:67], v[26:27] op_sel:[1,1] op_sel_hi:[0,1]
	v_pk_fma_f32 v[68:69], v[66:67], v[26:27], v[222:223] op_sel:[0,0,0] op_sel_hi:[1,0,1] neg_hi:[0,0,1]
	v_pk_add_f32 v[70:71], v[60:61], v[30:31]
	v_pk_add_f32 v[72:73], v[60:61], v[30:31] neg_lo:[0,1] neg_hi:[0,1]
	v_pk_add_f32 v[74:75], v[28:29], v[68:69]
	v_pk_add_f32 v[80:81], v[28:29], v[68:69] neg_lo:[0,1] neg_hi:[0,1]
	v_pk_add_f32 v[82:83], v[70:71], v[74:75]
	v_pk_add_f32 v[84:85], v[72:73], v[80:81] op_sel:[0,1] op_sel_hi:[1,0] neg_lo:[0,1]
	s_waitcnt vmcnt(4)
	v_lshlrev_b32_e32 v224, 16, v240
	v_mov_b32_e32 v225, 0
	v_mov_b32_e32 v226, 0
	v_mov_b32_dpp v225, v224 wave_shr:1 row_mask:0xf bank_mask:0xf
	v_mov_b32_dpp v226, v224 wave_shl:1 row_mask:0xf bank_mask:0xf
	v_mul_f32_e32 v227, v88, v224
	v_fmac_f32_e32 v227, v87, v225
	v_fmac_f32_e32 v227, v89, v226
	v_add_f32_e32 v94, v90, v227
	v_lshlrev_b32_e32 v224, 16, v242
	v_mov_b32_e32 v225, 0
	v_mov_b32_e32 v226, 0
	v_mov_b32_dpp v225, v224 wave_shr:1 row_mask:0xf bank_mask:0xf
	v_mov_b32_dpp v226, v224 wave_shl:1 row_mask:0xf bank_mask:0xf
	v_mul_f32_e32 v227, v88, v224
	v_fmac_f32_e32 v227, v87, v225
	v_fmac_f32_e32 v227, v89, v226
	v_add_f32_e32 v97, v90, v227
	v_lshlrev_b32_e32 v224, 16, v241
	v_mov_b32_e32 v225, 0
	v_mov_b32_e32 v226, 0
	v_mov_b32_dpp v225, v224 wave_shr:1 row_mask:0xf bank_mask:0xf
	v_mov_b32_dpp v226, v224 wave_shl:1 row_mask:0xf bank_mask:0xf
	v_mul_f32_e32 v227, v88, v224
	v_fmac_f32_e32 v227, v87, v225
	v_fmac_f32_e32 v227, v89, v226
	v_add_f32_e32 v98, v90, v227
	v_lshlrev_b32_e32 v224, 16, v243
	v_mov_b32_e32 v225, 0
	v_mov_b32_e32 v226, 0
	v_mov_b32_dpp v225, v224 wave_shr:1 row_mask:0xf bank_mask:0xf
	v_mov_b32_dpp v226, v224 wave_shl:1 row_mask:0xf bank_mask:0xf
	v_mul_f32_e32 v227, v88, v224
	v_fmac_f32_e32 v227, v87, v225
	v_fmac_f32_e32 v227, v89, v226
	v_add_f32_e32 v100, v90, v227
	v_mul_f32_e32 v108, v91, v248
	v_fmac_f32_e32 v108, 0x38800000, v82
	v_mul_f32_e32 v108, v94, v108
	v_lshlrev_b32_e32 v109, 16, v244
	v_mul_f32_e32 v108, v108, v109
	v_cvt_pk_bf16_f32 v224, v108, v108
	v_mul_f32_e32 v108, v91, v249
	v_fmac_f32_e32 v108, 0x38800000, v83
	v_mul_f32_e32 v108, v108, v97
	v_lshlrev_b32_e32 v109, 16, v246
	v_mul_f32_e32 v108, v108, v109
	v_cvt_pk_bf16_f32 v225, v108, v108
	v_add_u32_e32 v106, 0xc00, v1
	v_lshl_add_u64 v[104:105], v[54:55], 0, v[106:107]
	global_store_short v[104:105], v224, off
	v_lshl_add_u64 v[104:105], v[56:57], 0, v[106:107]
	global_store_short v[104:105], v225, off
	v_mul_f32_e32 v108, v91, v250
	v_fmac_f32_e32 v108, 0x38800000, v84
	v_mul_f32_e32 v108, v98, v108
	v_lshlrev_b32_e32 v109, 16, v245
	v_mul_f32_e32 v108, v108, v109
	v_cvt_pk_bf16_f32 v224, v108, v108
	v_mul_f32_e32 v108, v91, v251
	v_fmac_f32_e32 v108, 0x38800000, v85
	v_mul_f32_e32 v108, v108, v100
	v_lshlrev_b32_e32 v109, 16, v247
	v_mul_f32_e32 v108, v108, v109
	v_cvt_pk_bf16_f32 v225, v108, v108
	v_add_u32_e32 v106, 0xc00, v4
	v_lshl_add_u64 v[104:105], v[54:55], 0, v[106:107]
	global_store_short v[104:105], v224, off
	v_lshl_add_u64 v[104:105], v[56:57], 0, v[106:107]
	global_store_short v[104:105], v225, off
	s_mov_b32 s50, 0x2000
	s_mov_b32 s51, 0
	s_mov_b64 s[12:13], 0
